# write-through (sc1) stores in rowwise/convA/SSD phases so the grid barrier's L2 write-back has little to flush
# baseline (speedup 1.0000x reference)
; __device__ __forceinline__ float bflo(unsigned u) { return __uint_as_float(u << 16); }
; __device__ __forceinline__ float bfhi(unsigned u) { return __uint_as_float(u & 0xffff0000u); }
; __device__ __forceinline__ void phase_rowwise(const Params& p, const float* xs32, const bf16_t* xs16, float* xd32, bf16_t* xd16, const bf16_t* y, const float* gpost, int modres,
;                                               bf16_t* hout, const float* gpre, int modh) {
;     ...
;         } else {
; #pragma unroll
;             for (int r = 0; r < RB; ++r)
; #pragma unroll
;                 for (int j = 0; j < 4; ++j) { const u32x2 t = *(const u32x2*)(xs16 + (row0 + r) * D + lane * 4 + 256 * j);
;                     xv[r][j][0] = bflo(t.x); xv[r][j][1] = bfhi(t.x); xv[r][j][2] = bflo(t.y); xv[r][j][3] = bfhi(t.y); }
;         }
;         if (y) {
;             u32x2 yp[RB][4];
; #pragma unroll
;             for (int r = 0; r < RB; ++r)
; #pragma unroll
;                 for (int j = 0; j < 4; ++j) yp[r][j] = *(const u32x2*)(y + (row0 + r) * LDH + lane * 4 + 256 * j);
;             float ss[RB];
; #pragma unroll
;             for (int r = 0; r < RB; ++r) { ss[r] = 0.f;
; #pragma unroll
;                 for (int j = 0; j < 4; ++j) { const float a = bflo(yp[r][j].x), b = bfhi(yp[r][j].x), c = bflo(yp[r][j].y), d = bfhi(yp[r][j].y); ss[r] += (a * a + b * b) + (c * c + d * d); } }
.LBB0_149:
	v_readlane_b32 s8, v254, 56
	v_readlane_b32 s9, v254, 57
	s_andn2_b64 vcc, exec, s[8:9]
	s_cbranch_vccnz .LBB0_148
	v_lshl_add_u64 v[26:27], v[20:21], 0, v[18:19]
	v_lshl_add_u64 v[2:3], v[22:23], 0, v[18:19]
	s_mov_b32 s8, 0x241c000
	global_load_dwordx2 v[34:35], v[26:27], off
	global_load_dwordx2 v[36:37], v[26:27], off offset:512
	global_load_dwordx2 v[38:39], v[26:27], off offset:1024
	global_load_dwordx2 v[42:43], v[26:27], off offset:1536
	v_add_co_u32_e32 v32, vcc, s8, v2
	s_movk_i32 s10, 0x1000
	s_nop 0
	v_addc_co_u32_e32 v33, vcc, 0, v3, vcc
	global_load_dwordx2 v[44:45], v[32:33], off offset:2048
	global_load_dwordx2 v[50:51], v[32:33], off
	v_add_co_u32_e32 v12, vcc, 0x241d000, v2
	v_ashrrev_i32_e32 v2, 9, v1
	s_nop 0
	v_addc_co_u32_e32 v13, vcc, 0, v3, vcc
	global_load_dwordx2 v[52:53], v[12:13], off offset:2048
	global_load_dwordx2 v[62:63], v[12:13], off
	global_load_dwordx2 v[48:49], v[32:33], off offset:2560
	global_load_dwordx2 v[46:47], v[32:33], off offset:512
	global_load_dwordx2 v[64:65], v[26:27], off offset:2176
	global_load_dwordx2 v[60:61], v[12:13], off offset:2560
	global_load_dwordx2 v[58:59], v[12:13], off offset:512
	global_load_dwordx2 v[66:67], v[26:27], off offset:2688
	global_load_dwordx2 v[68:69], v[26:27], off offset:3200
	global_load_dwordx2 v[74:75], v[26:27], off offset:3712
	v_add_co_u32_e32 v28, vcc, s10, v26
	v_readlane_b32 s8, v254, 54
	v_mul_hi_i32_i24_e32 v3, 0x18000, v2
	v_mul_i32_i24_e32 v2, 0x18000, v2
	v_addc_co_u32_e32 v29, vcc, 0, v27, vcc
	v_readlane_b32 s9, v254, 55
	s_mov_b32 s12, 0x3a800000
	s_waitcnt vmcnt(15)
	v_and_b32_e32 v85, 0xffff0000, v34
	v_lshl_add_u64 v[10:11], s[8:9], 0, v[2:3]
	global_load_dwordx2 v[76:77], v[28:29], off offset:256
	global_load_dwordx2 v[78:79], v[28:29], off offset:768
	global_load_dwordx2 v[80:81], v[28:29], off offset:1280
	global_load_dwordx2 v[8:9], v[28:29], off offset:1792
	global_load_dwordx2 v[6:7], v[28:29], off offset:2432
	global_load_dwordx2 v[4:5], v[28:29], off offset:2944
	global_load_dwordx2 v[2:3], v[28:29], off offset:3456
	global_load_dwordx2 v[30:31], v[28:29], off offset:3968
	v_and_b32_e32 v83, 0xffff0000, v35
	v_lshlrev_b32_e32 v84, 16, v34
	v_lshlrev_b32_e32 v82, 16, v35
	s_waitcnt vmcnt(22)
	v_and_b32_e32 v57, 0xffff0000, v37
	v_and_b32_e32 v56, 0xffff0000, v36
	s_waitcnt vmcnt(20)
	v_lshlrev_b32_e32 v35, 16, v42
	v_and_b32_e32 v114, 0xffff0000, v42
	v_mul_f32_e32 v34, v83, v83
	v_mul_f32_e32 v42, v85, v85
	v_lshlrev_b32_e32 v55, 16, v37
	v_lshlrev_b32_e32 v54, 16, v36
	v_lshlrev_b32_e32 v113, 16, v43
	v_and_b32_e32 v112, 0xffff0000, v43
	s_waitcnt vmcnt(19)
	v_lshlrev_b32_e32 v129, 16, v44
	v_and_b32_e32 v130, 0xffff0000, v44
	v_lshlrev_b32_e32 v131, 16, v45
	v_and_b32_e32 v132, 0xffff0000, v45
	v_pk_mul_f32 v[36:37], v[56:57], v[56:57]
	v_pk_fma_f32 v[44:45], v[82:83], v[82:83], v[34:35] op_sel_hi:[1,1,0]
	v_pk_fma_f32 v[42:43], v[84:85], v[84:85], v[42:43] op_sel_hi:[1,1,0]
	s_waitcnt vmcnt(18)
	v_lshlrev_b32_e32 v135, 16, v50
	v_and_b32_e32 v139, 0xffff0000, v50
	v_lshlrev_b32_e32 v133, 16, v51
	v_and_b32_e32 v134, 0xffff0000, v51
	v_pk_fma_f32 v[36:37], v[54:55], v[54:55], v[36:37]
	v_mov_b32_e32 v34, v42
	v_mov_b32_e32 v50, v44
	v_mov_b32_e32 v51, v35
	v_and_b32_e32 v41, 0xffff0000, v38
	v_mul_f32_e32 v25, v114, v114
	v_pk_add_f32 v[42:43], v[42:43], v[44:45]
	v_pk_mul_f32 v[44:45], v[34:35], v[50:51]
	v_pk_add_f32 v[36:37], v[36:37], v[36:37] op_sel:[0,1] op_sel_hi:[1,0]
	v_lshlrev_b32_e32 v40, 16, v38
	v_lshlrev_b32_e32 v38, 16, v39
	v_and_b32_e32 v39, 0xffff0000, v39
	v_mov_b32_e32 v43, v45
	v_mov_b32_e32 v37, v25
	v_mul_f32_e32 v34, v41, v41
	v_pk_add_f32 v[36:37], v[42:43], v[36:37]
	v_pk_fma_f32 v[42:43], v[40:41], v[40:41], v[34:35] op_sel_hi:[1,1,0]
	v_mul_f32_e32 v34, v39, v39
	v_mul_f32_e32 v70, v113, v113
	v_mul_f32_e32 v71, v112, v112
	v_pk_fma_f32 v[44:45], v[38:39], v[38:39], v[34:35] op_sel_hi:[1,1,0]
	v_mov_b32_e32 v43, v70
	v_mov_b32_e32 v45, v71
	v_pk_add_f32 v[42:43], v[42:43], v[44:45]
	s_waitcnt vmcnt(10)
	v_and_b32_e32 v73, 0xffff0000, v67
	v_and_b32_e32 v72, 0xffff0000, v66
	v_pk_add_f32 v[98:99], v[36:37], v[42:43]
	v_and_b32_e32 v93, 0xffff0000, v64
	v_and_b32_e32 v87, 0xffff0000, v65
	v_lshlrev_b32_e32 v71, 16, v67
	v_lshlrev_b32_e32 v70, 16, v66
	v_pk_mul_f32 v[36:37], v[72:73], v[72:73]
	v_lshlrev_b32_e32 v92, 16, v64
	v_lshlrev_b32_e32 v86, 16, v65
	v_mul_f32_e32 v34, v87, v87
	v_pk_fma_f32 v[44:45], v[70:71], v[70:71], v[36:37]
	s_waitcnt vmcnt(8)
	v_lshlrev_b32_e32 v37, 16, v74
	v_mul_f32_e32 v36, v93, v93
	v_lshlrev_b32_e32 v125, 16, v62
	v_and_b32_e32 v126, 0xffff0000, v62
	v_lshlrev_b32_e32 v127, 16, v63
	v_and_b32_e32 v128, 0xffff0000, v63
	v_pk_fma_f32 v[42:43], v[86:87], v[86:87], v[34:35] op_sel_hi:[1,1,0]
	v_pk_fma_f32 v[62:63], v[92:93], v[92:93], v[36:37] op_sel_hi:[1,1,0]
	v_and_b32_e32 v116, 0xffff0000, v74
	v_mov_b32_e32 v36, v62
	v_mov_b32_e32 v64, v42
	v_mov_b32_e32 v65, v37
	v_lshlrev_b32_e32 v123, 16, v53
	v_and_b32_e32 v124, 0xffff0000, v53
	v_and_b32_e32 v53, 0xffff0000, v68
	v_mul_f32_e32 v25, v116, v116
	v_pk_add_f32 v[42:43], v[62:63], v[42:43]
	v_pk_mul_f32 v[62:63], v[36:37], v[64:65]
	v_pk_add_f32 v[44:45], v[44:45], v[44:45] op_sel:[0,1] op_sel_hi:[1,0]
	v_lshlrev_b32_e32 v121, 16, v52
	v_and_b32_e32 v122, 0xffff0000, v52
	v_lshlrev_b32_e32 v52, 16, v68
	v_and_b32_e32 v51, 0xffff0000, v69
	v_mov_b32_e32 v43, v63
	v_mov_b32_e32 v45, v25
	v_mul_f32_e32 v36, v53, v53
	v_lshlrev_b32_e32 v50, 16, v69
	v_lshlrev_b32_e32 v115, 16, v75
	v_and_b32_e32 v34, 0xffff0000, v75
	v_pk_add_f32 v[42:43], v[42:43], v[44:45]
	v_pk_fma_f32 v[44:45], v[52:53], v[52:53], v[36:37] op_sel_hi:[1,1,0]
	v_mul_f32_e32 v36, v51, v51
	v_mul_f32_e32 v66, v115, v115
	v_mul_f32_e32 v67, v34, v34
	v_pk_fma_f32 v[62:63], v[50:51], v[50:51], v[36:37] op_sel_hi:[1,1,0]
	v_mov_b32_e32 v45, v66
	v_mov_b32_e32 v63, v67
	v_pk_add_f32 v[44:45], v[44:45], v[62:63]
	s_waitcnt vmcnt(7)
; __device__ __forceinline__ float bflo(unsigned u) { return __uint_as_float(u << 16); }
; __device__ __forceinline__ float bfhi(unsigned u) { return __uint_as_float(u & 0xffff0000u); }
; __device__ __forceinline__ void phase_rowwise(const Params& p, const float* xs32, const bf16_t* xs16, float* xd32, bf16_t* xd16, const bf16_t* y, const float* gpost, int modres,
;                                               bf16_t* hout, const float* gpre, int modh) {
;     ...
;                 for (int j = 0; j < 4; ++j) { const float a = bflo(yp[r][j].x), b = bfhi(yp[r][j].x), c = bflo(yp[r][j].y), d = bfhi(yp[r][j].y); ss[r] += (a * a + b * b) + (c * c + d * d); } }
; #pragma unroll
;             for (int o = 1; o < 64; o <<= 1)
; #pragma unroll
;                 for (int r = 0; r < RB; ++r) ss[r] += __shfl_xor(ss[r], o);
; #pragma unroll
;             for (int j = 0; j < 4; ++j) { const f32x4 gt = *(const f32x4*)(modb + modres + lane * 4 + 256 * j), gp = *(const f32x4*)(gpost + lane * 4 + 256 * j);
;                 const f32x4 gg = gt * gp;
; #pragma unroll
;                 for (int r = 0; r < RB; ++r) { const float rstd = rsqrtf(ss[r] * (1.f / D) + EPS);
	v_lshlrev_b32_e32 v90, 16, v76
	v_and_b32_e32 v91, 0xffff0000, v76
	v_lshlrev_b32_e32 v88, 16, v77
	v_and_b32_e32 v89, 0xffff0000, v77
	s_waitcnt vmcnt(6)
	v_and_b32_e32 v77, 0xffff0000, v79
	v_and_b32_e32 v76, 0xffff0000, v78
	v_pk_add_f32 v[102:103], v[42:43], v[44:45]
	v_lshlrev_b32_e32 v75, 16, v79
	v_lshlrev_b32_e32 v74, 16, v78
	v_pk_mul_f32 v[42:43], v[76:77], v[76:77]
	v_mul_f32_e32 v36, v89, v89
	v_pk_fma_f32 v[66:67], v[74:75], v[74:75], v[42:43]
	s_waitcnt vmcnt(4)
	v_lshlrev_b32_e32 v43, 16, v8
	v_and_b32_e32 v118, 0xffff0000, v8
	v_mul_f32_e32 v8, v91, v91
	v_pk_fma_f32 v[44:45], v[88:89], v[88:89], v[36:37] op_sel_hi:[1,1,0]
	v_lshlrev_b32_e32 v117, 16, v9
	v_and_b32_e32 v36, 0xffff0000, v9
	v_pk_fma_f32 v[8:9], v[90:91], v[90:91], v[8:9] op_sel_hi:[1,1,0]
	v_mov_b32_e32 v68, v44
	v_mov_b32_e32 v42, v8
	v_mov_b32_e32 v69, v43
	v_pk_add_f32 v[8:9], v[8:9], v[44:45]
	v_pk_mul_f32 v[44:45], v[42:43], v[68:69]
	v_and_b32_e32 v65, 0xffff0000, v80
	v_mul_f32_e32 v25, v118, v118
	v_mov_b32_e32 v9, v45
	v_pk_add_f32 v[44:45], v[66:67], v[66:67] op_sel:[0,1] op_sel_hi:[1,0]
	v_lshlrev_b32_e32 v64, 16, v80
	v_and_b32_e32 v63, 0xffff0000, v81
	v_mov_b32_e32 v45, v25
	v_mul_f32_e32 v42, v65, v65
	v_lshlrev_b32_e32 v62, 16, v81
	v_pk_add_f32 v[8:9], v[8:9], v[44:45]
	v_pk_fma_f32 v[44:45], v[64:65], v[64:65], v[42:43] op_sel_hi:[1,1,0]
	v_mul_f32_e32 v42, v63, v63
	v_mul_f32_e32 v78, v117, v117
	v_mul_f32_e32 v79, v36, v36
	v_pk_fma_f32 v[66:67], v[62:63], v[62:63], v[42:43] op_sel_hi:[1,1,0]
	v_mov_b32_e32 v45, v78
	v_mov_b32_e32 v67, v79
	v_pk_add_f32 v[44:45], v[44:45], v[66:67]
	s_waitcnt vmcnt(1)
	v_lshlrev_b32_e32 v68, 16, v2
	v_and_b32_e32 v69, 0xffff0000, v2
	v_lshlrev_b32_e32 v66, 16, v3
	v_and_b32_e32 v67, 0xffff0000, v3
	v_lshl_add_u64 v[2:3], s[70:71], 2, v[10:11]
	v_mov_b32_e32 v25, v0
	v_lshl_add_u64 v[104:105], v[2:3], 0, v[24:25]
	s_movk_i32 s8, 0x5000
	v_and_b32_e32 v95, 0xffff0000, v7
	v_and_b32_e32 v81, 0xffff0000, v5
	v_and_b32_e32 v80, 0xffff0000, v4
	v_add_co_u32_e32 v2, vcc, s8, v104
	v_lshlrev_b32_e32 v96, 16, v6
	v_and_b32_e32 v97, 0xffff0000, v6
	v_lshlrev_b32_e32 v94, 16, v7
	v_mul_f32_e32 v6, v95, v95
	v_lshlrev_b32_e32 v79, 16, v5
	v_lshlrev_b32_e32 v78, 16, v4
	v_pk_mul_f32 v[4:5], v[80:81], v[80:81]
	v_addc_co_u32_e32 v3, vcc, 0, v105, vcc
	v_pk_add_f32 v[100:101], v[8:9], v[44:45]
	v_pk_fma_f32 v[106:107], v[94:95], v[94:95], v[6:7] op_sel_hi:[1,1,0]
	v_pk_fma_f32 v[108:109], v[78:79], v[78:79], v[4:5]
	global_load_dwordx4 v[2:5], v[2:3], off
	s_nop 0
	global_load_dwordx4 v[6:9], v[14:15], off
	s_waitcnt vmcnt(2)
	v_lshlrev_b32_e32 v45, 16, v30
	v_and_b32_e32 v42, 0xffff0000, v30
	v_mul_f32_e32 v30, v97, v97
	v_lshlrev_b32_e32 v120, 16, v31
	v_and_b32_e32 v119, 0xffff0000, v31
	v_pk_fma_f32 v[30:31], v[96:97], v[96:97], v[30:31] op_sel_hi:[1,1,0]
	v_mov_b32_e32 v110, v106
	v_mov_b32_e32 v44, v30
	v_mov_b32_e32 v111, v45
	v_pk_add_f32 v[30:31], v[30:31], v[106:107]
	v_pk_mul_f32 v[106:107], v[44:45], v[110:111]
	v_mul_f32_e32 v156, v42, v42
	v_mov_b32_e32 v31, v107
	v_pk_add_f32 v[106:107], v[108:109], v[108:109] op_sel:[0,1] op_sel_hi:[1,0]
	v_mov_b32_e32 v108, v102
	v_mov_b32_e32 v107, v156
	v_pk_add_f32 v[30:31], v[30:31], v[106:107]
	v_and_b32_e32 v106, 64, v137
	v_add_u32_e32 v111, 64, v106
	v_xor_b32_e32 v106, 1, v137
	v_cmp_lt_i32_e32 vcc, v106, v111
	v_mov_b32_e32 v109, v98
	v_mov_b32_e32 v98, v103
	v_cndmask_b32_e32 v106, v137, v106, vcc
	v_lshlrev_b32_e32 v106, 2, v106
	v_pk_add_f32 v[98:99], v[108:109], v[98:99]
	ds_bpermute_b32 v103, v106, v99
	ds_bpermute_b32 v102, v106, v98
	v_xor_b32_e32 v107, 2, v137
	v_cmp_lt_i32_e32 vcc, v107, v111
	v_xor_b32_e32 v108, 4, v137
	v_xor_b32_e32 v109, 8, v137
	v_cndmask_b32_e32 v107, v137, v107, vcc
	v_lshlrev_b32_e32 v107, 2, v107
	s_waitcnt lgkmcnt(0)
	v_pk_add_f32 v[98:99], v[98:99], v[102:103]
	ds_bpermute_b32 v103, v107, v99
	ds_bpermute_b32 v102, v107, v98
	v_cmp_lt_i32_e32 vcc, v108, v111
	v_xor_b32_e32 v110, 16, v137
	v_mul_f32_e32 v44, v69, v69
	v_cndmask_b32_e32 v108, v137, v108, vcc
	v_lshlrev_b32_e32 v108, 2, v108
	s_waitcnt lgkmcnt(0)
	v_pk_add_f32 v[98:99], v[98:99], v[102:103]
	ds_bpermute_b32 v103, v108, v99
	ds_bpermute_b32 v102, v108, v98
	v_cmp_lt_i32_e32 vcc, v109, v111
	v_mul_f32_e32 v158, v120, v120
	v_pk_fma_f32 v[156:157], v[68:69], v[68:69], v[44:45] op_sel_hi:[1,1,0]
	v_cndmask_b32_e32 v109, v137, v109, vcc
	v_lshlrev_b32_e32 v109, 2, v109
	s_waitcnt lgkmcnt(0)
	v_pk_add_f32 v[98:99], v[98:99], v[102:103]
	ds_bpermute_b32 v103, v109, v99
	ds_bpermute_b32 v102, v109, v98
	v_cmp_lt_i32_e32 vcc, v110, v111
	v_mov_b32_e32 v157, v158
	v_xor_b32_e32 v158, 32, v137
	v_cndmask_b32_e32 v110, v137, v110, vcc
	v_lshlrev_b32_e32 v110, 2, v110
	s_waitcnt lgkmcnt(0)
	v_pk_add_f32 v[98:99], v[98:99], v[102:103]
	ds_bpermute_b32 v103, v110, v99
	ds_bpermute_b32 v102, v110, v98
	v_cmp_lt_i32_e32 vcc, v158, v111
	v_mul_f32_e32 v44, v67, v67
	v_mul_f32_e32 v160, v119, v119
	v_cndmask_b32_e32 v111, v137, v158, vcc
	v_lshlrev_b32_e32 v111, 2, v111
	s_waitcnt lgkmcnt(0)
	v_pk_add_f32 v[98:99], v[98:99], v[102:103]
	ds_bpermute_b32 v103, v111, v99
	ds_bpermute_b32 v102, v111, v98
	v_pk_fma_f32 v[158:159], v[66:67], v[66:67], v[44:45] op_sel_hi:[1,1,0]
	s_mov_b32 s8, 0x358637bd
	v_mov_b32_e32 v159, v160
	v_pk_add_f32 v[156:157], v[156:157], v[158:159]
	s_waitcnt lgkmcnt(0)
	v_pk_add_f32 v[98:99], v[98:99], v[102:103]
	v_pk_add_f32 v[156:157], v[30:31], v[156:157]
	v_mov_b64_e32 v[30:31], s[8:9]
	v_pk_fma_f32 v[158:159], v[98:99], s[12:13], v[30:31] op_sel_hi:[1,0,0]
	s_mov_b64 s[8:9], 0x5000
	v_mul_f32_e32 v44, 0x4b800000, v159
	v_cmp_gt_f32_e32 vcc, s76, v159
	s_waitcnt vmcnt(0)
; __device__ __forceinline__ unsigned pk2(float lo, float hi) { unsigned r; asm("v_cvt_pk_bf16_f32 %0, %1, %2" : "=v"(r) : "v"(lo), "v"(hi)); return r; }
; __device__ __forceinline__ float bflo(unsigned u) { return __uint_as_float(u << 16); }
; __device__ __forceinline__ float bfhi(unsigned u) { return __uint_as_float(u & 0xffff0000u); }
; __device__ __forceinline__ void phase_rowwise(const Params& p, const float* xs32, const bf16_t* xs16, float* xd32, bf16_t* xd16, const bf16_t* y, const float* gpost, int modres,
;                                               bf16_t* hout, const float* gpre, int modh) {
;     ...
;             for (int j = 0; j < 4; ++j) { const f32x4 gt = *(const f32x4*)(modb + modres + lane * 4 + 256 * j), gp = *(const f32x4*)(gpost + lane * 4 + 256 * j);
;                 const f32x4 gg = gt * gp;
; #pragma unroll
;                 for (int r = 0; r < RB; ++r) { const float rstd = rsqrtf(ss[r] * (1.f / D) + EPS);
;                     xv[r][j][0] += gg[0] * (bflo(yp[r][j].x) * rstd); xv[r][j][1] += gg[1] * (bfhi(yp[r][j].x) * rstd);
;                     xv[r][j][2] += gg[2] * (bflo(yp[r][j].y) * rstd); xv[r][j][3] += gg[3] * (bfhi(yp[r][j].y) * rstd);
;                     if (xd32) *(f32x4*)(xd32 + (row0 + r) * D + lane * 4 + 256 * j) = xv[r][j];
;                     if (xd16) { u32x2 o; o.x = pk2(xv[r][j][0], xv[r][j][1]); o.y = pk2(xv[r][j][2], xv[r][j][3]);
;                         *(u32x2*)(xd16 + (row0 + r) * D + lane * 4 + 256 * j) = o;
;                         xv[r][j][0] = bflo(o.x); xv[r][j][1] = bfhi(o.x); xv[r][j][2] = bflo(o.y); xv[r][j][3] = bfhi(o.y); } } }
	v_pk_mul_f32 v[102:103], v[2:3], v[6:7]
	v_mov_b32_e32 v3, v100
	v_cndmask_b32_e32 v44, v159, v44, vcc
	v_rsq_f32_e32 v44, v44
	v_mov_b32_e32 v100, v157
	v_pk_mul_f32 v[8:9], v[4:5], v[8:9]
	v_lshl_add_u64 v[98:99], v[104:105], 0, s[8:9]
	v_mul_f32_e32 v2, 0x45800000, v44
	v_cndmask_b32_e32 v44, v44, v2, vcc
	v_mov_b32_e32 v2, v156
	v_pk_add_f32 v[2:3], v[2:3], v[100:101]
	ds_bpermute_b32 v5, v106, v3
	ds_bpermute_b32 v4, v106, v2
	v_mul_f32_e32 v6, v44, v84
	v_fmac_f32_e32 v135, v102, v6
	v_mul_f32_e32 v6, v44, v85
	v_fmac_f32_e32 v139, v103, v6
	s_waitcnt lgkmcnt(0)
	v_pk_add_f32 v[4:5], v[2:3], v[4:5]
	ds_bpermute_b32 v7, v107, v5
	ds_bpermute_b32 v6, v107, v4
	v_mul_f32_e32 v3, 0x4b800000, v158
	v_cmp_gt_f32_e32 vcc, s76, v158
	v_mul_f32_e32 v82, v44, v82
	v_fmac_f32_e32 v133, v8, v82
	s_waitcnt lgkmcnt(0)
	v_pk_add_f32 v[4:5], v[4:5], v[6:7]
	ds_bpermute_b32 v7, v108, v5
	ds_bpermute_b32 v6, v108, v4
	v_cndmask_b32_e32 v3, v158, v3, vcc
	v_rsq_f32_e32 v82, v3
	v_mul_f32_e32 v2, v44, v83
	v_fmac_f32_e32 v134, v9, v2
	s_waitcnt lgkmcnt(0)
	v_pk_add_f32 v[4:5], v[4:5], v[6:7]
	ds_bpermute_b32 v7, v109, v5
	ds_bpermute_b32 v6, v109, v4
	v_mul_f32_e32 v83, 0x45800000, v82
	v_cndmask_b32_e32 v84, v82, v83, vcc
	v_mul_f32_e32 v82, v84, v92
	v_fmac_f32_e32 v129, v102, v82
	s_waitcnt lgkmcnt(0)
	v_pk_add_f32 v[4:5], v[4:5], v[6:7]
	ds_bpermute_b32 v7, v110, v5
	ds_bpermute_b32 v6, v110, v4
	v_mul_f32_e32 v82, v84, v93
	v_fmac_f32_e32 v130, v103, v82
	v_mul_f32_e32 v82, v84, v86
	v_fmac_f32_e32 v131, v8, v82
	s_waitcnt lgkmcnt(0)
	v_pk_add_f32 v[4:5], v[4:5], v[6:7]
	ds_bpermute_b32 v7, v111, v5
	ds_bpermute_b32 v6, v111, v4
	v_mul_f32_e32 v82, v84, v87
	v_fmac_f32_e32 v132, v9, v82
	v_cvt_pk_bf16_f32 v2, v135, v139
	v_cvt_pk_bf16_f32 v3, v133, v134
	s_waitcnt lgkmcnt(0)
	v_pk_add_f32 v[4:5], v[4:5], v[6:7]
	global_store_dwordx2 v[32:33], v[2:3], off sc1
	v_pk_fma_f32 v[4:5], v[4:5], s[12:13], v[30:31] op_sel_hi:[1,0,0]
	v_cvt_pk_bf16_f32 v7, v131, v132
	v_lshlrev_b32_e32 v104, 16, v60
	v_mul_f32_e32 v6, 0x4b800000, v5
	v_cmp_gt_f32_e32 vcc, s76, v5
	v_and_b32_e32 v105, 0xffff0000, v60
	v_mul_f32_e32 v54, v44, v54
	v_cndmask_b32_e32 v5, v5, v6, vcc
	v_rsq_f32_e32 v5, v5
	v_cvt_pk_bf16_f32 v6, v129, v130
	global_store_dwordx2 v[32:33], v[6:7], off offset:2048 sc1
	v_and_b32_e32 v129, 0xffff0000, v49
	v_mul_f32_e32 v82, 0x45800000, v5
	v_cndmask_b32_e32 v85, v5, v82, vcc
	v_mul_f32_e32 v5, v85, v90
	v_fmac_f32_e32 v125, v102, v5
	v_mul_f32_e32 v5, v85, v91
	v_fmac_f32_e32 v126, v103, v5
	v_mul_f32_e32 v5, v85, v88
	v_fmac_f32_e32 v127, v8, v5
	v_mul_f32_e32 v5, v85, v89
	v_fmac_f32_e32 v128, v9, v5
	v_mul_f32_e32 v5, 0x4b800000, v4
	v_cmp_gt_f32_e32 vcc, s76, v4
	v_mul_f32_e32 v38, v44, v38
	v_mul_f32_e32 v40, v44, v40
	v_cndmask_b32_e32 v4, v4, v5, vcc
	v_rsq_f32_e32 v82, v4
	v_cvt_pk_bf16_f32 v4, v125, v126
	v_cvt_pk_bf16_f32 v5, v127, v128
	global_store_dwordx2 v[12:13], v[4:5], off sc1
	v_mul_f32_e32 v83, 0x45800000, v82
	v_cndmask_b32_e32 v125, v82, v83, vcc
	v_mul_f32_e32 v82, v125, v96
	v_fmac_f32_e32 v121, v102, v82
	v_mul_f32_e32 v82, v125, v97
	v_fmac_f32_e32 v122, v103, v82
	v_mul_f32_e32 v82, v125, v94
	v_fmac_f32_e32 v123, v8, v82
	v_mul_f32_e32 v8, v125, v95
	v_fmac_f32_e32 v124, v9, v8
	v_cvt_pk_bf16_f32 v82, v121, v122
	v_cvt_pk_bf16_f32 v83, v123, v124
	global_store_dwordx2 v[12:13], v[82:83], off offset:2048 sc1
	global_load_dwordx4 v[86:89], v[98:99], off offset:1024
	global_load_dwordx4 v[90:93], v[14:15], off offset:1024
	global_load_dwordx2 v[94:95], v[12:13], off offset:3072
	global_load_dwordx2 v[96:97], v[12:13], off offset:1024
	global_load_dwordx2 v[100:101], v[32:33], off offset:3072
	global_load_dwordx2 v[102:103], v[32:33], off offset:1024
	v_lshlrev_b32_e32 v121, 16, v61
	v_and_b32_e32 v122, 0xffff0000, v61
	v_lshlrev_b32_e32 v126, 16, v48
	v_and_b32_e32 v127, 0xffff0000, v48
	v_lshlrev_b32_e32 v48, 16, v46
	v_and_b32_e32 v46, 0xffff0000, v46
	v_lshlrev_b32_e32 v8, 16, v58
	v_and_b32_e32 v9, 0xffff0000, v58
	v_lshlrev_b32_e32 v123, 16, v59
	v_and_b32_e32 v124, 0xffff0000, v59
	v_lshlrev_b32_e32 v128, 16, v49
	v_lshlrev_b32_e32 v49, 16, v47
	v_and_b32_e32 v47, 0xffff0000, v47
	v_mul_f32_e32 v35, v44, v35
	v_mul_f32_e32 v37, v84, v37
	v_mul_f32_e32 v34, v84, v34
	v_readlane_b32 s8, v255, 49
	v_readlane_b32 s9, v255, 50
	s_waitcnt vmcnt(4)
	v_pk_mul_f32 v[60:61], v[86:87], v[90:91]
	s_nop 0
	v_fmac_f32_e32 v48, v54, v60
	v_mul_f32_e32 v54, v44, v56
	v_pk_mul_f32 v[58:59], v[88:89], v[92:93]
	v_fmac_f32_e32 v46, v54, v61
	v_mul_f32_e32 v54, v44, v55
	v_fmac_f32_e32 v49, v54, v58
	v_mul_f32_e32 v54, v44, v57
	v_fmac_f32_e32 v47, v54, v59
	v_mul_f32_e32 v54, v85, v74
	v_fmac_f32_e32 v8, v54, v60
	v_mul_f32_e32 v54, v85, v76
	v_fmac_f32_e32 v9, v54, v61
	v_mul_f32_e32 v54, v85, v75
	v_fmac_f32_e32 v123, v54, v58
	v_mul_f32_e32 v54, v85, v77
	v_cvt_pk_bf16_f32 v48, v48, v46
	v_mul_f32_e32 v46, v84, v70
	v_fmac_f32_e32 v124, v54, v59
	v_mul_f32_e32 v54, v125, v78
	v_fmac_f32_e32 v126, v46, v60
	v_mul_f32_e32 v46, v84, v72
	v_fmac_f32_e32 v104, v54, v60
	v_mul_f32_e32 v54, v125, v80
	v_fmac_f32_e32 v127, v46, v61
	v_mul_f32_e32 v46, v84, v71
	v_fmac_f32_e32 v105, v54, v61
	v_mul_f32_e32 v54, v125, v79
	v_fmac_f32_e32 v128, v46, v58
	v_mul_f32_e32 v46, v84, v73
	v_fmac_f32_e32 v121, v54, v58
	v_mul_f32_e32 v54, v125, v81
	v_cvt_pk_bf16_f32 v49, v49, v47
	global_store_dwordx2 v[32:33], v[48:49], off offset:512 sc1
	v_fmac_f32_e32 v129, v46, v59
	v_cvt_pk_bf16_f32 v46, v126, v127
	v_cvt_pk_bf16_f32 v47, v128, v129
	global_store_dwordx2 v[32:33], v[46:47], off offset:2560 sc1
	v_cvt_pk_bf16_f32 v8, v8, v9
	v_cvt_pk_bf16_f32 v9, v123, v124
	global_store_dwordx2 v[12:13], v[8:9], off offset:512 sc1
	v_fmac_f32_e32 v122, v54, v59
	v_cvt_pk_bf16_f32 v78, v104, v105
	v_cvt_pk_bf16_f32 v79, v121, v122
	global_store_dwordx2 v[12:13], v[78:79], off offset:2560 sc1
	global_load_dwordx4 v[54:57], v[98:99], off offset:2048
	global_load_dwordx4 v[58:61], v[14:15], off offset:2048
	global_load_dwordx2 v[70:71], v[12:13], off offset:3584
	global_load_dwordx2 v[72:73], v[12:13], off offset:1536
	global_load_dwordx2 v[74:75], v[32:33], off offset:3584
	global_load_dwordx2 v[76:77], v[32:33], off offset:1536
	s_waitcnt vmcnt(11)
; __device__ __forceinline__ unsigned pk2(float lo, float hi) { unsigned r; asm("v_cvt_pk_bf16_f32 %0, %1, %2" : "=v"(r) : "v"(lo), "v"(hi)); return r; }
; __device__ __forceinline__ float bflo(unsigned u) { return __uint_as_float(u << 16); }
; __device__ __forceinline__ float bfhi(unsigned u) { return __uint_as_float(u & 0xffff0000u); }
; __device__ __forceinline__ void phase_rowwise(const Params& p, const float* xs32, const bf16_t* xs16, float* xd32, bf16_t* xd16, const bf16_t* y, const float* gpost, int modres,
;                                               bf16_t* hout, const float* gpre, int modh) {
;     ...
;             for (int j = 0; j < 4; ++j) { const f32x4 gt = *(const f32x4*)(modb + modres + lane * 4 + 256 * j), gp = *(const f32x4*)(gpost + lane * 4 + 256 * j);
;                 const f32x4 gg = gt * gp;
; #pragma unroll
;                 for (int r = 0; r < RB; ++r) { const float rstd = rsqrtf(ss[r] * (1.f / D) + EPS);
;                     xv[r][j][0] += gg[0] * (bflo(yp[r][j].x) * rstd); xv[r][j][1] += gg[1] * (bfhi(yp[r][j].x) * rstd);
;                     xv[r][j][2] += gg[2] * (bflo(yp[r][j].y) * rstd); xv[r][j][3] += gg[3] * (bfhi(yp[r][j].y) * rstd);
;                     if (xd32) *(f32x4*)(xd32 + (row0 + r) * D + lane * 4 + 256 * j) = xv[r][j];
;                     if (xd16) { u32x2 o; o.x = pk2(xv[r][j][0], xv[r][j][1]); o.y = pk2(xv[r][j][2], xv[r][j][3]);
;                         *(u32x2*)(xd16 + (row0 + r) * D + lane * 4 + 256 * j) = o;
;                         xv[r][j][0] = bflo(o.x); xv[r][j][1] = bfhi(o.x); xv[r][j][2] = bflo(o.y); xv[r][j][3] = bfhi(o.y); } } }
;         }
;         if (hout) {
;             float ss[RB];
; #pragma unroll
;             for (int r = 0; r < RB; ++r) { ss[r] = 0.f;
; #pragma unroll
;                 for (int j = 0; j < 4; ++j) ss[r] += (xv[r][j][0] * xv[r][j][0] + xv[r][j][1] * xv[r][j][1]) + (xv[r][j][2] * xv[r][j][2] + xv[r][j][3] * xv[r][j][3]); }
	v_lshlrev_b32_e32 v92, 16, v100
	v_and_b32_e32 v93, 0xffff0000, v100
	s_waitcnt vmcnt(10)
	v_lshlrev_b32_e32 v100, 16, v103
	v_lshlrev_b32_e32 v80, 16, v94
	v_and_b32_e32 v81, 0xffff0000, v94
	v_lshlrev_b32_e32 v87, 16, v95
	v_and_b32_e32 v88, 0xffff0000, v95
	v_lshlrev_b32_e32 v94, 16, v101
	v_and_b32_e32 v95, 0xffff0000, v101
	v_and_b32_e32 v101, 0xffff0000, v103
	v_lshlrev_b32_e32 v86, 16, v96
	v_and_b32_e32 v89, 0xffff0000, v96
	v_lshlrev_b32_e32 v90, 16, v97
	v_and_b32_e32 v91, 0xffff0000, v97
	v_lshlrev_b32_e32 v96, 16, v102
	v_and_b32_e32 v97, 0xffff0000, v102
	s_waitcnt vmcnt(4)
	v_pk_mul_f32 v[56:57], v[56:57], v[60:61]
	s_nop 0
	v_fmac_f32_e32 v100, v38, v56
	v_mul_f32_e32 v38, v44, v39
	v_pk_mul_f32 v[58:59], v[54:55], v[58:59]
	v_fmac_f32_e32 v101, v38, v57
	v_mul_f32_e32 v38, v84, v52
	v_fmac_f32_e32 v92, v38, v58
	v_mul_f32_e32 v38, v84, v53
	v_fmac_f32_e32 v93, v38, v59
	v_mul_f32_e32 v38, v84, v50
	v_fmac_f32_e32 v94, v38, v56
	v_mul_f32_e32 v38, v84, v51
	v_fmac_f32_e32 v95, v38, v57
	v_mul_f32_e32 v38, v85, v64
	v_fmac_f32_e32 v86, v38, v58
	v_mul_f32_e32 v38, v85, v65
	v_fmac_f32_e32 v89, v38, v59
	v_mul_f32_e32 v38, v85, v62
	v_fmac_f32_e32 v90, v38, v56
	v_mul_f32_e32 v38, v85, v63
	v_fmac_f32_e32 v91, v38, v57
	v_mul_f32_e32 v38, v125, v68
	v_fmac_f32_e32 v80, v38, v58
	v_mul_f32_e32 v38, v125, v69
	v_fmac_f32_e32 v81, v38, v59
	v_mul_f32_e32 v38, v125, v66
	v_fmac_f32_e32 v96, v40, v58
	v_mul_f32_e32 v40, v44, v41
	v_fmac_f32_e32 v87, v38, v56
	v_mul_f32_e32 v38, v125, v67
	v_fmac_f32_e32 v97, v40, v59
	v_cvt_pk_bf16_f32 v60, v96, v97
	v_cvt_pk_bf16_f32 v61, v100, v101
	global_store_dwordx2 v[32:33], v[60:61], off offset:1024 sc1
	v_cvt_pk_bf16_f32 v54, v92, v93
	v_cvt_pk_bf16_f32 v55, v94, v95
	global_store_dwordx2 v[32:33], v[54:55], off offset:3072 sc1
	v_cvt_pk_bf16_f32 v52, v86, v89
	v_cvt_pk_bf16_f32 v53, v90, v91
	global_store_dwordx2 v[12:13], v[52:53], off offset:1024 sc1
	v_fmac_f32_e32 v88, v38, v57
	v_cvt_pk_bf16_f32 v86, v80, v81
	v_cvt_pk_bf16_f32 v87, v87, v88
	global_store_dwordx2 v[12:13], v[86:87], off offset:3072 sc1
	global_load_dwordx4 v[38:41], v[98:99], off offset:3072
	global_load_dwordx4 v[56:59], v[14:15], off offset:3072
	s_waitcnt vmcnt(6)
	v_lshlrev_b32_e32 v50, 16, v76
	v_and_b32_e32 v51, 0xffff0000, v76
	v_lshlrev_b32_e32 v62, 16, v70
	v_and_b32_e32 v63, 0xffff0000, v70
	v_lshlrev_b32_e32 v64, 16, v71
	v_and_b32_e32 v65, 0xffff0000, v71
	v_lshlrev_b32_e32 v70, 16, v74
	v_and_b32_e32 v71, 0xffff0000, v74
	v_lshlrev_b32_e32 v74, 16, v77
	v_lshlrev_b32_e32 v66, 16, v72
	v_and_b32_e32 v67, 0xffff0000, v72
	v_lshlrev_b32_e32 v68, 16, v73
	v_and_b32_e32 v69, 0xffff0000, v73
	v_lshlrev_b32_e32 v72, 16, v75
	v_and_b32_e32 v73, 0xffff0000, v75
	v_and_b32_e32 v75, 0xffff0000, v77
	v_and_b32_e32 v91, 0xffff0000, v82
	s_waitcnt vmcnt(0)
	v_pk_mul_f32 v[38:39], v[38:39], v[56:57]
	s_nop 0
	v_fmac_f32_e32 v50, v35, v38
	v_mul_f32_e32 v35, v44, v114
	v_pk_mul_f32 v[40:41], v[40:41], v[58:59]
	v_fmac_f32_e32 v51, v35, v39
	v_mul_f32_e32 v35, v44, v113
	v_fmac_f32_e32 v74, v35, v40
	v_mul_f32_e32 v35, v44, v112
	v_fmac_f32_e32 v70, v37, v38
	v_mul_f32_e32 v37, v84, v116
	v_fmac_f32_e32 v75, v35, v41
	v_cvt_pk_bf16_f32 v50, v50, v51
	v_cvt_pk_bf16_f32 v51, v74, v75
	v_fmac_f32_e32 v71, v37, v39
	v_mul_f32_e32 v37, v84, v115
	global_store_dwordx2 v[32:33], v[50:51], off offset:1536 sc1
	v_lshlrev_b32_e32 v35, 16, v50
	v_and_b32_e32 v100, 0xffff0000, v50
	v_lshlrev_b32_e32 v99, 16, v51
	v_and_b32_e32 v98, 0xffff0000, v51
	v_fmac_f32_e32 v72, v37, v40
	v_fmac_f32_e32 v73, v34, v41
	v_cvt_pk_bf16_f32 v50, v70, v71
	v_cvt_pk_bf16_f32 v51, v72, v73
	global_store_dwordx2 v[32:33], v[50:51], off offset:3584 sc1
	v_mul_f32_e32 v32, v85, v43
	v_fmac_f32_e32 v66, v32, v38
	v_mul_f32_e32 v32, v85, v118
	v_fmac_f32_e32 v67, v32, v39
	v_mul_f32_e32 v32, v85, v117
	v_fmac_f32_e32 v68, v32, v40
	v_mul_f32_e32 v32, v85, v36
	v_fmac_f32_e32 v69, v32, v41
	v_mul_f32_e32 v32, v125, v45
	v_fmac_f32_e32 v62, v32, v38
	v_mul_f32_e32 v32, v125, v42
	v_fmac_f32_e32 v63, v32, v39
	v_mul_f32_e32 v32, v125, v120
	v_lshlrev_b32_e32 v33, 16, v50
	v_and_b32_e32 v103, 0xffff0000, v50
	v_lshlrev_b32_e32 v102, 16, v51
	v_and_b32_e32 v101, 0xffff0000, v51
	v_cvt_pk_bf16_f32 v50, v66, v67
	v_cvt_pk_bf16_f32 v51, v68, v69
	v_fmac_f32_e32 v64, v32, v40
	v_mul_f32_e32 v32, v125, v119
	v_and_b32_e32 v75, 0xffff0000, v2
	v_and_b32_e32 v73, 0xffff0000, v3
	global_store_dwordx2 v[12:13], v[50:51], off offset:1536 sc1
	v_lshlrev_b32_e32 v37, 16, v50
	v_and_b32_e32 v112, 0xffff0000, v50
	v_lshlrev_b32_e32 v105, 16, v51
	v_and_b32_e32 v104, 0xffff0000, v51
	v_fmac_f32_e32 v65, v32, v41
	v_lshlrev_b32_e32 v74, 16, v2
	v_lshlrev_b32_e32 v72, 16, v3
	v_mul_f32_e32 v2, v73, v73
	v_lshlrev_b32_e32 v50, 16, v48
	v_lshlrev_b32_e32 v51, 16, v49
	v_and_b32_e32 v49, 0xffff0000, v49
	v_and_b32_e32 v48, 0xffff0000, v48
	v_mul_f32_e32 v32, v75, v75
	v_cvt_pk_bf16_f32 v40, v62, v63
	v_cvt_pk_bf16_f32 v41, v64, v65
	global_store_dwordx2 v[12:13], v[40:41], off offset:3584 sc1
	v_pk_fma_f32 v[2:3], v[72:73], v[72:73], v[2:3] op_sel_hi:[1,1,0]
	v_pk_mul_f32 v[12:13], v[48:49], v[48:49]
	v_pk_fma_f32 v[44:45], v[74:75], v[74:75], v[32:33] op_sel_hi:[1,1,0]
	v_pk_fma_f32 v[12:13], v[50:51], v[50:51], v[12:13]
	v_mov_b32_e32 v34, v44
	v_mov_b32_e32 v56, v2
	v_mov_b32_e32 v57, v35
	v_mul_f32_e32 v36, v100, v100
	v_pk_add_f32 v[2:3], v[44:45], v[2:3]
	v_pk_mul_f32 v[44:45], v[34:35], v[56:57]
	v_pk_add_f32 v[12:13], v[12:13], v[12:13] op_sel:[0,1] op_sel_hi:[1,0]
	v_lshlrev_b32_e32 v114, 16, v41
	v_and_b32_e32 v113, 0xffff0000, v41
	v_and_b32_e32 v43, 0xffff0000, v60
; __device__ __forceinline__ void phase_rowwise(const Params& p, const float* xs32, const bf16_t* xs16, float* xd32, bf16_t* xd16, const bf16_t* y, const float* gpost, int modres,
;                                               bf16_t* hout, const float* gpre, int modh) {
;     ...
;         if (hout) {
;             float ss[RB];
; #pragma unroll
;             for (int r = 0; r < RB; ++r) { ss[r] = 0.f;
; #pragma unroll
;                 for (int j = 0; j < 4; ++j) ss[r] += (xv[r][j][0] * xv[r][j][0] + xv[r][j][1] * xv[r][j][1]) + (xv[r][j][2] * xv[r][j][2] + xv[r][j][3] * xv[r][j][3]); }
; #pragma unroll
;             for (int o = 1; o < 64; o <<= 1)
; #pragma unroll
;                 for (int r = 0; r < RB; ++r) ss[r] += __shfl_xor(ss[r], o);
; #pragma unroll
;             for (int j = 0; j < 4; ++j) { const f32x4 sh = *(const f32x4*)(modb + modh + lane * 4 + 256 * j), scl = *(const f32x4*)(modb + modh + 1024 + lane * 4 + 256 * j), gp = *(const f32x4*)(gpre + lane * 4 + 256 * j);
	v_and_b32_e32 v41, 0xffff0000, v61
	v_mov_b32_e32 v3, v45
	v_mov_b32_e32 v13, v36
	v_lshlrev_b32_e32 v39, 16, v40
	v_and_b32_e32 v115, 0xffff0000, v40
	v_lshlrev_b32_e32 v42, 16, v60
	v_lshlrev_b32_e32 v40, 16, v61
	v_pk_add_f32 v[2:3], v[2:3], v[12:13]
	v_mul_f32_e32 v12, v43, v43
	v_mul_f32_e32 v32, v41, v41
	v_mul_f32_e32 v38, v99, v99
	v_mul_f32_e32 v58, v98, v98
	v_pk_fma_f32 v[12:13], v[42:43], v[42:43], v[12:13] op_sel_hi:[1,1,0]
	v_pk_fma_f32 v[44:45], v[40:41], v[40:41], v[32:33] op_sel_hi:[1,1,0]
	v_mov_b32_e32 v13, v38
	v_mov_b32_e32 v45, v58
	v_pk_add_f32 v[12:13], v[12:13], v[44:45]
	v_and_b32_e32 v71, 0xffff0000, v6
	v_and_b32_e32 v65, 0xffff0000, v7
	v_pk_add_f32 v[92:93], v[2:3], v[12:13]
	v_lshlrev_b32_e32 v70, 16, v6
	v_lshlrev_b32_e32 v64, 16, v7
	v_mul_f32_e32 v2, v65, v65
	v_and_b32_e32 v57, 0xffff0000, v47
	v_and_b32_e32 v56, 0xffff0000, v46
	v_mul_f32_e32 v12, v71, v71
	v_pk_fma_f32 v[2:3], v[64:65], v[64:65], v[2:3] op_sel_hi:[1,1,0]
	v_lshlrev_b32_e32 v59, 16, v47
	v_lshlrev_b32_e32 v58, 16, v46
	v_pk_mul_f32 v[6:7], v[56:57], v[56:57]
	v_pk_fma_f32 v[12:13], v[70:71], v[70:71], v[12:13] op_sel_hi:[1,1,0]
	v_pk_fma_f32 v[6:7], v[58:59], v[58:59], v[6:7]
	v_lshlrev_b32_e32 v46, 16, v54
	v_and_b32_e32 v47, 0xffff0000, v54
	v_lshlrev_b32_e32 v44, 16, v55
	v_and_b32_e32 v45, 0xffff0000, v55
	v_mov_b32_e32 v32, v12
	v_mov_b32_e32 v54, v2
	v_mov_b32_e32 v55, v33
	v_mul_f32_e32 v34, v103, v103
	v_pk_add_f32 v[2:3], v[12:13], v[2:3]
	v_pk_mul_f32 v[12:13], v[32:33], v[54:55]
	v_pk_add_f32 v[6:7], v[6:7], v[6:7] op_sel:[0,1] op_sel_hi:[1,0]
	v_mov_b32_e32 v3, v13
	v_mov_b32_e32 v7, v34
	v_pk_add_f32 v[2:3], v[2:3], v[6:7]
	v_mul_f32_e32 v6, v47, v47
	v_mul_f32_e32 v12, v45, v45
	v_mul_f32_e32 v36, v102, v102
	v_mul_f32_e32 v38, v101, v101
	v_pk_fma_f32 v[6:7], v[46:47], v[46:47], v[6:7] op_sel_hi:[1,1,0]
	v_pk_fma_f32 v[12:13], v[44:45], v[44:45], v[12:13] op_sel_hi:[1,1,0]
	v_mov_b32_e32 v7, v36
	v_mov_b32_e32 v13, v38
	v_pk_add_f32 v[6:7], v[6:7], v[12:13]
	v_and_b32_e32 v67, 0xffff0000, v5
	v_pk_add_f32 v[94:95], v[2:3], v[6:7]
	v_lshlrev_b32_e32 v66, 16, v5
	v_mul_f32_e32 v2, v67, v67
	v_and_b32_e32 v61, 0xffff0000, v9
	v_and_b32_e32 v60, 0xffff0000, v8
	v_pk_fma_f32 v[12:13], v[66:67], v[66:67], v[2:3] op_sel_hi:[1,1,0]
	v_lshlrev_b32_e32 v63, 16, v9
	v_lshlrev_b32_e32 v62, 16, v8
	v_pk_mul_f32 v[2:3], v[60:61], v[60:61]
	v_and_b32_e32 v69, 0xffff0000, v4
	v_pk_fma_f32 v[80:81], v[62:63], v[62:63], v[2:3]
	v_lshl_add_u64 v[2:3], s[8:9], 2, v[10:11]
	v_lshlrev_b32_e32 v68, 16, v4
	v_mul_f32_e32 v32, v69, v69
	v_lshl_add_u64 v[76:77], v[2:3], 0, v[24:25]
	v_add_co_u32_e32 v6, vcc, s10, v76
	v_pk_fma_f32 v[10:11], v[68:69], v[68:69], v[32:33] op_sel_hi:[1,1,0]
	s_nop 0
	v_addc_co_u32_e32 v7, vcc, 0, v77, vcc
	v_mov_b32_e32 v36, v10
	v_mov_b32_e32 v84, v12
	v_mov_b32_e32 v85, v37
	global_load_dwordx4 v[2:5], v[76:77], off
	s_nop 0
	global_load_dwordx4 v[6:9], v[6:7], off
	v_pk_add_f32 v[88:89], v[10:11], v[12:13]
	v_pk_mul_f32 v[10:11], v[36:37], v[84:85]
	v_and_b32_e32 v55, 0xffff0000, v52
	v_mov_b32_e32 v89, v11
	global_load_dwordx4 v[10:13], v[16:17], off
	v_lshlrev_b32_e32 v54, 16, v52
	v_lshlrev_b32_e32 v52, 16, v53
	v_and_b32_e32 v53, 0xffff0000, v53
	v_mul_f32_e32 v34, v112, v112
	v_pk_add_f32 v[80:81], v[80:81], v[80:81] op_sel:[0,1] op_sel_hi:[1,0]
	v_mul_f32_e32 v32, v55, v55
	v_mov_b32_e32 v81, v34
	v_pk_fma_f32 v[84:85], v[54:55], v[54:55], v[32:33] op_sel_hi:[1,1,0]
	v_mul_f32_e32 v32, v53, v53
	v_mul_f32_e32 v38, v105, v105
	v_mul_f32_e32 v90, v104, v104
	v_pk_add_f32 v[80:81], v[88:89], v[80:81]
	v_pk_fma_f32 v[88:89], v[52:53], v[52:53], v[32:33] op_sel_hi:[1,1,0]
	v_mov_b32_e32 v85, v38
	v_mov_b32_e32 v89, v90
	v_pk_add_f32 v[84:85], v[84:85], v[88:89]
	v_lshlrev_b32_e32 v90, 16, v82
	v_lshlrev_b32_e32 v88, 16, v83
	v_and_b32_e32 v89, 0xffff0000, v83
	v_and_b32_e32 v83, 0xffff0000, v79
	v_and_b32_e32 v82, 0xffff0000, v78
	v_pk_add_f32 v[96:97], v[80:81], v[84:85]
	v_lshlrev_b32_e32 v85, 16, v79
	v_lshlrev_b32_e32 v84, 16, v78
	v_pk_mul_f32 v[78:79], v[82:83], v[82:83]
	v_lshlrev_b32_e32 v80, 16, v86
	v_pk_fma_f32 v[118:119], v[84:85], v[84:85], v[78:79]
	v_and_b32_e32 v81, 0xffff0000, v86
	v_lshlrev_b32_e32 v78, 16, v87
	v_and_b32_e32 v79, 0xffff0000, v87
	v_mov_b32_e32 v86, v94
	v_mov_b32_e32 v87, v92
	v_mov_b32_e32 v92, v95
	v_pk_add_f32 v[86:87], v[86:87], v[92:93]
	ds_bpermute_b32 v93, v106, v87
	ds_bpermute_b32 v92, v106, v86
	v_mul_f32_e32 v32, v89, v89
	v_pk_fma_f32 v[116:117], v[88:89], v[88:89], v[32:33] op_sel_hi:[1,1,0]
	v_mul_f32_e32 v32, v91, v91
	v_pk_fma_f32 v[94:95], v[90:91], v[90:91], v[32:33] op_sel_hi:[1,1,0]
	s_waitcnt lgkmcnt(0)
	v_pk_add_f32 v[86:87], v[86:87], v[92:93]
	ds_bpermute_b32 v93, v107, v87
	ds_bpermute_b32 v92, v107, v86
	v_mov_b32_e32 v38, v94
	v_mov_b32_e32 v120, v116
	v_mov_b32_e32 v121, v39
	v_pk_add_f32 v[94:95], v[94:95], v[116:117]
	s_waitcnt lgkmcnt(0)
	v_pk_add_f32 v[86:87], v[86:87], v[92:93]
	ds_bpermute_b32 v93, v108, v87
	ds_bpermute_b32 v92, v108, v86
	v_pk_mul_f32 v[116:117], v[38:39], v[120:121]
	v_mul_f32_e32 v25, v115, v115
	v_mov_b32_e32 v95, v117
	v_pk_add_f32 v[116:117], v[118:119], v[118:119] op_sel:[0,1] op_sel_hi:[1,0]
	s_waitcnt lgkmcnt(0)
	v_pk_add_f32 v[86:87], v[86:87], v[92:93]
	ds_bpermute_b32 v93, v109, v87
	ds_bpermute_b32 v92, v109, v86
	v_mov_b32_e32 v117, v25
	v_mul_f32_e32 v32, v81, v81
	v_pk_add_f32 v[94:95], v[94:95], v[116:117]
	v_pk_fma_f32 v[116:117], v[80:81], v[80:81], v[32:33] op_sel_hi:[1,1,0]
	s_waitcnt lgkmcnt(0)
; __device__ __forceinline__ unsigned pk2(float lo, float hi) { unsigned r; asm("v_cvt_pk_bf16_f32 %0, %1, %2" : "=v"(r) : "v"(lo), "v"(hi)); return r; }
; __device__ __forceinline__ void phase_rowwise(const Params& p, const float* xs32, const bf16_t* xs16, float* xd32, bf16_t* xd16, const bf16_t* y, const float* gpost, int modres,
;                                               bf16_t* hout, const float* gpre, int modh) {
;     ...
;             for (int o = 1; o < 64; o <<= 1)
; #pragma unroll
;                 for (int r = 0; r < RB; ++r) ss[r] += __shfl_xor(ss[r], o);
; #pragma unroll
;             for (int j = 0; j < 4; ++j) { const f32x4 sh = *(const f32x4*)(modb + modh + lane * 4 + 256 * j), scl = *(const f32x4*)(modb + modh + 1024 + lane * 4 + 256 * j), gp = *(const f32x4*)(gpre + lane * 4 + 256 * j);
;                 const f32x4 gs = gp * (scl + 1.f);
; #pragma unroll
;                 for (int r = 0; r < RB; ++r) { const float rstd = rsqrtf(ss[r] * (1.f / D) + EPS);
;                     u32x2 o; o.x = pk2(xv[r][j][0] * rstd * gs[0] + sh[0], xv[r][j][1] * rstd * gs[1] + sh[1]); o.y = pk2(xv[r][j][2] * rstd * gs[2] + sh[2], xv[r][j][3] * rstd * gs[3] + sh[3]);
;                     *(u32x2*)(hout + (row0 + r) * LDH + lane * 4 + 256 * j) = o; } }
	v_pk_add_f32 v[86:87], v[86:87], v[92:93]
	ds_bpermute_b32 v93, v110, v87
	ds_bpermute_b32 v92, v110, v86
	v_mul_f32_e32 v32, v79, v79
	v_mul_f32_e32 v34, v114, v114
	v_mul_f32_e32 v36, v113, v113
	v_pk_fma_f32 v[118:119], v[78:79], v[78:79], v[32:33] op_sel_hi:[1,1,0]
	s_waitcnt lgkmcnt(0)
	v_pk_add_f32 v[92:93], v[86:87], v[92:93]
	ds_bpermute_b32 v121, v111, v93
	ds_bpermute_b32 v120, v111, v92
	v_mov_b32_e32 v117, v34
	v_mov_b32_e32 v119, v36
	v_pk_add_f32 v[86:87], v[116:117], v[118:119]
	s_waitcnt vmcnt(1)
	v_pk_add_f32 v[8:9], v[8:9], 1.0 op_sel_hi:[1,0]
	s_waitcnt lgkmcnt(0)
	v_pk_add_f32 v[92:93], v[92:93], v[120:121]
	v_pk_add_f32 v[116:117], v[6:7], 1.0 op_sel_hi:[1,0]
	v_pk_fma_f32 v[92:93], v[92:93], s[12:13], v[30:31] op_sel_hi:[1,0,0]
	v_pk_add_f32 v[94:95], v[94:95], v[86:87]
	v_mul_f32_e32 v25, 0x4b800000, v93
	v_cmp_gt_f32_e32 vcc, s76, v93
	s_waitcnt vmcnt(0)
	v_pk_mul_f32 v[6:7], v[12:13], v[8:9]
	v_pk_mul_f32 v[8:9], v[10:11], v[116:117]
	v_cndmask_b32_e32 v25, v93, v25, vcc
	v_rsq_f32_e32 v25, v25
	v_mov_b32_e32 v11, v96
	v_mov_b32_e32 v96, v95
	v_mul_f32_e32 v36, 0x4b800000, v92
	v_mul_f32_e32 v10, 0x45800000, v25
	v_cndmask_b32_e32 v25, v25, v10, vcc
	v_mov_b32_e32 v10, v94
	v_pk_add_f32 v[10:11], v[10:11], v[96:97]
	ds_bpermute_b32 v13, v106, v11
	ds_bpermute_b32 v12, v106, v10
	v_cmp_gt_f32_e32 vcc, s76, v92
	v_mul_f32_e32 v32, v25, v74
	v_fma_f32 v32, v8, v32, v2
	v_cndmask_b32_e32 v36, v92, v36, vcc
	s_waitcnt lgkmcnt(0)
	v_pk_add_f32 v[10:11], v[10:11], v[12:13]
	ds_bpermute_b32 v13, v107, v11
	ds_bpermute_b32 v12, v107, v10
	v_rsq_f32_e32 v36, v36
	v_mul_f32_e32 v34, v25, v75
	v_fma_f32 v34, v9, v34, v3
	v_cvt_pk_bf16_f32 v74, v32, v34
	s_waitcnt lgkmcnt(0)
	v_pk_add_f32 v[10:11], v[10:11], v[12:13]
	ds_bpermute_b32 v13, v108, v11
	ds_bpermute_b32 v12, v108, v10
	v_mul_f32_e32 v32, v25, v72
	v_fma_f32 v32, v6, v32, v4
	v_mul_f32_e32 v34, v25, v73
	v_fma_f32 v34, v7, v34, v5
	s_waitcnt lgkmcnt(0)
	v_pk_add_f32 v[10:11], v[10:11], v[12:13]
	ds_bpermute_b32 v13, v109, v11
	ds_bpermute_b32 v12, v109, v10
	v_cvt_pk_bf16_f32 v75, v32, v34
	v_mul_f32_e32 v32, 0x45800000, v36
	v_cndmask_b32_e32 v32, v36, v32, vcc
	v_mul_f32_e32 v36, v32, v71
	s_waitcnt lgkmcnt(0)
	v_pk_add_f32 v[10:11], v[10:11], v[12:13]
	ds_bpermute_b32 v13, v110, v11
	ds_bpermute_b32 v12, v110, v10
	v_mul_f32_e32 v34, v32, v70
	v_fma_f32 v36, v9, v36, v3
	v_fma_f32 v34, v8, v34, v2
	v_cvt_pk_bf16_f32 v70, v34, v36
	s_waitcnt lgkmcnt(0)
	v_pk_add_f32 v[10:11], v[10:11], v[12:13]
	ds_bpermute_b32 v13, v111, v11
	ds_bpermute_b32 v12, v111, v10
	v_mul_f32_e32 v36, v32, v65
	v_mul_f32_e32 v34, v32, v64
	v_fma_f32 v34, v6, v34, v4
	v_lshl_add_u64 v[86:87], v[76:77], 0, s[86:87]
	s_waitcnt lgkmcnt(0)
	v_pk_add_f32 v[10:11], v[10:11], v[12:13]
	global_store_dwordx2 v[26:27], v[74:75], off sc1
	v_pk_fma_f32 v[10:11], v[10:11], s[12:13], v[30:31] op_sel_hi:[1,0,0]
	s_nop 0
	v_mul_f32_e32 v12, 0x4b800000, v11
	v_cmp_gt_f32_e32 vcc, s76, v11
	v_mul_f32_e32 v31, 0x4b800000, v10
	s_nop 0
	v_cndmask_b32_e32 v11, v11, v12, vcc
	v_rsq_f32_e32 v11, v11
	v_fma_f32 v12, v7, v36, v5
	v_cvt_pk_bf16_f32 v71, v34, v12
	global_store_dwordx2 v[26:27], v[70:71], off offset:2176 sc1
	v_mul_f32_e32 v12, 0x45800000, v11
	v_cndmask_b32_e32 v30, v11, v12, vcc
	v_cmp_gt_f32_e32 vcc, s76, v10
	v_mul_f32_e32 v11, v30, v68
	v_mul_f32_e32 v12, v30, v69
	v_cndmask_b32_e32 v10, v10, v31, vcc
	v_rsq_f32_e32 v10, v10
	v_fma_f32 v11, v8, v11, v2
	v_fma_f32 v12, v9, v12, v3
	v_cvt_pk_bf16_f32 v12, v11, v12
	v_mul_f32_e32 v11, v30, v66
	v_mul_f32_e32 v13, v30, v67
	v_fma_f32 v11, v6, v11, v4
	v_fma_f32 v13, v7, v13, v5
	v_cvt_pk_bf16_f32 v13, v11, v13
	v_mul_f32_e32 v11, 0x45800000, v10
	v_cndmask_b32_e32 v31, v10, v11, vcc
	v_mul_f32_e32 v10, v31, v90
	v_fma_f32 v2, v8, v10, v2
	v_mul_f32_e32 v8, v31, v91
	v_fma_f32 v3, v9, v8, v3
	v_cvt_pk_bf16_f32 v2, v2, v3
	v_mul_f32_e32 v3, v31, v88
	v_fma_f32 v3, v6, v3, v4
	v_mul_f32_e32 v4, v31, v89
	global_store_dwordx2 v[28:29], v[12:13], off offset:256 sc1
	v_fmac_f32_e32 v5, v7, v4
	v_cvt_pk_bf16_f32 v3, v3, v5
	global_store_dwordx2 v[28:29], v[2:3], off offset:2432 sc1
	global_load_dwordx4 v[2:5], v[86:87], off offset:1024
	s_nop 0
	global_load_dwordx4 v[6:9], v[16:17], off offset:1024
	global_load_dwordx4 v[10:13], v[76:77], off offset:1024
	s_waitcnt vmcnt(2)
	v_pk_add_f32 v[2:3], v[2:3], 1.0 op_sel_hi:[1,0]
	s_waitcnt vmcnt(1)
	v_pk_mul_f32 v[2:3], v[6:7], v[2:3]
	v_mul_f32_e32 v6, v25, v50
	v_mul_f32_e32 v7, v25, v48
	v_pk_add_f32 v[4:5], v[4:5], 1.0 op_sel_hi:[1,0]
	s_waitcnt vmcnt(0)
; __device__ __forceinline__ unsigned pk2(float lo, float hi) { unsigned r; asm("v_cvt_pk_bf16_f32 %0, %1, %2" : "=v"(r) : "v"(lo), "v"(hi)); return r; }
; __device__ __forceinline__ void phase_rowwise(const Params& p, const float* xs32, const bf16_t* xs16, float* xd32, bf16_t* xd16, const bf16_t* y, const float* gpost, int modres,
;                                               bf16_t* hout, const float* gpre, int modh) {
;     ...
;             for (int j = 0; j < 4; ++j) { const f32x4 sh = *(const f32x4*)(modb + modh + lane * 4 + 256 * j), scl = *(const f32x4*)(modb + modh + 1024 + lane * 4 + 256 * j), gp = *(const f32x4*)(gpre + lane * 4 + 256 * j);
;                 const f32x4 gs = gp * (scl + 1.f);
; #pragma unroll
;                 for (int r = 0; r < RB; ++r) { const float rstd = rsqrtf(ss[r] * (1.f / D) + EPS);
;                     u32x2 o; o.x = pk2(xv[r][j][0] * rstd * gs[0] + sh[0], xv[r][j][1] * rstd * gs[1] + sh[1]); o.y = pk2(xv[r][j][2] * rstd * gs[2] + sh[2], xv[r][j][3] * rstd * gs[3] + sh[3]);
;                     *(u32x2*)(hout + (row0 + r) * LDH + lane * 4 + 256 * j) = o; } }
	v_fma_f32 v6, v6, v2, v10
	v_fma_f32 v7, v7, v3, v11
	v_pk_mul_f32 v[4:5], v[8:9], v[4:5]
	v_cvt_pk_bf16_f32 v6, v6, v7
	v_mul_f32_e32 v7, v25, v51
	v_fma_f32 v7, v7, v4, v12
	v_mul_f32_e32 v8, v25, v49
	v_fma_f32 v8, v8, v5, v13
	v_cvt_pk_bf16_f32 v7, v7, v8
	global_store_dwordx2 v[26:27], v[6:7], off offset:512 sc1
	v_mul_f32_e32 v6, v32, v58
	v_mul_f32_e32 v7, v32, v56
	v_fma_f32 v6, v6, v2, v10
	v_fma_f32 v7, v7, v3, v11
	v_cvt_pk_bf16_f32 v6, v6, v7
	v_mul_f32_e32 v7, v32, v59
	v_fma_f32 v7, v7, v4, v12
	v_mul_f32_e32 v8, v32, v57
	v_fma_f32 v8, v8, v5, v13
	v_cvt_pk_bf16_f32 v7, v7, v8
	global_store_dwordx2 v[26:27], v[6:7], off offset:2688 sc1
	v_mul_f32_e32 v6, v30, v62
	v_mul_f32_e32 v7, v30, v60
	v_fma_f32 v6, v6, v2, v10
	v_fma_f32 v7, v7, v3, v11
	v_cvt_pk_bf16_f32 v6, v6, v7
	v_mul_f32_e32 v7, v30, v63
	v_fma_f32 v7, v7, v4, v12
	v_mul_f32_e32 v8, v30, v61
	v_fma_f32 v8, v8, v5, v13
	v_cvt_pk_bf16_f32 v7, v7, v8
	global_store_dwordx2 v[28:29], v[6:7], off offset:768 sc1
	v_mul_f32_e32 v6, v31, v84
	v_fma_f32 v2, v6, v2, v10
	v_mul_f32_e32 v6, v31, v82
	v_fma_f32 v3, v6, v3, v11
	v_cvt_pk_bf16_f32 v2, v2, v3
	v_mul_f32_e32 v3, v31, v85
	v_fma_f32 v3, v3, v4, v12
	v_mul_f32_e32 v4, v31, v83
	v_fmac_f32_e32 v13, v4, v5
	v_cvt_pk_bf16_f32 v3, v3, v13
	global_store_dwordx2 v[28:29], v[2:3], off offset:2944 sc1
	global_load_dwordx4 v[2:5], v[86:87], off offset:2048
	s_nop 0
	global_load_dwordx4 v[6:9], v[16:17], off offset:2048
	global_load_dwordx4 v[10:13], v[76:77], off offset:2048
	s_waitcnt vmcnt(2)
	v_pk_add_f32 v[2:3], v[2:3], 1.0 op_sel_hi:[1,0]
	s_waitcnt vmcnt(1)
	v_pk_mul_f32 v[2:3], v[6:7], v[2:3]
	v_mul_f32_e32 v6, v25, v42
	v_mul_f32_e32 v7, v25, v43
	v_pk_add_f32 v[4:5], v[4:5], 1.0 op_sel_hi:[1,0]
	s_waitcnt vmcnt(0)
	v_fma_f32 v6, v6, v2, v10
	v_fma_f32 v7, v7, v3, v11
	v_pk_mul_f32 v[4:5], v[8:9], v[4:5]
	v_cvt_pk_bf16_f32 v6, v6, v7
	v_mul_f32_e32 v7, v25, v40
	v_fma_f32 v7, v7, v4, v12
	v_mul_f32_e32 v8, v25, v41
	v_fma_f32 v8, v8, v5, v13
	v_cvt_pk_bf16_f32 v7, v7, v8
	global_store_dwordx2 v[26:27], v[6:7], off offset:1024 sc1
	v_mul_f32_e32 v6, v32, v46
	v_mul_f32_e32 v7, v32, v47
	v_fma_f32 v6, v6, v2, v10
	v_fma_f32 v7, v7, v3, v11
	v_cvt_pk_bf16_f32 v6, v6, v7
	v_mul_f32_e32 v7, v32, v44
	v_fma_f32 v7, v7, v4, v12
	v_mul_f32_e32 v8, v32, v45
	v_fma_f32 v8, v8, v5, v13
	v_cvt_pk_bf16_f32 v7, v7, v8
	global_store_dwordx2 v[26:27], v[6:7], off offset:3200 sc1
	v_mul_f32_e32 v6, v30, v54
	v_mul_f32_e32 v7, v30, v55
	v_fma_f32 v6, v6, v2, v10
	v_fma_f32 v7, v7, v3, v11
	v_cvt_pk_bf16_f32 v6, v6, v7
	v_mul_f32_e32 v7, v30, v52
	v_fma_f32 v7, v7, v4, v12
	v_mul_f32_e32 v8, v30, v53
	v_fma_f32 v8, v8, v5, v13
	v_cvt_pk_bf16_f32 v7, v7, v8
	global_store_dwordx2 v[28:29], v[6:7], off offset:1280 sc1
	v_mul_f32_e32 v6, v31, v80
	v_fma_f32 v2, v6, v2, v10
	v_mul_f32_e32 v6, v31, v81
	v_fma_f32 v3, v6, v3, v11
	v_cvt_pk_bf16_f32 v2, v2, v3
	v_mul_f32_e32 v3, v31, v78
	v_fma_f32 v3, v3, v4, v12
	v_mul_f32_e32 v4, v31, v79
	v_fmac_f32_e32 v13, v4, v5
	v_cvt_pk_bf16_f32 v3, v3, v13
	global_store_dwordx2 v[28:29], v[2:3], off offset:3456 sc1
	global_load_dwordx4 v[2:5], v[86:87], off offset:3072
	s_nop 0
	global_load_dwordx4 v[6:9], v[16:17], off offset:3072
	global_load_dwordx4 v[10:13], v[76:77], off offset:3072
	s_waitcnt vmcnt(2)
	v_pk_add_f32 v[2:3], v[2:3], 1.0 op_sel_hi:[1,0]
	s_waitcnt vmcnt(1)
	v_pk_mul_f32 v[2:3], v[6:7], v[2:3]
	v_mul_f32_e32 v6, v25, v35
	v_mul_f32_e32 v7, v25, v100
	v_pk_add_f32 v[4:5], v[4:5], 1.0 op_sel_hi:[1,0]
	s_waitcnt vmcnt(0)
	v_fma_f32 v6, v6, v2, v10
	v_fma_f32 v7, v7, v3, v11
	v_pk_mul_f32 v[4:5], v[8:9], v[4:5]
	v_cvt_pk_bf16_f32 v6, v6, v7
	v_mul_f32_e32 v7, v25, v99
	v_fma_f32 v7, v7, v4, v12
	v_mul_f32_e32 v8, v25, v98
	v_fma_f32 v8, v8, v5, v13
	v_cvt_pk_bf16_f32 v7, v7, v8
	global_store_dwordx2 v[26:27], v[6:7], off offset:1536 sc1
	v_mul_f32_e32 v6, v32, v33
	v_mul_f32_e32 v7, v32, v103
	v_fma_f32 v6, v6, v2, v10
	v_fma_f32 v7, v7, v3, v11
	v_cvt_pk_bf16_f32 v6, v6, v7
	v_mul_f32_e32 v7, v32, v102
	v_fma_f32 v7, v7, v4, v12
	v_mul_f32_e32 v8, v32, v101
	v_fma_f32 v8, v8, v5, v13
	v_cvt_pk_bf16_f32 v7, v7, v8
	global_store_dwordx2 v[26:27], v[6:7], off offset:3712 sc1
	v_mul_f32_e32 v6, v30, v37
	v_mul_f32_e32 v7, v30, v112
	v_fma_f32 v6, v6, v2, v10
	v_fma_f32 v7, v7, v3, v11
	v_cvt_pk_bf16_f32 v6, v6, v7
	v_mul_f32_e32 v7, v30, v105
	v_fma_f32 v7, v7, v4, v12
	v_mul_f32_e32 v8, v30, v104
	v_fma_f32 v8, v8, v5, v13
	v_cvt_pk_bf16_f32 v7, v7, v8
	global_store_dwordx2 v[28:29], v[6:7], off offset:1792 sc1
	v_mul_f32_e32 v6, v31, v39
	v_fma_f32 v2, v6, v2, v10
	v_mul_f32_e32 v6, v31, v115
	v_fma_f32 v3, v6, v3, v11
	v_cvt_pk_bf16_f32 v2, v2, v3
	v_mul_f32_e32 v3, v31, v114
	v_fma_f32 v3, v3, v4, v12
	v_mul_f32_e32 v4, v31, v113
	v_fmac_f32_e32 v13, v4, v5
	v_cvt_pk_bf16_f32 v3, v3, v13
	global_store_dwordx2 v[28:29], v[2:3], off offset:3968 sc1
	s_branch .LBB0_148

; __device__ __forceinline__ void phase_rowwise(const Params& p, const float* xs32, const bf16_t* xs16, float* xd32, bf16_t* xd16, const bf16_t* y, const float* gpost, int modres,
;                                               bf16_t* hout, const float* gpre, int modh) {
;     ...
;         if (hout) {
;             float ss[RB];
; #pragma unroll
;             for (int r = 0; r < RB; ++r) { ss[r] = 0.f;
; #pragma unroll
;                 for (int j = 0; j < 4; ++j) ss[r] += (xv[r][j][0] * xv[r][j][0] + xv[r][j][1] * xv[r][j][1]) + (xv[r][j][2] * xv[r][j][2] + xv[r][j][3] * xv[r][j][3]); }
; #pragma unroll
;             for (int o = 1; o < 64; o <<= 1)
; #pragma unroll
;                 for (int r = 0; r < RB; ++r) ss[r] += __shfl_xor(ss[r], o);
; #pragma unroll
;             for (int j = 0; j < 4; ++j) { const f32x4 sh = *(const f32x4*)(modb + modh + lane * 4 + 256 * j), scl = *(const f32x4*)(modb + modh + 1024 + lane * 4 + 256 * j), gp = *(const f32x4*)(gpre + lane * 4 + 256 * j);
.LBB0_261:
	v_readlane_b32 s0, v254, 56
	v_readlane_b32 s1, v254, 57
	s_andn2_b64 vcc, exec, s[0:1]
	s_cbranch_vccnz .LBB0_257
	s_waitcnt vmcnt(15)
	v_pk_mul_f32 v[68:69], v[64:65], v[64:65]
	v_pk_mul_f32 v[82:83], v[62:63], v[62:63]
	s_waitcnt vmcnt(12)
	v_mul_f32_e32 v81, v2, v2
	v_pk_mov_b32 v[84:85], v[82:83], v[68:69] op_sel:[1,0]
	v_mov_b32_e32 v83, v69
	v_pk_add_f32 v[68:69], v[84:85], v[82:83]
	v_pk_mul_f32 v[82:83], v[36:37], v[36:37]
	v_pk_mul_f32 v[84:85], v[34:35], v[34:35]
	v_pk_add_f32 v[68:69], v[68:69], v[68:69] op_sel:[0,1] op_sel_hi:[1,0]
	v_pk_mov_b32 v[86:87], v[84:85], v[82:83] op_sel:[1,0]
	v_mov_b32_e32 v85, v83
	v_pk_add_f32 v[82:83], v[86:87], v[84:85]
	v_mul_f32_e32 v84, v3, v3
	v_pk_add_f32 v[82:83], v[82:83], v[82:83] op_sel:[0,1] op_sel_hi:[1,0]
	v_mov_b32_e32 v69, v81
	v_mov_b32_e32 v83, v84
	v_pk_add_f32 v[68:69], v[68:69], v[82:83]
	v_mul_f32_e32 v82, v19, v19
	v_mul_f32_e32 v85, v4, v4
	v_pk_fma_f32 v[82:83], v[18:19], v[18:19], v[82:83] op_sel_hi:[1,1,0]
	v_mul_f32_e32 v84, v21, v21
	v_mul_f32_e32 v86, v5, v5
	v_mov_b32_e32 v83, v85
	v_pk_fma_f32 v[84:85], v[20:21], v[20:21], v[84:85] op_sel_hi:[1,1,0]
	s_waitcnt vmcnt(8)
	v_mul_f32_e32 v81, v6, v6
	v_mov_b32_e32 v85, v86
	v_pk_add_f32 v[82:83], v[82:83], v[84:85]
	v_ashrrev_i32_e32 v66, 9, v1
	v_pk_add_f32 v[84:85], v[68:69], v[82:83]
	v_pk_mul_f32 v[68:69], v[52:53], v[52:53]
	v_pk_mul_f32 v[82:83], v[50:51], v[50:51]
	v_mul_hi_i32_i24_e32 v67, 0x18000, v66
	v_pk_mov_b32 v[86:87], v[82:83], v[68:69] op_sel:[1,0]
	v_mov_b32_e32 v83, v69
	v_pk_add_f32 v[68:69], v[86:87], v[82:83]
	v_pk_mul_f32 v[82:83], v[40:41], v[40:41]
	v_pk_mul_f32 v[86:87], v[38:39], v[38:39]
	v_pk_add_f32 v[68:69], v[68:69], v[68:69] op_sel:[0,1] op_sel_hi:[1,0]
	v_pk_mov_b32 v[88:89], v[86:87], v[82:83] op_sel:[1,0]
	v_mov_b32_e32 v87, v83
	v_pk_add_f32 v[82:83], v[88:89], v[86:87]
	v_mul_f32_e32 v86, v7, v7
	v_pk_add_f32 v[82:83], v[82:83], v[82:83] op_sel:[0,1] op_sel_hi:[1,0]
	v_mov_b32_e32 v69, v81
	v_mov_b32_e32 v83, v86
	v_pk_add_f32 v[68:69], v[68:69], v[82:83]
	v_mul_f32_e32 v82, v23, v23
	v_mul_f32_e32 v87, v8, v8
	v_pk_fma_f32 v[82:83], v[22:23], v[22:23], v[82:83] op_sel_hi:[1,1,0]
	v_mul_f32_e32 v86, v25, v25
	v_mul_f32_e32 v88, v9, v9
	v_mov_b32_e32 v83, v87
	v_pk_fma_f32 v[86:87], v[24:25], v[24:25], v[86:87] op_sel_hi:[1,1,0]
	s_waitcnt vmcnt(4)
	v_mul_f32_e32 v81, v10, v10
	v_mov_b32_e32 v87, v88
	v_pk_add_f32 v[82:83], v[82:83], v[86:87]
	v_mul_i32_i24_e32 v66, 0x18000, v66
	v_pk_add_f32 v[86:87], v[68:69], v[82:83]
	v_pk_mul_f32 v[68:69], v[60:61], v[60:61]
	v_pk_mul_f32 v[82:83], v[58:59], v[58:59]
	v_mul_f32_e32 v98, v13, v13
	v_pk_mov_b32 v[88:89], v[82:83], v[68:69] op_sel:[1,0]
	v_mov_b32_e32 v83, v69
	v_pk_add_f32 v[68:69], v[88:89], v[82:83]
	v_pk_mul_f32 v[82:83], v[44:45], v[44:45]
	v_pk_mul_f32 v[88:89], v[42:43], v[42:43]
	v_pk_add_f32 v[68:69], v[68:69], v[68:69] op_sel:[0,1] op_sel_hi:[1,0]
	v_pk_mov_b32 v[90:91], v[88:89], v[82:83] op_sel:[1,0]
	v_mov_b32_e32 v89, v83
	v_pk_add_f32 v[82:83], v[90:91], v[88:89]
	v_mul_f32_e32 v88, v11, v11
	v_pk_add_f32 v[82:83], v[82:83], v[82:83] op_sel:[0,1] op_sel_hi:[1,0]
	v_mov_b32_e32 v69, v81
	v_mov_b32_e32 v83, v88
	v_pk_add_f32 v[92:93], v[68:69], v[82:83]
	v_mul_f32_e32 v68, v27, v27
	v_pk_fma_f32 v[94:95], v[26:27], v[26:27], v[68:69] op_sel_hi:[1,1,0]
	v_mul_f32_e32 v68, v29, v29
	v_mul_f32_e32 v89, v12, v12
	v_pk_fma_f32 v[96:97], v[28:29], v[28:29], v[68:69] op_sel_hi:[1,1,0]
	v_lshl_add_u64 v[66:67], s[6:7], 0, v[66:67]
	v_mov_b32_e32 v81, v0
	v_mov_b32_e32 v95, v89
	v_lshl_add_u64 v[82:83], v[66:67], 0, v[80:81]
	s_movk_i32 s0, 0x1000
	v_mov_b32_e32 v97, v98
	v_add_co_u32_e32 v88, vcc, s0, v82
	v_pk_add_f32 v[94:95], v[94:95], v[96:97]
	s_nop 0
	v_addc_co_u32_e32 v89, vcc, 0, v83, vcc
	v_pk_add_f32 v[96:97], v[92:93], v[94:95]
	s_waitcnt vmcnt(3)
	v_pk_mul_f32 v[92:93], v[56:57], v[56:57]
	v_pk_mul_f32 v[94:95], v[54:55], v[54:55]
	global_load_dwordx4 v[66:69], v[82:83], off
	s_nop 0
	global_load_dwordx4 v[88:91], v[88:89], off
	v_pk_mov_b32 v[98:99], v[94:95], v[92:93] op_sel:[1,0]
	v_mov_b32_e32 v95, v93
	v_pk_add_f32 v[98:99], v[98:99], v[94:95]
	global_load_dwordx4 v[92:95], v[70:71], off
	s_waitcnt vmcnt(5)
	v_pk_mul_f32 v[100:101], v[48:49], v[48:49]
	v_pk_mul_f32 v[102:103], v[46:47], v[46:47]
	s_waitcnt vmcnt(3)
	v_mul_f32_e32 v81, v14, v14
	v_pk_mov_b32 v[104:105], v[102:103], v[100:101] op_sel:[1,0]
	v_mov_b32_e32 v103, v101
	v_pk_add_f32 v[100:101], v[104:105], v[102:103]
	v_mul_f32_e32 v102, v15, v15
	v_pk_add_f32 v[98:99], v[98:99], v[98:99] op_sel:[0,1] op_sel_hi:[1,0]
	v_pk_add_f32 v[100:101], v[100:101], v[100:101] op_sel:[0,1] op_sel_hi:[1,0]
	v_mov_b32_e32 v99, v81
	v_mov_b32_e32 v101, v102
	v_pk_add_f32 v[98:99], v[98:99], v[100:101]
	v_mul_f32_e32 v100, v31, v31
	v_mul_f32_e32 v103, v16, v16
	v_pk_fma_f32 v[100:101], v[30:31], v[30:31], v[100:101] op_sel_hi:[1,1,0]
	v_mul_f32_e32 v102, v33, v33
	v_mul_f32_e32 v104, v17, v17
	v_mov_b32_e32 v101, v103
	v_pk_fma_f32 v[102:103], v[32:33], v[32:33], v[102:103] op_sel_hi:[1,1,0]
	v_and_b32_e32 v81, 64, v137
	v_mov_b32_e32 v103, v104
	v_pk_add_f32 v[100:101], v[100:101], v[102:103]
	v_add_u32_e32 v81, 64, v81
	v_xor_b32_e32 v102, 1, v137
	v_cmp_lt_i32_e32 vcc, v102, v81
	v_mov_b32_e32 v103, v84
	v_mov_b32_e32 v84, v87
	v_cndmask_b32_e32 v102, v137, v102, vcc
	v_lshlrev_b32_e32 v104, 2, v102
	v_mov_b32_e32 v102, v86
	v_pk_add_f32 v[84:85], v[102:103], v[84:85]
	ds_bpermute_b32 v87, v104, v85
	ds_bpermute_b32 v86, v104, v84
	v_xor_b32_e32 v102, 2, v137
	v_cmp_lt_i32_e32 vcc, v102, v81
	s_mov_b32 s10, 0x358637bd
	v_pk_add_f32 v[98:99], v[98:99], v[100:101]
	v_cndmask_b32_e32 v102, v137, v102, vcc
	v_lshlrev_b32_e32 v105, 2, v102
	s_waitcnt lgkmcnt(0)
; __device__ __forceinline__ unsigned pk2(float lo, float hi) { unsigned r; asm("v_cvt_pk_bf16_f32 %0, %1, %2" : "=v"(r) : "v"(lo), "v"(hi)); return r; }
; __device__ __forceinline__ void phase_rowwise(const Params& p, const float* xs32, const bf16_t* xs16, float* xd32, bf16_t* xd16, const bf16_t* y, const float* gpost, int modres,
;                                               bf16_t* hout, const float* gpre, int modh) {
;     ...
;             for (int o = 1; o < 64; o <<= 1)
; #pragma unroll
;                 for (int r = 0; r < RB; ++r) ss[r] += __shfl_xor(ss[r], o);
; #pragma unroll
;             for (int j = 0; j < 4; ++j) { const f32x4 sh = *(const f32x4*)(modb + modh + lane * 4 + 256 * j), scl = *(const f32x4*)(modb + modh + 1024 + lane * 4 + 256 * j), gp = *(const f32x4*)(gpre + lane * 4 + 256 * j);
;                 const f32x4 gs = gp * (scl + 1.f);
; #pragma unroll
;                 for (int r = 0; r < RB; ++r) { const float rstd = rsqrtf(ss[r] * (1.f / D) + EPS);
;                     u32x2 o; o.x = pk2(xv[r][j][0] * rstd * gs[0] + sh[0], xv[r][j][1] * rstd * gs[1] + sh[1]); o.y = pk2(xv[r][j][2] * rstd * gs[2] + sh[2], xv[r][j][3] * rstd * gs[3] + sh[3]);
;                     *(u32x2*)(hout + (row0 + r) * LDH + lane * 4 + 256 * j) = o; } }
	v_pk_add_f32 v[84:85], v[84:85], v[86:87]
	ds_bpermute_b32 v87, v105, v85
	ds_bpermute_b32 v86, v105, v84
	v_xor_b32_e32 v102, 4, v137
	v_cmp_lt_i32_e32 vcc, v102, v81
	v_mov_b64_e32 v[100:101], s[10:11]
	s_mov_b32 s10, 0x3a800000
	v_cndmask_b32_e32 v102, v137, v102, vcc
	v_lshlrev_b32_e32 v106, 2, v102
	s_waitcnt lgkmcnt(0)
	v_pk_add_f32 v[84:85], v[84:85], v[86:87]
	ds_bpermute_b32 v87, v106, v85
	ds_bpermute_b32 v86, v106, v84
	v_xor_b32_e32 v102, 8, v137
	v_cmp_lt_i32_e32 vcc, v102, v81
	s_waitcnt lgkmcnt(0)
	v_pk_add_f32 v[84:85], v[84:85], v[86:87]
	v_cndmask_b32_e32 v102, v137, v102, vcc
	v_lshlrev_b32_e32 v107, 2, v102
	ds_bpermute_b32 v87, v107, v85
	ds_bpermute_b32 v86, v107, v84
	v_xor_b32_e32 v102, 16, v137
	v_cmp_lt_i32_e32 vcc, v102, v81
	s_waitcnt lgkmcnt(0)
	v_pk_add_f32 v[84:85], v[84:85], v[86:87]
	v_cndmask_b32_e32 v102, v137, v102, vcc
	v_lshlrev_b32_e32 v108, 2, v102
	ds_bpermute_b32 v87, v108, v85
	ds_bpermute_b32 v86, v108, v84
	v_xor_b32_e32 v102, 32, v137
	v_cmp_lt_i32_e32 vcc, v102, v81
	s_waitcnt lgkmcnt(0)
	v_pk_add_f32 v[84:85], v[84:85], v[86:87]
	v_cndmask_b32_e32 v81, v137, v102, vcc
	v_lshlrev_b32_e32 v81, 2, v81
	ds_bpermute_b32 v103, v81, v85
	ds_bpermute_b32 v102, v81, v84
	s_waitcnt vmcnt(1)
	v_pk_add_f32 v[88:89], v[88:89], 1.0 op_sel_hi:[1,0]
	v_pk_add_f32 v[90:91], v[90:91], 1.0 op_sel_hi:[1,0]
	s_waitcnt vmcnt(0)
	v_pk_mul_f32 v[88:89], v[92:93], v[88:89]
	v_mov_b32_e32 v93, v96
	s_waitcnt lgkmcnt(0)
	v_pk_add_f32 v[84:85], v[84:85], v[102:103]
	v_mov_b32_e32 v96, v99
	v_pk_fma_f32 v[102:103], v[84:85], s[10:11], v[100:101] op_sel_hi:[1,0,0]
	v_pk_mul_f32 v[90:91], v[94:95], v[90:91]
	v_mul_f32_e32 v84, 0x4b800000, v103
	v_cmp_gt_f32_e32 vcc, s76, v103
	v_lshl_add_u64 v[86:87], v[82:83], 0, s[86:87]
	s_nop 0
	v_cndmask_b32_e32 v84, v103, v84, vcc
	v_rsq_f32_e32 v103, v84
	v_lshl_add_u64 v[84:85], v[78:79], 0, v[72:73]
	v_mul_f32_e32 v92, 0x45800000, v103
	v_cndmask_b32_e32 v103, v103, v92, vcc
	v_mov_b32_e32 v92, v98
	v_pk_add_f32 v[92:93], v[92:93], v[96:97]
	ds_bpermute_b32 v95, v104, v93
	ds_bpermute_b32 v94, v104, v92
	v_mul_f32_e32 v62, v62, v103
	v_mul_f32_e32 v63, v63, v103
	v_fma_f32 v62, v88, v62, v66
	v_fma_f32 v63, v89, v63, v67
	s_waitcnt lgkmcnt(0)
	v_pk_add_f32 v[92:93], v[92:93], v[94:95]
	ds_bpermute_b32 v95, v105, v93
	ds_bpermute_b32 v94, v105, v92
	v_cvt_pk_bf16_f32 v62, v62, v63
	v_mul_f32_e32 v63, v64, v103
	v_mul_f32_e32 v64, v65, v103
	v_fma_f32 v96, v91, v64, v69
	s_waitcnt lgkmcnt(0)
	v_pk_add_f32 v[64:65], v[92:93], v[94:95]
	ds_bpermute_b32 v93, v106, v65
	ds_bpermute_b32 v92, v106, v64
	v_mul_f32_e32 v94, 0x4b800000, v102
	v_cmp_gt_f32_e32 vcc, s76, v102
	v_fma_f32 v63, v90, v63, v68
	v_cvt_pk_bf16_f32 v63, v63, v96
	s_waitcnt lgkmcnt(0)
	v_pk_add_f32 v[64:65], v[64:65], v[92:93]
	v_cndmask_b32_e32 v94, v102, v94, vcc
	v_rsq_f32_e32 v94, v94
	ds_bpermute_b32 v93, v107, v65
	ds_bpermute_b32 v92, v107, v64
	global_store_dwordx2 v[84:85], v[62:63], off sc1
	v_mul_f32_e32 v62, 0x45800000, v94
	v_cndmask_b32_e32 v94, v94, v62, vcc
	v_mul_f32_e32 v50, v50, v94
	s_waitcnt lgkmcnt(0)
	v_pk_add_f32 v[62:63], v[64:65], v[92:93]
	ds_bpermute_b32 v65, v108, v63
	ds_bpermute_b32 v64, v108, v62
	v_fma_f32 v92, v88, v50, v66
	v_mul_f32_e32 v50, v51, v94
	v_fma_f32 v93, v89, v50, v67
	v_mul_f32_e32 v52, v52, v94
	s_waitcnt lgkmcnt(0)
	v_pk_add_f32 v[50:51], v[62:63], v[64:65]
	ds_bpermute_b32 v63, v81, v51
	ds_bpermute_b32 v62, v81, v50
	v_fma_f32 v52, v90, v52, v68
	v_mul_f32_e32 v53, v53, v94
	v_cvt_pk_bf16_f32 v64, v92, v93
	v_fma_f32 v53, v91, v53, v69
	s_waitcnt lgkmcnt(0)
	v_pk_add_f32 v[50:51], v[50:51], v[62:63]
	v_cvt_pk_bf16_f32 v65, v52, v53
	global_store_dwordx2 v[84:85], v[64:65], off offset:2176 sc1
	v_pk_fma_f32 v[50:51], v[50:51], s[10:11], v[100:101] op_sel_hi:[1,0,0]
	v_mul_f32_e32 v34, v34, v103
	v_mul_f32_e32 v62, 0x4b800000, v51
	v_cmp_gt_f32_e32 vcc, s76, v51
	v_mul_f32_e32 v35, v35, v103
	v_mul_f32_e32 v18, v18, v103
	v_cndmask_b32_e32 v51, v51, v62, vcc
	v_rsq_f32_e32 v51, v51
	v_add_co_u32_e64 v62, s[0:1], s0, v84
	v_mul_f32_e32 v19, v19, v103
	v_mul_f32_e32 v52, 0x45800000, v51
	v_cndmask_b32_e32 v64, v51, v52, vcc
	v_mul_f32_e32 v51, v58, v64
	v_mul_f32_e32 v52, v59, v64
	v_fma_f32 v51, v88, v51, v66
	v_fma_f32 v52, v89, v52, v67
	v_cvt_pk_bf16_f32 v52, v51, v52
	v_mul_f32_e32 v51, v60, v64
	v_mul_f32_e32 v53, v61, v64
	v_fma_f32 v51, v90, v51, v68
	v_fma_f32 v53, v91, v53, v69
	v_cvt_pk_bf16_f32 v53, v51, v53
	v_mul_f32_e32 v51, 0x4b800000, v50
	v_cmp_gt_f32_e32 vcc, s76, v50
	v_addc_co_u32_e64 v63, s[0:1], 0, v85, s[0:1]
	s_nop 0
	v_cndmask_b32_e32 v50, v50, v51, vcc
	v_rsq_f32_e32 v50, v50
	global_store_dwordx2 v[62:63], v[52:53], off offset:256 sc1
	v_mul_f32_e32 v2, v2, v103
	v_mul_f32_e32 v3, v3, v103
	v_mul_f32_e32 v51, 0x45800000, v50
	v_cndmask_b32_e32 v65, v50, v51, vcc
	v_mul_f32_e32 v50, v54, v65
	v_mul_f32_e32 v51, v55, v65
	v_fma_f32 v50, v88, v50, v66
	v_fma_f32 v51, v89, v51, v67
	v_cvt_pk_bf16_f32 v50, v50, v51
	v_mul_f32_e32 v51, v56, v65
	v_fma_f32 v51, v90, v51, v68
	v_mul_f32_e32 v52, v57, v65
	v_fmac_f32_e32 v69, v91, v52
	v_cvt_pk_bf16_f32 v51, v51, v69
	global_store_dwordx2 v[62:63], v[50:51], off offset:2432 sc1
	global_load_dwordx4 v[50:53], v[86:87], off offset:1024
	s_nop 0
	global_load_dwordx4 v[54:57], v[70:71], off offset:1024
	global_load_dwordx4 v[58:61], v[82:83], off offset:1024
	s_waitcnt vmcnt(2)
; __device__ __forceinline__ unsigned pk2(float lo, float hi) { unsigned r; asm("v_cvt_pk_bf16_f32 %0, %1, %2" : "=v"(r) : "v"(lo), "v"(hi)); return r; }
; __device__ __forceinline__ void phase_rowwise(const Params& p, const float* xs32, const bf16_t* xs16, float* xd32, bf16_t* xd16, const bf16_t* y, const float* gpost, int modres,
;                                               bf16_t* hout, const float* gpre, int modh) {
;     ...
;             for (int j = 0; j < 4; ++j) { const f32x4 sh = *(const f32x4*)(modb + modh + lane * 4 + 256 * j), scl = *(const f32x4*)(modb + modh + 1024 + lane * 4 + 256 * j), gp = *(const f32x4*)(gpre + lane * 4 + 256 * j);
;                 const f32x4 gs = gp * (scl + 1.f);
; #pragma unroll
;                 for (int r = 0; r < RB; ++r) { const float rstd = rsqrtf(ss[r] * (1.f / D) + EPS);
;                     u32x2 o; o.x = pk2(xv[r][j][0] * rstd * gs[0] + sh[0], xv[r][j][1] * rstd * gs[1] + sh[1]); o.y = pk2(xv[r][j][2] * rstd * gs[2] + sh[2], xv[r][j][3] * rstd * gs[3] + sh[3]);
;                     *(u32x2*)(hout + (row0 + r) * LDH + lane * 4 + 256 * j) = o; } }
	v_pk_add_f32 v[50:51], v[50:51], 1.0 op_sel_hi:[1,0]
	s_waitcnt vmcnt(1)
	v_pk_mul_f32 v[50:51], v[54:55], v[50:51]
	v_pk_add_f32 v[52:53], v[52:53], 1.0 op_sel_hi:[1,0]
	s_waitcnt vmcnt(0)
	v_fma_f32 v34, v34, v50, v58
	v_fma_f32 v35, v35, v51, v59
	v_pk_mul_f32 v[52:53], v[56:57], v[52:53]
	v_cvt_pk_bf16_f32 v34, v34, v35
	v_mul_f32_e32 v35, v36, v103
	v_fma_f32 v35, v35, v52, v60
	v_mul_f32_e32 v36, v37, v103
	v_fma_f32 v36, v36, v53, v61
	v_cvt_pk_bf16_f32 v35, v35, v36
	global_store_dwordx2 v[84:85], v[34:35], off offset:512 sc1
	v_mul_f32_e32 v34, v38, v94
	v_mul_f32_e32 v35, v39, v94
	v_fma_f32 v34, v34, v50, v58
	v_fma_f32 v35, v35, v51, v59
	v_cvt_pk_bf16_f32 v34, v34, v35
	v_mul_f32_e32 v35, v40, v94
	v_fma_f32 v35, v35, v52, v60
	v_mul_f32_e32 v36, v41, v94
	v_fma_f32 v36, v36, v53, v61
	v_cvt_pk_bf16_f32 v35, v35, v36
	global_store_dwordx2 v[84:85], v[34:35], off offset:2688 sc1
	v_mul_f32_e32 v34, v42, v64
	v_mul_f32_e32 v35, v43, v64
	v_fma_f32 v34, v34, v50, v58
	v_fma_f32 v35, v35, v51, v59
	v_cvt_pk_bf16_f32 v34, v34, v35
	v_mul_f32_e32 v35, v44, v64
	v_fma_f32 v35, v35, v52, v60
	v_mul_f32_e32 v36, v45, v64
	v_fma_f32 v36, v36, v53, v61
	v_cvt_pk_bf16_f32 v35, v35, v36
	global_store_dwordx2 v[62:63], v[34:35], off offset:768 sc1
	v_mul_f32_e32 v34, v46, v65
	v_mul_f32_e32 v35, v47, v65
	v_fma_f32 v34, v34, v50, v58
	v_fma_f32 v35, v35, v51, v59
	v_cvt_pk_bf16_f32 v34, v34, v35
	v_mul_f32_e32 v35, v48, v65
	v_fma_f32 v35, v35, v52, v60
	v_mul_f32_e32 v36, v49, v65
	v_fmac_f32_e32 v61, v36, v53
	v_cvt_pk_bf16_f32 v35, v35, v61
	global_store_dwordx2 v[62:63], v[34:35], off offset:2944 sc1
	global_load_dwordx4 v[34:37], v[86:87], off offset:2048
	s_nop 0
	global_load_dwordx4 v[38:41], v[70:71], off offset:2048
	global_load_dwordx4 v[42:45], v[82:83], off offset:2048
	s_waitcnt vmcnt(2)
	v_pk_add_f32 v[34:35], v[34:35], 1.0 op_sel_hi:[1,0]
	s_waitcnt vmcnt(1)
	v_pk_mul_f32 v[34:35], v[38:39], v[34:35]
	v_pk_add_f32 v[36:37], v[36:37], 1.0 op_sel_hi:[1,0]
	s_waitcnt vmcnt(0)
	v_fma_f32 v18, v18, v34, v42
	v_fma_f32 v19, v19, v35, v43
	v_pk_mul_f32 v[36:37], v[40:41], v[36:37]
	v_cvt_pk_bf16_f32 v18, v18, v19
	v_mul_f32_e32 v19, v20, v103
	v_fma_f32 v19, v19, v36, v44
	v_mul_f32_e32 v20, v21, v103
	v_fma_f32 v20, v20, v37, v45
	v_cvt_pk_bf16_f32 v19, v19, v20
	global_store_dwordx2 v[84:85], v[18:19], off offset:1024 sc1
	v_mul_f32_e32 v18, v22, v94
	v_mul_f32_e32 v19, v23, v94
	v_fma_f32 v18, v18, v34, v42
	v_fma_f32 v19, v19, v35, v43
	v_cvt_pk_bf16_f32 v18, v18, v19
	v_mul_f32_e32 v19, v24, v94
	v_fma_f32 v19, v19, v36, v44
	v_mul_f32_e32 v20, v25, v94
	v_fma_f32 v20, v20, v37, v45
	v_cvt_pk_bf16_f32 v19, v19, v20
	global_store_dwordx2 v[84:85], v[18:19], off offset:3200 sc1
	v_mul_f32_e32 v18, v26, v64
	v_mul_f32_e32 v19, v27, v64
	v_fma_f32 v18, v18, v34, v42
	v_fma_f32 v19, v19, v35, v43
	v_cvt_pk_bf16_f32 v18, v18, v19
	v_mul_f32_e32 v19, v28, v64
	v_fma_f32 v19, v19, v36, v44
	v_mul_f32_e32 v20, v29, v64
	v_fma_f32 v20, v20, v37, v45
	v_cvt_pk_bf16_f32 v19, v19, v20
	global_store_dwordx2 v[62:63], v[18:19], off offset:1280 sc1
	v_mul_f32_e32 v18, v30, v65
	v_mul_f32_e32 v19, v31, v65
	v_fma_f32 v18, v18, v34, v42
	v_fma_f32 v19, v19, v35, v43
	v_cvt_pk_bf16_f32 v18, v18, v19
	v_mul_f32_e32 v19, v32, v65
	v_fma_f32 v19, v19, v36, v44
	v_mul_f32_e32 v20, v33, v65
	v_fmac_f32_e32 v45, v20, v37
	v_cvt_pk_bf16_f32 v19, v19, v45
	global_store_dwordx2 v[62:63], v[18:19], off offset:3456 sc1
	global_load_dwordx4 v[18:21], v[86:87], off offset:3072
	s_nop 0
	global_load_dwordx4 v[22:25], v[70:71], off offset:3072
	global_load_dwordx4 v[26:29], v[82:83], off offset:3072
	s_waitcnt vmcnt(2)
	v_pk_add_f32 v[18:19], v[18:19], 1.0 op_sel_hi:[1,0]
	s_waitcnt vmcnt(1)
	v_pk_mul_f32 v[18:19], v[22:23], v[18:19]
	v_pk_add_f32 v[20:21], v[20:21], 1.0 op_sel_hi:[1,0]
	s_waitcnt vmcnt(0)
	v_fma_f32 v2, v2, v18, v26
	v_fma_f32 v3, v3, v19, v27
	v_pk_mul_f32 v[20:21], v[24:25], v[20:21]
	v_cvt_pk_bf16_f32 v2, v2, v3
	v_mul_f32_e32 v3, v4, v103
	v_fma_f32 v3, v3, v20, v28
	v_mul_f32_e32 v4, v5, v103
	v_fma_f32 v4, v4, v21, v29
	v_cvt_pk_bf16_f32 v3, v3, v4
	global_store_dwordx2 v[84:85], v[2:3], off offset:1536 sc1
	v_mul_f32_e32 v2, v6, v94
	v_mul_f32_e32 v3, v7, v94
	v_fma_f32 v2, v2, v18, v26
	v_fma_f32 v3, v3, v19, v27
	v_cvt_pk_bf16_f32 v2, v2, v3
	v_mul_f32_e32 v3, v8, v94
	v_fma_f32 v3, v3, v20, v28
	v_mul_f32_e32 v4, v9, v94
	v_fma_f32 v4, v4, v21, v29
	v_cvt_pk_bf16_f32 v3, v3, v4
	global_store_dwordx2 v[84:85], v[2:3], off offset:3712 sc1
	v_mul_f32_e32 v2, v10, v64
	v_mul_f32_e32 v3, v11, v64
	v_fma_f32 v2, v2, v18, v26
	v_fma_f32 v3, v3, v19, v27
	v_cvt_pk_bf16_f32 v2, v2, v3
	v_mul_f32_e32 v3, v12, v64
	v_fma_f32 v3, v3, v20, v28
	v_mul_f32_e32 v4, v13, v64
	v_fma_f32 v4, v4, v21, v29
	v_cvt_pk_bf16_f32 v3, v3, v4
	global_store_dwordx2 v[62:63], v[2:3], off offset:1792 sc1
	v_mul_f32_e32 v2, v14, v65
	v_mul_f32_e32 v3, v15, v65
	v_fma_f32 v2, v2, v18, v26
	v_fma_f32 v3, v3, v19, v27
	v_cvt_pk_bf16_f32 v2, v2, v3
	v_mul_f32_e32 v3, v16, v65
	v_fma_f32 v3, v3, v20, v28
	v_mul_f32_e32 v4, v17, v65
	v_fmac_f32_e32 v29, v4, v21
	v_cvt_pk_bf16_f32 v3, v3, v29
	global_store_dwordx2 v[62:63], v[2:3], off offset:3968 sc1
	s_branch .LBB0_257

; __device__ __forceinline__ u32x4 pack8(const float (&o)[8]) { u32x4 r; r.x = pk2(o[0], o[1]); r.y = pk2(o[2], o[3]); r.z = pk2(o[4], o[5]); r.w = pk2(o[6], o[7]); return r; }
; __device__ __forceinline__ float silu_f(float v) { return v * __builtin_amdgcn_rcpf(1.f + __expf(-v)); }
; __device__ __forceinline__ void phase_ssd(const Params& p, uchar* sm, int j, bf16_t* zx, const float* dtraw, float* ssqb) {
;     ...
;             __syncthreads();
; #pragma unroll
;             for (int m = 0; m < 4; ++m)
; #pragma unroll
;                 for (int r = 0; r < 4; ++r) *(float*)(sm + (m * 16 + quad * 4 + r) * RS_Y + (chl + l15) * 4) = yacc[m][r];
;             __syncthreads();
;             {
;                 float zf[8], o[8], xf[8];
;                 const f32x4 y0 = *(const f32x4*)(sm + (2 * lp) * RS_Y + c8 * 32), y1 = *(const f32x4*)(sm + (2 * lp) * RS_Y + c8 * 32 + 16);
;                 unpack8(z0, zf); unpack8(xp0, xf);
; #pragma unroll
;                 for (int i = 0; i < 4; ++i) { o[i] = (y0[i] + dskip * xf[i]) * silu_f(zf[i]); o[4 + i] = (y1[i] + dskip * xf[4 + i]) * silu_f(zf[4 + i]); }
;                 *(u32x4*)(zc + colx + toff) = pack8(o);
;                 float q0 = 0.f;
; #pragma unroll
;                 for (int i = 0; i < 8; ++i) q0 += o[i] * o[i];
;                 const f32x4 y2 = *(const f32x4*)(sm + (2 * lp + 1) * RS_Y + c8 * 32), y3 = *(const f32x4*)(sm + (2 * lp + 1) * RS_Y + c8 * 32 + 16);
;                 unpack8(z1, zf); unpack8(xp1, xf);
; #pragma unroll
;                 for (int i = 0; i < 4; ++i) { o[i] = (y2[i] + dskip * xf[i]) * silu_f(zf[i]); o[4 + i] = (y3[i] + dskip * xf[4 + i]) * silu_f(zf[4 + i]); }
.LBB0_479:
	v_add_u32_e32 v104, 0x400, v224
	s_barrier
	ds_write2_b32 v104, v110, v111 offset0:8 offset1:140
	v_add_u32_e32 v104, 0x2000, v224
	ds_write2_b32 v104, v112, v113 offset0:64 offset1:196
	v_add_u32_e32 v104, 0x2400, v224
	ds_write2_b32 v104, v114, v115 offset0:72 offset1:204
	v_add_u32_e32 v104, 0x4200, v224
	ds_write2_b32 v104, v120, v121 offset1:132
	v_add_u32_e32 v104, 0x4600, v224
	ds_write2_b32 v104, v122, v123 offset0:8 offset1:140
	v_add_u32_e32 v104, 0x6200, v224
	ds_write2_b32 v104, v116, v117 offset0:64 offset1:196
	v_add_u32_e32 v104, 0x6600, v224
	s_waitcnt vmcnt(11)
	v_lshlrev_b32_e32 v112, 16, v100
	ds_write2_b32 v104, v118, v119 offset0:72 offset1:204
	v_mul_f32_e32 v104, 0xbfb8aa3b, v112
	v_exp_f32_e32 v114, v104
	ds_write2_b32 v224, v108, v109 offset1:132
	s_waitcnt lgkmcnt(0)
	s_barrier
	ds_read_b128 v[104:107], v225
	ds_read_b128 v[108:111], v225 offset:16
	v_add_f32_e32 v114, 1.0, v114
	v_rcp_f32_e32 v170, v114
	v_lshlrev_b32_e32 v114, 16, v102
	v_lshlrev_b32_e32 v113, 16, v235
	v_mul_f32_e32 v115, 0xbfb8aa3b, v114
	v_exp_f32_e32 v115, v115
	v_pk_mul_f32 v[112:113], v[170:171], v[112:113]
	s_waitcnt lgkmcnt(1)
	v_add_f32_e32 v104, v113, v104
	v_mul_f32_e32 v116, v112, v104
	v_and_b32_e32 v112, 0xffff0000, v100
	v_mul_f32_e32 v100, 0xbfb8aa3b, v112
	v_add_f32_e32 v104, 1.0, v115
	v_exp_f32_e32 v100, v100
	v_rcp_f32_e32 v170, v104
	v_lshlrev_b32_e32 v115, 16, v236
	v_and_b32_e32 v104, 0xffff0000, v102
	v_add_f32_e32 v100, 1.0, v100
	v_pk_mul_f32 v[114:115], v[170:171], v[114:115]
	v_rcp_f32_e32 v170, v100
	v_mul_f32_e32 v100, 0xbfb8aa3b, v104
	v_exp_f32_e32 v100, v100
	v_and_b32_e32 v113, 0xffff0000, v235
	s_waitcnt lgkmcnt(0)
	v_add_f32_e32 v108, v115, v108
	v_pk_mul_f32 v[112:113], v[170:171], v[112:113]
	v_add_f32_e32 v100, 1.0, v100
	v_mul_f32_e32 v114, v114, v108
	v_rcp_f32_e32 v170, v100
	v_add_f32_e32 v100, v113, v105
	v_lshlrev_b32_e32 v108, 16, v101
	v_mul_f32_e32 v112, v112, v100
	v_mul_f32_e32 v100, 0xbfb8aa3b, v108
	v_exp_f32_e32 v100, v100
	v_and_b32_e32 v105, 0xffff0000, v236
	v_pk_mul_f32 v[104:105], v[170:171], v[104:105]
	v_mul_f32_e32 v120, v112, v112
	v_add_f32_e32 v100, 1.0, v100
	v_add_f32_e32 v102, v105, v109
	v_rcp_f32_e32 v170, v100
	v_lshlrev_b32_e32 v100, 16, v103
	v_mul_f32_e32 v113, v104, v102
	v_mul_f32_e32 v102, 0xbfb8aa3b, v100
	v_exp_f32_e32 v102, v102
	v_lshlrev_b32_e32 v109, 16, v233
	v_pk_mul_f32 v[104:105], v[170:171], v[108:109]
	s_waitcnt vmcnt(10)
	v_lshlrev_b32_e32 v108, 16, v96
	v_add_f32_e32 v102, 1.0, v102
	v_rcp_f32_e32 v170, v102
	v_and_b32_e32 v102, 0xffff0000, v101
	v_add_f32_e32 v105, v105, v106
	v_mul_f32_e32 v101, 0xbfb8aa3b, v102
	v_mul_f32_e32 v115, v104, v105
	v_exp_f32_e32 v104, v101
	v_lshlrev_b32_e32 v101, 16, v234
	v_pk_mul_f32 v[100:101], v[170:171], v[100:101]
	v_lshlrev_b32_e32 v109, 16, v231
	v_add_f32_e32 v104, 1.0, v104
	v_rcp_f32_e32 v170, v104
	v_and_b32_e32 v104, 0xffff0000, v103
	v_mul_f32_e32 v103, 0xbfb8aa3b, v104
	ds_read_b128 v[124:127], v226
	v_exp_f32_e32 v105, v103
	v_add_f32_e32 v101, v101, v110
	v_and_b32_e32 v103, 0xffff0000, v233
	v_mul_f32_e32 v117, v100, v101
	v_pk_mul_f32 v[100:101], v[170:171], v[102:103]
	v_add_f32_e32 v102, 1.0, v105
	v_rcp_f32_e32 v170, v102
	v_add_f32_e32 v101, v101, v107
	v_and_b32_e32 v105, 0xffff0000, v234
	v_mul_f32_e32 v118, v100, v101
	v_pk_mul_f32 v[100:101], v[170:171], v[104:105]
	v_fmac_f32_e32 v120, v116, v116
	v_add_f32_e32 v101, v101, v111
	v_mul_f32_e32 v119, v100, v101
	v_mul_f32_e32 v100, 0xbfb8aa3b, v108
	v_exp_f32_e32 v110, v100
	ds_read_b128 v[104:107], v226 offset:16
	v_fmac_f32_e32 v120, v115, v115
	v_fmac_f32_e32 v120, v118, v118
	v_add_f32_e32 v110, 1.0, v110
	v_rcp_f32_e32 v170, v110
	v_lshlrev_b32_e32 v110, 16, v98
	v_mul_f32_e32 v111, 0xbfb8aa3b, v110
	v_exp_f32_e32 v111, v111
	v_pk_mul_f32 v[108:109], v[170:171], v[108:109]
	v_fmac_f32_e32 v120, v114, v114
	s_waitcnt lgkmcnt(1)
	v_add_f32_e32 v124, v109, v124
	v_mul_f32_e32 v121, v108, v124
	v_and_b32_e32 v108, 0xffff0000, v96
	v_mul_f32_e32 v96, 0xbfb8aa3b, v108
	v_add_f32_e32 v100, 1.0, v111
	v_exp_f32_e32 v96, v96
	v_rcp_f32_e32 v170, v100
	v_lshlrev_b32_e32 v111, 16, v232
	v_and_b32_e32 v100, 0xffff0000, v98
	v_add_f32_e32 v96, 1.0, v96
	v_pk_mul_f32 v[110:111], v[170:171], v[110:111]
	v_rcp_f32_e32 v170, v96
	v_mul_f32_e32 v96, 0xbfb8aa3b, v100
	v_exp_f32_e32 v96, v96
	v_and_b32_e32 v109, 0xffff0000, v231
	s_waitcnt lgkmcnt(0)
; __device__ __forceinline__ u32x4 pack8(const float (&o)[8]) { u32x4 r; r.x = pk2(o[0], o[1]); r.y = pk2(o[2], o[3]); r.z = pk2(o[4], o[5]); r.w = pk2(o[6], o[7]); return r; }
; __device__ __forceinline__ float silu_f(float v) { return v * __builtin_amdgcn_rcpf(1.f + __expf(-v)); }
; __device__ __forceinline__ void phase_ssd(const Params& p, uchar* sm, int j, bf16_t* zx, const float* dtraw, float* ssqb) {
;     ...
;             {
;                 float zf[8], o[8], xf[8];
;                 const f32x4 y0 = *(const f32x4*)(sm + (2 * lp) * RS_Y + c8 * 32), y1 = *(const f32x4*)(sm + (2 * lp) * RS_Y + c8 * 32 + 16);
;                 unpack8(z0, zf); unpack8(xp0, xf);
; #pragma unroll
;                 for (int i = 0; i < 4; ++i) { o[i] = (y0[i] + dskip * xf[i]) * silu_f(zf[i]); o[4 + i] = (y1[i] + dskip * xf[4 + i]) * silu_f(zf[4 + i]); }
;                 *(u32x4*)(zc + colx + toff) = pack8(o);
;                 float q0 = 0.f;
; #pragma unroll
;                 for (int i = 0; i < 8; ++i) q0 += o[i] * o[i];
;                 const f32x4 y2 = *(const f32x4*)(sm + (2 * lp + 1) * RS_Y + c8 * 32), y3 = *(const f32x4*)(sm + (2 * lp + 1) * RS_Y + c8 * 32 + 16);
;                 unpack8(z1, zf); unpack8(xp1, xf);
; #pragma unroll
;                 for (int i = 0; i < 4; ++i) { o[i] = (y2[i] + dskip * xf[i]) * silu_f(zf[i]); o[4 + i] = (y3[i] + dskip * xf[4 + i]) * silu_f(zf[4 + i]); }
;                 *(u32x4*)(zc + colx + LDZ + toff) = pack8(o);
;                 float q1 = 0.f;
; #pragma unroll
;                 for (int i = 0; i < 8; ++i) q1 += o[i] * o[i];
; #pragma unroll
;                 for (int sft = 1; sft < 16; sft <<= 1) { q0 += __shfl_xor(q0, sft); q1 += __shfl_xor(q1, sft); }
;                 if (c8 == 0) { float* sq = ssqb + (size_t)(zrow0 + 2 * lp) * 16 + g * 2 + hp; sq[0] = q0; sq[16] = q1; }
	v_add_f32_e32 v104, v111, v104
	v_pk_mul_f32 v[108:109], v[170:171], v[108:109]
	v_add_f32_e32 v96, 1.0, v96
	v_mul_f32_e32 v110, v110, v104
	v_rcp_f32_e32 v170, v96
	v_add_f32_e32 v96, v109, v125
	v_lshlrev_b32_e32 v104, 16, v97
	v_mul_f32_e32 v108, v108, v96
	v_mul_f32_e32 v96, 0xbfb8aa3b, v104
	v_exp_f32_e32 v96, v96
	v_and_b32_e32 v101, 0xffff0000, v232
	v_pk_mul_f32 v[100:101], v[170:171], v[100:101]
	v_fmac_f32_e32 v120, v113, v113
	v_add_f32_e32 v96, 1.0, v96
	v_add_f32_e32 v98, v101, v105
	v_rcp_f32_e32 v170, v96
	v_lshlrev_b32_e32 v96, 16, v99
	v_mul_f32_e32 v109, v100, v98
	v_mul_f32_e32 v98, 0xbfb8aa3b, v96
	v_exp_f32_e32 v98, v98
	v_lshlrev_b32_e32 v105, 16, v229
	v_pk_mul_f32 v[100:101], v[170:171], v[104:105]
	v_fmac_f32_e32 v120, v117, v117
	v_add_f32_e32 v98, 1.0, v98
	v_rcp_f32_e32 v170, v98
	v_and_b32_e32 v98, 0xffff0000, v97
	v_add_f32_e32 v101, v101, v126
	v_mul_f32_e32 v97, 0xbfb8aa3b, v98
	v_mul_f32_e32 v102, v100, v101
	v_exp_f32_e32 v100, v97
	v_lshlrev_b32_e32 v97, 16, v230
	v_pk_mul_f32 v[96:97], v[170:171], v[96:97]
	v_fmac_f32_e32 v120, v119, v119
	v_add_f32_e32 v100, 1.0, v100
	v_rcp_f32_e32 v170, v100
	v_and_b32_e32 v100, 0xffff0000, v99
	v_mul_f32_e32 v99, 0xbfb8aa3b, v100
	v_exp_f32_e32 v101, v99
	v_add_f32_e32 v97, v97, v106
	v_and_b32_e32 v99, 0xffff0000, v229
	v_mul_f32_e32 v104, v96, v97
	v_pk_mul_f32 v[96:97], v[170:171], v[98:99]
	v_add_f32_e32 v98, 1.0, v101
	v_rcp_f32_e32 v170, v98
	v_add_f32_e32 v97, v97, v127
	v_and_b32_e32 v101, 0xffff0000, v230
	v_mul_f32_e32 v103, v96, v97
	v_pk_mul_f32 v[96:97], v[170:171], v[100:101]
	s_nop 0
	v_add_f32_e32 v97, v97, v107
	v_mul_f32_e32 v105, v96, v97
	v_mul_f32_e32 v96, v108, v108
	v_fmac_f32_e32 v96, v121, v121
	v_fmac_f32_e32 v96, v102, v102
	v_fmac_f32_e32 v96, v103, v103
	v_and_b32_e32 v97, 64, v137
	v_fmac_f32_e32 v96, v110, v110
	v_add_u32_e32 v101, 64, v97
	v_xor_b32_e32 v97, 1, v137
	v_fmac_f32_e32 v96, v109, v109
	v_cmp_lt_i32_e32 vcc, v97, v101
	v_fmac_f32_e32 v96, v104, v104
	v_fmac_f32_e32 v96, v105, v105
	v_cndmask_b32_e32 v97, v137, v97, vcc
	v_lshlrev_b32_e32 v97, 2, v97
	ds_bpermute_b32 v98, v97, v120
	ds_bpermute_b32 v97, v97, v96
	s_waitcnt lgkmcnt(0)
	v_add_f32_e32 v99, v120, v98
	v_add_f32_e32 v100, v96, v97
	v_xor_b32_e32 v96, 2, v137
	v_cmp_lt_i32_e32 vcc, v96, v101
	v_cvt_pk_bf16_f32 v98, v114, v113
	v_cvt_pk_bf16_f32 v97, v115, v118
	s_nop 1
	v_cndmask_b32_e32 v96, v137, v96, vcc
	v_lshlrev_b32_e32 v96, 2, v96
	ds_bpermute_b32 v106, v96, v99
	ds_bpermute_b32 v107, v96, v100
	v_cvt_pk_bf16_f32 v96, v116, v112
	s_waitcnt lgkmcnt(1)
	v_add_f32_e32 v106, v99, v106
	v_xor_b32_e32 v99, 4, v137
	v_cmp_lt_i32_e32 vcc, v99, v101
	s_waitcnt lgkmcnt(0)
	v_add_f32_e32 v107, v100, v107
	v_cvt_pk_bf16_f32 v100, v121, v108
	v_cndmask_b32_e32 v99, v137, v99, vcc
	v_lshlrev_b32_e32 v99, 2, v99
	ds_bpermute_b32 v111, v99, v106
	ds_bpermute_b32 v112, v99, v107
	v_cvt_pk_bf16_f32 v99, v117, v119
	global_store_dwordx4 v[180:181], v[96:99], off sc1
	s_nop 1
	v_xor_b32_e32 v98, 8, v137
	v_cmp_lt_i32_e32 vcc, v98, v101
	s_waitcnt lgkmcnt(0)
	v_add_f32_e32 v96, v106, v111
	v_add_f32_e32 v97, v107, v112
	v_cndmask_b32_e32 v98, v137, v98, vcc
	v_lshlrev_b32_e32 v99, 2, v98
	ds_bpermute_b32 v98, v99, v96
	ds_bpermute_b32 v99, v99, v97
	v_cvt_pk_bf16_f32 v101, v102, v103
	v_cvt_pk_bf16_f32 v102, v110, v109
	v_cvt_pk_bf16_f32 v103, v104, v105
	global_store_dwordx4 v[178:179], v[100:103], off sc1
	s_and_saveexec_b64 s[0:1], s[24:25]
	s_cbranch_execz .LBB0_465
	v_readlane_b32 s60, v254, 0
	v_readlane_b32 s66, v254, 6
	v_readlane_b32 s67, v254, 7
	s_waitcnt lgkmcnt(0)
	v_add_f32_e32 v99, v97, v99
	v_add_f32_e32 v98, v96, v98
	v_lshl_add_u64 v[96:97], s[66:67], 0, v[172:173]
	v_add_co_u32_e32 v96, vcc, 0x1ec1c000, v96
	v_readlane_b32 s61, v254, 1
	s_nop 0
	v_addc_co_u32_e32 v97, vcc, 0, v97, vcc
	v_readlane_b32 s62, v254, 2
	v_readlane_b32 s63, v254, 3
	v_readlane_b32 s64, v254, 4
	v_readlane_b32 s65, v254, 5
	global_store_dword v[96:97], v98, off
	global_store_dword v[96:97], v99, off offset:64
	s_branch .LBB0_465

; __device__ __forceinline__ u32x4 pack8(const float (&o)[8]) { u32x4 r; r.x = pk2(o[0], o[1]); r.y = pk2(o[2], o[3]); r.z = pk2(o[4], o[5]); r.w = pk2(o[6], o[7]); return r; }
; __device__ __forceinline__ void phase_convA(const Params& p, const bf16_t* bcv  , bf16_t* tout, const float* cw  ) {
;     ...
;         u32x4 bq[4], cq[4];
; #pragma unroll
;         for (int q = 0; q < 4; ++q) { const bf16_t* rp = bcv + (r0 + q) * 2048 + c8 * 8; bq[q] = *(const u32x4*)rp; cq[q] = *(const u32x4*)(rp + 1024); }
; #pragma unroll
;         for (int bt = 0; bt < 4; ++bt) {
;             u32x4 bn[4], cn[4];
;             if (bt < 3) {
; #pragma unroll
;                 for (int q = 0; q < 4; ++q) { const bf16_t* rp = bcv + (r0 + (bt + 1) * 4 + q) * 2048 + c8 * 8; bn[q] = *(const u32x4*)rp; cn[q] = *(const u32x4*)(rp + 1024); }
;             }
; #pragma unroll
;             for (int q = 0; q < 4; ++q) {
;                 float bb[8], cv[8], o[8];
;                 unpack8(bq[q], bb); unpack8(cq[q], cv);
; #pragma unroll
;                 for (int i = 0; i < 8; ++i) { o[i] = bb[i] * (w0[i] * cvm2[i] + w1[i] * cvm1[i] + w2[i] * cv[i]); cvm2[i] = cvm1[i]; cvm1[i] = cv[i]; }
;                 *(u32x4*)(tout + (r0 + bt * 4 + q) * LDH + c8 * 8) = pack8(o);
;             }
;             if (bt < 3) {
; #pragma unroll
;                 for (int q = 0; q < 4; ++q) { bq[q] = bn[q]; cq[q] = cn[q]; }
;             }
;         }
.LBB0_747:
	s_or_b64 exec, exec, s[6:7]
	v_lshl_add_u64 v[128:129], v[96:97], 0, v[26:27]
	v_lshlrev_b64 v[84:85], 4, v[28:29]
	global_load_dwordx4 v[124:127], v[128:129], off
	global_load_dwordx4 v[50:53], v[128:129], off offset:2048
	v_or_b32_e32 v84, 1, v84
	v_lshlrev_b64 v[30:31], 12, v[84:85]
	v_lshl_add_u64 v[30:31], v[96:97], 0, v[30:31]
	global_load_dwordx4 v[130:133], v[30:31], off
	global_load_dwordx4 v[54:57], v[30:31], off offset:2048
	v_or_b32_e32 v30, 0x2000, v26
	v_mov_b32_e32 v31, v27
	s_mov_b32 s6, 0x8800
	s_movk_i32 s9, 0x4000
	v_mad_i64_i32 v[102:103], s[6:7], v28, s6, v[98:99]
	v_lshl_add_u64 v[28:29], v[96:97], 0, v[30:31]
	v_add_co_u32_e32 v30, vcc, s9, v128
	s_movk_i32 s8, 0x5000
	s_nop 0
	v_addc_co_u32_e32 v31, vcc, 0, v129, vcc
	v_add_co_u32_e32 v32, vcc, s8, v128
	s_movk_i32 s10, 0x6000
	s_nop 0
	v_addc_co_u32_e32 v33, vcc, 0, v129, vcc
	v_add_co_u32_e32 v42, vcc, s10, v128
	v_or_b32_e32 v26, 0x3000, v26
	s_nop 0
	v_addc_co_u32_e32 v43, vcc, 0, v129, vcc
	s_movk_i32 s11, 0x7000
	v_lshl_add_u64 v[26:27], v[96:97], 0, v[26:27]
	v_add_co_u32_e32 v134, vcc, s11, v128
	s_waitcnt vmcnt(8)
	v_mov_b32_e32 v118, v14
	v_addc_co_u32_e32 v135, vcc, 0, v129, vcc
	global_load_dwordx4 v[156:159], v[28:29], off
	global_load_dwordx4 v[34:37], v[28:29], off offset:2048
	global_load_dwordx4 v[160:163], v[26:27], off
	global_load_dwordx4 v[38:41], v[26:27], off offset:2048
	global_load_dwordx4 v[86:89], v[32:33], off offset:-4096
	global_load_dwordx4 v[78:81], v[32:33], off
	global_load_dwordx4 v[58:61], v[32:33], off offset:2048
	global_load_dwordx4 v[46:49], v[134:135], off offset:-4096
	global_load_dwordx4 v[62:65], v[30:31], off offset:2048
	global_load_dwordx4 v[26:29], v[42:43], off offset:2048
	s_nop 0
	global_load_dwordx4 v[42:45], v[134:135], off
	global_load_dwordx4 v[30:33], v[134:135], off offset:2048
	s_waitcnt vmcnt(16)
	v_mov_b32_e32 v119, v18
	v_mov_b32_e32 v120, v22
	v_mov_b32_e32 v121, v18
	v_mov_b32_e32 v116, v15
	v_mov_b32_e32 v117, v19
	v_mov_b32_e32 v114, v16
	v_mov_b32_e32 v115, v20
	v_mov_b32_e32 v112, v17
	v_mov_b32_e32 v113, v21
	v_mov_b32_e32 v110, v2
	v_mov_b32_e32 v111, v6
	v_mov_b32_e32 v108, v3
	v_mov_b32_e32 v109, v7
	v_mov_b32_e32 v106, v4
	v_mov_b32_e32 v107, v8
	v_mov_b32_e32 v104, v5
	v_mov_b32_e32 v105, v9
	s_waitcnt vmcnt(15)
	v_lshlrev_b32_e32 v152, 16, v127
	s_waitcnt vmcnt(14)
	v_lshlrev_b32_e32 v134, 16, v50
	v_mov_b32_e32 v123, v134
	v_pk_mul_f32 v[122:123], v[118:119], v[122:123]
	v_and_b32_e32 v153, 0xffff0000, v127
	s_waitcnt vmcnt(12)
	v_lshlrev_b32_e32 v135, 16, v54
	v_fma_f32 v122, v22, v83, v122
	v_lshlrev_b32_e32 v127, 16, v130
	v_and_b32_e32 v164, 0xffff0000, v130
	v_add_f32_e32 v130, v122, v123
	v_pk_mul_f32 v[122:123], v[120:121], v[134:135]
	v_lshlrev_b32_e32 v18, 16, v124
	v_fma_f32 v83, v14, v83, v122
	v_mul_f32_e32 v18, v130, v18
	v_add_f32_e32 v83, v83, v123
	v_and_b32_e32 v130, 0xffff0000, v50
	v_mul_f32_e32 v169, v83, v127
	v_mov_b32_e32 v83, v130
	v_pk_mul_f32 v[82:83], v[116:117], v[82:83]
	v_and_b32_e32 v85, 0xffff0000, v124
	v_fma_f32 v50, v23, v77, v82
	v_add_f32_e32 v50, v50, v83
	v_mul_f32_e32 v50, v50, v85
	v_lshlrev_b32_e32 v165, 16, v131
	v_and_b32_e32 v166, 0xffff0000, v131
	v_and_b32_e32 v131, 0xffff0000, v54
	v_cvt_pk_bf16_f32 v50, v18, v50
	v_mov_b32_e32 v18, v23
	v_pk_mul_f32 v[82:83], v[18:19], v[130:131]
	v_lshlrev_b32_e32 v124, 16, v125
	v_fma_f32 v54, v15, v77, v82
	v_lshlrev_b32_e32 v82, 16, v51
	v_mov_b32_e32 v77, v82
	v_add_f32_e32 v54, v54, v83
	v_pk_mul_f32 v[76:77], v[114:115], v[76:77]
	v_mul_f32_e32 v85, v54, v164
	v_fma_f32 v54, v24, v75, v76
	v_lshlrev_b32_e32 v83, 16, v55
	v_add_f32_e32 v54, v54, v77
	v_mov_b32_e32 v122, v24
	v_mov_b32_e32 v123, v20
	v_mul_f32_e32 v124, v54, v124
	v_pk_mul_f32 v[76:77], v[122:123], v[82:83]
	v_and_b32_e32 v54, 0xffff0000, v51
	v_fma_f32 v20, v16, v75, v76
	v_mov_b32_e32 v75, v54
	v_add_f32_e32 v20, v20, v77
	v_pk_mul_f32 v[74:75], v[112:113], v[74:75]
	v_mul_f32_e32 v76, v20, v165
	v_fma_f32 v20, v25, v73, v74
	v_and_b32_e32 v125, 0xffff0000, v125
	v_add_f32_e32 v20, v20, v75
	v_mul_f32_e32 v20, v20, v125
	v_and_b32_e32 v55, 0xffff0000, v55
	v_cvt_pk_bf16_f32 v51, v124, v20
	v_mov_b32_e32 v20, v25
	v_pk_mul_f32 v[74:75], v[20:21], v[54:55]
	v_lshlrev_b32_e32 v139, 16, v126
	v_fma_f32 v73, v17, v73, v74
	v_add_f32_e32 v73, v73, v75
	v_lshlrev_b32_e32 v74, 16, v52
	v_mul_f32_e32 v77, v73, v166
	v_mov_b32_e32 v73, v74
	v_pk_mul_f32 v[72:73], v[110:111], v[72:73]
	v_lshlrev_b32_e32 v75, 16, v56
	v_fma_f32 v72, v10, v71, v72
	v_add_f32_e32 v72, v72, v73
	v_mov_b32_e32 v124, v10
	v_mov_b32_e32 v125, v6
	v_mul_f32_e32 v127, v72, v139
	v_pk_mul_f32 v[72:73], v[124:125], v[74:75]
	v_lshlrev_b32_e32 v167, 16, v132
	v_fma_f32 v6, v2, v71, v72
	v_and_b32_e32 v72, 0xffff0000, v52
	v_mov_b32_e32 v71, v72
	v_add_f32_e32 v6, v6, v73
	v_pk_mul_f32 v[70:71], v[108:109], v[70:71]
	v_mul_f32_e32 v139, v6, v167
	v_fma_f32 v6, v11, v69, v70
	v_and_b32_e32 v126, 0xffff0000, v126
	v_add_f32_e32 v6, v6, v71
	v_mul_f32_e32 v6, v6, v126
	v_and_b32_e32 v73, 0xffff0000, v56
	v_cvt_pk_bf16_f32 v52, v127, v6
	v_mov_b32_e32 v6, v11
	v_pk_mul_f32 v[70:71], v[6:7], v[72:73]
	v_and_b32_e32 v132, 0xffff0000, v132
	v_fma_f32 v56, v3, v69, v70
	v_lshlrev_b32_e32 v70, 16, v53
	v_mov_b32_e32 v69, v70
	v_add_f32_e32 v56, v56, v71
	v_pk_mul_f32 v[68:69], v[106:107], v[68:69]
	v_mul_f32_e32 v132, v56, v132
	v_fma_f32 v56, v12, v67, v68
	v_lshlrev_b32_e32 v71, 16, v57
	v_add_f32_e32 v56, v56, v69
	v_mov_b32_e32 v126, v12
	v_mov_b32_e32 v127, v8
	v_mul_f32_e32 v152, v56, v152
	v_pk_mul_f32 v[68:69], v[126:127], v[70:71]
	v_and_b32_e32 v56, 0xffff0000, v53
	v_fma_f32 v8, v4, v67, v68
	v_mov_b32_e32 v67, v56
	v_lshlrev_b32_e32 v168, 16, v133
	v_add_f32_e32 v8, v8, v69
	v_pk_mul_f32 v[66:67], v[104:105], v[66:67]
	v_mul_f32_e32 v68, v8, v168
	v_fma_f32 v8, v13, v101, v66
	v_add_f32_e32 v8, v8, v67
	v_mul_f32_e32 v8, v8, v153
	v_and_b32_e32 v57, 0xffff0000, v57
	v_cvt_pk_bf16_f32 v53, v152, v8
	v_mov_b32_e32 v8, v13
	global_store_dwordx4 v[102:103], v[50:53], off sc1
	v_and_b32_e32 v133, 0xffff0000, v133
	v_mad_i64_i32 v[66:67], s[6:7], v84, s33, v[98:99]
	v_pk_mul_f32 v[50:51], v[8:9], v[56:57]
	v_cvt_pk_bf16_f32 v52, v139, v132
	s_waitcnt vmcnt(11)
; __device__ __forceinline__ u32x4 pack8(const float (&o)[8]) { u32x4 r; r.x = pk2(o[0], o[1]); r.y = pk2(o[2], o[3]); r.z = pk2(o[4], o[5]); r.w = pk2(o[6], o[7]); return r; }
; __device__ __forceinline__ void phase_convA(const Params& p, const bf16_t* bcv  , bf16_t* tout, const float* cw  ) {
;     ...
;             for (int q = 0; q < 4; ++q) {
;                 float bb[8], cv[8], o[8];
;                 unpack8(bq[q], bb); unpack8(cq[q], cv);
; #pragma unroll
;                 for (int i = 0; i < 8; ++i) { o[i] = bb[i] * (w0[i] * cvm2[i] + w1[i] * cvm1[i] + w2[i] * cv[i]); cvm2[i] = cvm1[i]; cvm1[i] = cv[i]; }
;                 *(u32x4*)(tout + (r0 + bt * 4 + q) * LDH + c8 * 8) = pack8(o);
;             }
	v_lshlrev_b32_e32 v132, 16, v34
	v_fma_f32 v50, v5, v101, v50
	v_add_f32_e32 v50, v50, v51
	v_mul_f32_e32 v53, v50, v133
	v_cvt_pk_bf16_f32 v53, v68, v53
	v_cvt_pk_bf16_f32 v50, v169, v85
	v_cvt_pk_bf16_f32 v51, v76, v77
	global_store_dwordx4 v[66:67], v[50:53], off sc1
	v_lshlrev_b32_e32 v68, 16, v156
	s_waitcnt vmcnt(10)
	v_lshlrev_b32_e32 v133, 16, v38
	v_mov_b32_e32 v52, v134
	v_mov_b32_e32 v53, v132
	v_pk_mul_f32 v[52:53], v[118:119], v[52:53]
	v_lshlrev_b32_e32 v152, 16, v160
	v_fma_f32 v52, v22, v135, v52
	v_add_f32_e32 v52, v52, v53
	v_mul_f32_e32 v68, v52, v68
	v_pk_mul_f32 v[52:53], v[120:121], v[132:133]
	v_and_b32_e32 v134, 0xffff0000, v34
	v_fma_f32 v52, v14, v135, v52
	v_add_f32_e32 v52, v52, v53
	v_mul_f32_e32 v165, v52, v152
	v_mov_b32_e32 v52, v130
	v_mov_b32_e32 v53, v134
	v_pk_mul_f32 v[52:53], v[116:117], v[52:53]
	v_and_b32_e32 v135, 0xffff0000, v38
	v_fma_f32 v34, v23, v131, v52
	v_add_f32_e32 v34, v34, v53
	v_pk_mul_f32 v[52:53], v[18:19], v[134:135]
	v_lshlrev_b32_e32 v130, 16, v35
	v_fma_f32 v38, v15, v131, v52
	v_and_b32_e32 v69, 0xffff0000, v156
	v_add_f32_e32 v38, v38, v53
	v_mov_b32_e32 v52, v82
	v_mov_b32_e32 v53, v130
	v_and_b32_e32 v153, 0xffff0000, v160
	v_mul_f32_e32 v34, v34, v69
	v_pk_mul_f32 v[52:53], v[114:115], v[52:53]
	v_cvt_pk_bf16_f32 v34, v68, v34
	v_mul_f32_e32 v68, v38, v153
	v_lshlrev_b32_e32 v131, 16, v39
	v_fma_f32 v38, v24, v83, v52
	v_lshlrev_b32_e32 v76, 16, v157
	v_add_f32_e32 v38, v38, v53
	v_pk_mul_f32 v[52:53], v[122:123], v[130:131]
	v_mul_f32_e32 v69, v38, v76
	v_fma_f32 v38, v16, v83, v52
	v_lshlrev_b32_e32 v156, 16, v161
	v_add_f32_e32 v38, v38, v53
	v_and_b32_e32 v152, 0xffff0000, v35
	v_mul_f32_e32 v52, v38, v156
	v_and_b32_e32 v153, 0xffff0000, v39
	v_mov_b32_e32 v38, v54
	v_mov_b32_e32 v39, v152
	v_pk_mul_f32 v[38:39], v[112:113], v[38:39]
	v_and_b32_e32 v77, 0xffff0000, v157
	v_fma_f32 v35, v25, v55, v38
	v_add_f32_e32 v35, v35, v39
	v_pk_mul_f32 v[38:39], v[20:21], v[152:153]
	v_and_b32_e32 v157, 0xffff0000, v161
	v_fma_f32 v38, v17, v55, v38
	v_add_f32_e32 v38, v38, v39
	v_lshlrev_b32_e32 v156, 16, v36
	v_mul_f32_e32 v53, v38, v157
	v_mov_b32_e32 v38, v74
	v_mov_b32_e32 v39, v156
	v_pk_mul_f32 v[38:39], v[110:111], v[38:39]
	v_lshlrev_b32_e32 v84, 16, v158
	v_fma_f32 v38, v10, v75, v38
	v_lshlrev_b32_e32 v157, 16, v40
	v_add_f32_e32 v38, v38, v39
	v_mul_f32_e32 v54, v38, v84
	v_pk_mul_f32 v[38:39], v[124:125], v[156:157]
	v_and_b32_e32 v85, 0xffff0000, v158
	v_fma_f32 v38, v2, v75, v38
	v_lshlrev_b32_e32 v158, 16, v162
	v_add_f32_e32 v38, v38, v39
	v_mul_f32_e32 v55, v38, v158
	v_and_b32_e32 v158, 0xffff0000, v36
	v_mov_b32_e32 v38, v72
	v_mov_b32_e32 v39, v158
	v_pk_mul_f32 v[38:39], v[108:109], v[38:39]
	v_lshlrev_b32_e32 v101, 16, v159
	v_and_b32_e32 v139, 0xffff0000, v159
	v_and_b32_e32 v159, 0xffff0000, v40
	v_fma_f32 v36, v11, v73, v38
	v_add_f32_e32 v36, v36, v39
	v_pk_mul_f32 v[38:39], v[6:7], v[158:159]
	v_and_b32_e32 v160, 0xffff0000, v162
	v_fma_f32 v38, v3, v73, v38
	v_add_f32_e32 v38, v38, v39
	v_mul_f32_e32 v40, v38, v160
	v_lshlrev_b32_e32 v160, 16, v37
	v_mov_b32_e32 v38, v70
	v_mov_b32_e32 v39, v160
	v_pk_mul_f32 v[38:39], v[106:107], v[38:39]
	v_mul_f32_e32 v36, v36, v85
	v_fma_f32 v38, v12, v71, v38
	v_lshlrev_b32_e32 v161, 16, v41
	v_add_f32_e32 v38, v38, v39
	v_cvt_pk_bf16_f32 v36, v54, v36
	v_mul_f32_e32 v54, v38, v101
	v_pk_mul_f32 v[38:39], v[126:127], v[160:161]
	v_lshlrev_b32_e32 v162, 16, v163
	v_fma_f32 v38, v4, v71, v38
	v_mul_f32_e32 v35, v35, v77
	v_add_f32_e32 v38, v38, v39
	v_cvt_pk_bf16_f32 v35, v69, v35
	v_mul_f32_e32 v69, v38, v162
	v_and_b32_e32 v162, 0xffff0000, v37
	v_mov_b32_e32 v38, v56
	v_mov_b32_e32 v39, v162
	v_pk_mul_f32 v[38:39], v[104:105], v[38:39]
	s_waitcnt vmcnt(9)
	v_lshlrev_b32_e32 v101, 16, v86
	v_fma_f32 v37, v13, v57, v38
	v_add_f32_e32 v37, v37, v39
	v_mul_f32_e32 v37, v37, v139
	v_and_b32_e32 v139, 0xffff0000, v86
	v_lshlrev_b32_e32 v166, 16, v88
	v_and_b32_e32 v167, 0xffff0000, v88
	s_waitcnt vmcnt(8)
	v_lshlrev_b32_e32 v86, 16, v78
	v_and_b32_e32 v88, 0xffff0000, v78
	s_waitcnt vmcnt(5)
	v_lshlrev_b32_e32 v78, 16, v62
	v_lshlrev_b32_e32 v172, 16, v80
	v_and_b32_e32 v173, 0xffff0000, v80
	v_lshlrev_b32_e32 v174, 16, v81
	v_and_b32_e32 v175, 0xffff0000, v81
	v_mov_b32_e32 v80, v132
	v_mov_b32_e32 v81, v78
	v_pk_mul_f32 v[80:81], v[118:119], v[80:81]
	v_lshlrev_b32_e32 v170, 16, v79
	v_fma_f32 v80, v22, v133, v80
	v_and_b32_e32 v171, 0xffff0000, v79
	v_lshlrev_b32_e32 v79, 16, v58
	v_add_f32_e32 v80, v80, v81
	v_and_b32_e32 v164, 0xffff0000, v163
	v_and_b32_e32 v163, 0xffff0000, v41
	v_lshlrev_b32_e32 v168, 16, v89
	v_and_b32_e32 v169, 0xffff0000, v89
	v_mul_f32_e32 v89, v80, v101
	v_pk_mul_f32 v[80:81], v[120:121], v[78:79]
	v_cvt_pk_bf16_f32 v37, v54, v37
	global_store_dwordx4 v[66:67], v[34:37], off offset:2176 sc1
	v_fma_f32 v80, v14, v133, v80
	v_add_f32_e32 v80, v80, v81
	v_pk_mul_f32 v[34:35], v[8:9], v[162:163]
	v_mul_f32_e32 v101, v80, v86
	v_fma_f32 v34, v5, v57, v34
	v_add_f32_e32 v34, v34, v35
	v_and_b32_e32 v80, 0xffff0000, v62
	v_mul_f32_e32 v37, v34, v164
	v_cvt_pk_bf16_f32 v34, v165, v68
	v_lshlrev_b32_e32 v164, 16, v87
	v_and_b32_e32 v165, 0xffff0000, v87
	v_mov_b32_e32 v86, v134
	v_mov_b32_e32 v87, v80
	v_pk_mul_f32 v[86:87], v[116:117], v[86:87]
	v_and_b32_e32 v81, 0xffff0000, v58
	v_fma_f32 v58, v23, v135, v86
	v_add_f32_e32 v58, v58, v87
	v_pk_mul_f32 v[86:87], v[18:19], v[80:81]
	v_mul_f32_e32 v58, v58, v139
	v_fma_f32 v62, v15, v135, v86
	v_add_f32_e32 v62, v62, v87
	v_lshlrev_b32_e32 v86, 16, v63
	v_cvt_pk_bf16_f32 v58, v89, v58
	v_mul_f32_e32 v139, v62, v88
	v_mov_b32_e32 v88, v130
; __device__ __forceinline__ u32x4 pack8(const float (&o)[8]) { u32x4 r; r.x = pk2(o[0], o[1]); r.y = pk2(o[2], o[3]); r.z = pk2(o[4], o[5]); r.w = pk2(o[6], o[7]); return r; }
; __device__ __forceinline__ void phase_convA(const Params& p, const bf16_t* bcv  , bf16_t* tout, const float* cw  ) {
;     ...
;         for (int bt = 0; bt < 4; ++bt) {
;             u32x4 bn[4], cn[4];
;             if (bt < 3) {
; #pragma unroll
;                 for (int q = 0; q < 4; ++q) { const bf16_t* rp = bcv + (r0 + (bt + 1) * 4 + q) * 2048 + c8 * 8; bn[q] = *(const u32x4*)rp; cn[q] = *(const u32x4*)(rp + 1024); }
;             }
; #pragma unroll
;             for (int q = 0; q < 4; ++q) {
;                 float bb[8], cv[8], o[8];
;                 unpack8(bq[q], bb); unpack8(cq[q], cv);
; #pragma unroll
;                 for (int i = 0; i < 8; ++i) { o[i] = bb[i] * (w0[i] * cvm2[i] + w1[i] * cvm1[i] + w2[i] * cv[i]); cvm2[i] = cvm1[i]; cvm1[i] = cv[i]; }
;                 *(u32x4*)(tout + (r0 + bt * 4 + q) * LDH + c8 * 8) = pack8(o);
;             }
;             if (bt < 3) {
; #pragma unroll
;                 for (int q = 0; q < 4; ++q) { bq[q] = bn[q]; cq[q] = cn[q]; }
	v_mov_b32_e32 v89, v86
	v_pk_mul_f32 v[88:89], v[114:115], v[88:89]
	v_lshlrev_b32_e32 v87, 16, v59
	v_fma_f32 v62, v24, v131, v88
	v_add_f32_e32 v62, v62, v89
	v_pk_mul_f32 v[88:89], v[122:123], v[86:87]
	v_mul_f32_e32 v130, v62, v164
	v_fma_f32 v62, v16, v131, v88
	v_add_f32_e32 v62, v62, v89
	v_and_b32_e32 v88, 0xffff0000, v63
	v_mul_f32_e32 v164, v62, v170
	v_mov_b32_e32 v62, v152
	v_mov_b32_e32 v63, v88
	v_pk_mul_f32 v[62:63], v[112:113], v[62:63]
	v_and_b32_e32 v89, 0xffff0000, v59
	v_fma_f32 v59, v25, v153, v62
	v_add_f32_e32 v59, v59, v63
	v_pk_mul_f32 v[62:63], v[20:21], v[88:89]
	v_mul_f32_e32 v59, v59, v165
	v_fma_f32 v62, v17, v153, v62
	v_add_f32_e32 v62, v62, v63
	v_mul_f32_e32 v152, v62, v171
	v_lshlrev_b32_e32 v62, 16, v64
	v_cvt_pk_bf16_f32 v59, v130, v59
	v_mov_b32_e32 v130, v156
	v_mov_b32_e32 v131, v62
	s_mov_b64 s[6:7], 0x880
	v_pk_mul_f32 v[130:131], v[110:111], v[130:131]
	v_lshl_add_u64 v[50:51], v[66:67], 0, s[6:7]
	s_mov_b32 s6, 0x8000
	v_fma_f32 v130, v10, v157, v130
	v_cvt_pk_bf16_f32 v35, v52, v53
	v_cvt_pk_bf16_f32 v36, v55, v40
	v_cvt_pk_bf16_f32 v37, v69, v37
	global_store_dwordx4 v[50:51], v[34:37], off offset:2176 sc1
	v_lshlrev_b32_e32 v63, 16, v60
	v_add_f32_e32 v130, v130, v131
	v_add_co_u32_e32 v34, vcc, s6, v128
	s_mov_b32 s6, 0x9000
	s_nop 0
	v_addc_co_u32_e32 v35, vcc, 0, v129, vcc
	v_mul_f32_e32 v134, v130, v166
	v_pk_mul_f32 v[130:131], v[124:125], v[62:63]
	v_add_co_u32_e32 v36, vcc, s6, v128
	v_fma_f32 v130, v2, v157, v130
	s_nop 0
	v_addc_co_u32_e32 v37, vcc, 0, v129, vcc
	s_mov_b32 s6, 0xa000
	v_add_f32_e32 v130, v130, v131
	v_add_co_u32_e32 v38, vcc, s6, v128
	v_mul_f32_e32 v153, v130, v172
	v_and_b32_e32 v130, 0xffff0000, v64
	global_load_dwordx4 v[82:85], v[36:37], off offset:-4096
	global_load_dwordx4 v[74:77], v[36:37], off
	v_addc_co_u32_e32 v39, vcc, 0, v129, vcc
	s_mov_b32 s6, 0xb000
	v_mov_b32_e32 v132, v158
	v_mov_b32_e32 v133, v130
	v_add_co_u32_e32 v40, vcc, s6, v128
	v_pk_mul_f32 v[132:133], v[108:109], v[132:133]
	s_nop 0
	v_addc_co_u32_e32 v41, vcc, 0, v129, vcc
	v_and_b32_e32 v131, 0xffff0000, v60
	v_fma_f32 v60, v11, v159, v132
	global_load_dwordx4 v[66:69], v[36:37], off offset:2048
	global_load_dwordx4 v[54:57], v[40:41], off offset:-4096
	global_load_dwordx4 v[70:73], v[34:35], off offset:2048
	s_nop 0
	global_load_dwordx4 v[34:37], v[38:39], off offset:2048
	global_load_dwordx4 v[50:53], v[40:41], off
	s_nop 0
	global_load_dwordx4 v[38:41], v[40:41], off offset:2048
	v_add_f32_e32 v60, v60, v133
	v_pk_mul_f32 v[132:133], v[6:7], v[130:131]
	v_mul_f32_e32 v60, v60, v167
	v_fma_f32 v64, v3, v159, v132
	v_lshlrev_b32_e32 v132, 16, v65
	v_cvt_pk_bf16_f32 v60, v134, v60
	v_mov_b32_e32 v134, v160
	v_mov_b32_e32 v135, v132
	v_add_f32_e32 v64, v64, v133
	v_pk_mul_f32 v[134:135], v[106:107], v[134:135]
	v_mul_f32_e32 v156, v64, v173
	v_lshlrev_b32_e32 v133, 16, v61
	v_fma_f32 v64, v12, v161, v134
	v_add_f32_e32 v64, v64, v135
	v_pk_mul_f32 v[134:135], v[126:127], v[132:133]
	v_mul_f32_e32 v157, v64, v168
	v_fma_f32 v64, v4, v161, v134
	v_add_f32_e32 v64, v64, v135
	v_and_b32_e32 v134, 0xffff0000, v65
	v_mul_f32_e32 v158, v64, v174
	v_mov_b32_e32 v64, v162
	v_mov_b32_e32 v65, v134
	v_pk_mul_f32 v[64:65], v[104:105], v[64:65]
	v_and_b32_e32 v135, 0xffff0000, v61
	v_fma_f32 v61, v13, v163, v64
	s_movk_i32 s6, 0x2000
	v_add_f32_e32 v61, v61, v65
	v_add_co_u32_e32 v64, vcc, s6, v102
	v_mul_f32_e32 v61, v61, v169
	s_nop 0
	v_addc_co_u32_e32 v65, vcc, 0, v103, vcc
	v_cvt_pk_bf16_f32 v61, v157, v61
	global_store_dwordx4 v[64:65], v[58:61], off offset:512 sc1
	s_waitcnt vmcnt(13)
	v_and_b32_e32 v157, 0xffff0000, v30
	v_lshlrev_b32_e32 v159, 16, v31
	v_pk_mul_f32 v[58:59], v[8:9], v[134:135]
	v_cvt_pk_bf16_f32 v60, v153, v156
	v_lshlrev_b32_e32 v153, 16, v30
	v_fma_f32 v58, v5, v163, v58
	v_add_f32_e32 v58, v58, v59
	v_mul_f32_e32 v61, v58, v175
	v_cvt_pk_bf16_f32 v59, v164, v152
	v_lshlrev_b32_e32 v152, 16, v26
	v_cvt_pk_bf16_f32 v58, v101, v139
	v_cvt_pk_bf16_f32 v61, v158, v61
	global_store_dwordx4 v[64:65], v[58:61], off offset:2688 sc1
	v_lshlrev_b32_e32 v64, 16, v42
	v_and_b32_e32 v65, 0xffff0000, v42
	v_lshlrev_b32_e32 v101, 16, v43
	v_and_b32_e32 v139, 0xffff0000, v43
	v_mov_b32_e32 v42, v78
	v_mov_b32_e32 v43, v152
	v_pk_mul_f32 v[42:43], v[118:119], v[42:43]
	v_lshlrev_b32_e32 v58, 16, v46
	v_fma_f32 v42, v22, v79, v42
	v_add_f32_e32 v42, v42, v43
	v_mul_f32_e32 v58, v42, v58
	v_pk_mul_f32 v[42:43], v[120:121], v[152:153]
	v_and_b32_e32 v156, 0xffff0000, v26
	v_fma_f32 v42, v14, v79, v42
	v_add_f32_e32 v42, v42, v43
	v_mul_f32_e32 v64, v42, v64
	v_mov_b32_e32 v42, v80
	v_mov_b32_e32 v43, v156
	v_pk_mul_f32 v[42:43], v[116:117], v[42:43]
	v_lshlrev_b32_e32 v158, 16, v27
	v_fma_f32 v26, v23, v81, v42
	v_add_f32_e32 v26, v26, v43
	v_pk_mul_f32 v[42:43], v[18:19], v[156:157]
	v_and_b32_e32 v46, 0xffff0000, v46
	v_fma_f32 v30, v15, v81, v42
	v_add_f32_e32 v30, v30, v43
	v_mov_b32_e32 v42, v86
	v_mov_b32_e32 v43, v158
	v_pk_mul_f32 v[42:43], v[114:115], v[42:43]
	v_mul_f32_e32 v26, v26, v46
	v_mul_f32_e32 v46, v30, v65
	v_fma_f32 v30, v24, v87, v42
	v_lshlrev_b32_e32 v59, 16, v47
	v_add_f32_e32 v30, v30, v43
	v_pk_mul_f32 v[42:43], v[122:123], v[158:159]
	v_cvt_pk_bf16_f32 v26, v58, v26
	v_mul_f32_e32 v58, v30, v59
	v_fma_f32 v30, v16, v87, v42
	v_add_f32_e32 v30, v30, v43
	v_and_b32_e32 v160, 0xffff0000, v27
	v_mul_f32_e32 v42, v30, v101
	v_and_b32_e32 v161, 0xffff0000, v31
	v_mov_b32_e32 v30, v88
	v_mov_b32_e32 v31, v160
	v_pk_mul_f32 v[30:31], v[112:113], v[30:31]
	v_lshlrev_b32_e32 v162, 16, v28
	v_fma_f32 v27, v25, v89, v30
	v_add_f32_e32 v27, v27, v31
	v_pk_mul_f32 v[30:31], v[20:21], v[160:161]
; __device__ __forceinline__ u32x4 pack8(const float (&o)[8]) { u32x4 r; r.x = pk2(o[0], o[1]); r.y = pk2(o[2], o[3]); r.z = pk2(o[4], o[5]); r.w = pk2(o[6], o[7]); return r; }
; __device__ __forceinline__ void phase_convA(const Params& p, const bf16_t* bcv  , bf16_t* tout, const float* cw  ) {
;     ...
;         for (int bt = 0; bt < 4; ++bt) {
;             u32x4 bn[4], cn[4];
;             if (bt < 3) {
; #pragma unroll
;                 for (int q = 0; q < 4; ++q) { const bf16_t* rp = bcv + (r0 + (bt + 1) * 4 + q) * 2048 + c8 * 8; bn[q] = *(const u32x4*)rp; cn[q] = *(const u32x4*)(rp + 1024); }
;             }
; #pragma unroll
;             for (int q = 0; q < 4; ++q) {
;                 float bb[8], cv[8], o[8];
;                 unpack8(bq[q], bb); unpack8(cq[q], cv);
; #pragma unroll
;                 for (int i = 0; i < 8; ++i) { o[i] = bb[i] * (w0[i] * cvm2[i] + w1[i] * cvm1[i] + w2[i] * cv[i]); cvm2[i] = cvm1[i]; cvm1[i] = cv[i]; }
;                 *(u32x4*)(tout + (r0 + bt * 4 + q) * LDH + c8 * 8) = pack8(o);
;             }
;             if (bt < 3) {
; #pragma unroll
;                 for (int q = 0; q < 4; ++q) { bq[q] = bn[q]; cq[q] = cn[q]; }
	v_and_b32_e32 v47, 0xffff0000, v47
	v_fma_f32 v30, v17, v89, v30
	v_add_f32_e32 v30, v30, v31
	v_mul_f32_e32 v43, v30, v139
	v_mov_b32_e32 v30, v62
	v_mov_b32_e32 v31, v162
	v_pk_mul_f32 v[30:31], v[110:111], v[30:31]
	v_lshlrev_b32_e32 v60, 16, v48
	v_fma_f32 v30, v10, v63, v30
	v_lshlrev_b32_e32 v163, 16, v32
	v_add_f32_e32 v30, v30, v31
	v_mul_f32_e32 v27, v27, v47
	v_mul_f32_e32 v47, v30, v60
	v_pk_mul_f32 v[30:31], v[124:125], v[162:163]
	v_lshlrev_b32_e32 v164, 16, v44
	v_fma_f32 v30, v2, v63, v30
	v_add_f32_e32 v30, v30, v31
	v_cvt_pk_bf16_f32 v27, v58, v27
	v_mul_f32_e32 v58, v30, v164
	v_and_b32_e32 v164, 0xffff0000, v28
	v_mov_b32_e32 v30, v130
	v_mov_b32_e32 v31, v164
	v_pk_mul_f32 v[30:31], v[108:109], v[30:31]
	v_and_b32_e32 v165, 0xffff0000, v32
	v_fma_f32 v28, v11, v131, v30
	v_add_f32_e32 v28, v28, v31
	v_pk_mul_f32 v[30:31], v[6:7], v[164:165]
	v_and_b32_e32 v44, 0xffff0000, v44
	v_fma_f32 v30, v3, v131, v30
	v_add_f32_e32 v30, v30, v31
	v_lshlrev_b32_e32 v130, 16, v29
	v_mul_f32_e32 v32, v30, v44
	v_mov_b32_e32 v30, v132
	v_mov_b32_e32 v31, v130
	v_pk_mul_f32 v[30:31], v[106:107], v[30:31]
	v_lshlrev_b32_e32 v61, 16, v49
	v_fma_f32 v30, v12, v133, v30
	v_lshlrev_b32_e32 v131, 16, v33
	v_add_f32_e32 v30, v30, v31
	v_mul_f32_e32 v44, v30, v61
	v_pk_mul_f32 v[30:31], v[126:127], v[130:131]
	v_and_b32_e32 v48, 0xffff0000, v48
	v_fma_f32 v30, v4, v133, v30
	v_lshlrev_b32_e32 v166, 16, v45
	v_mul_f32_e32 v28, v28, v48
	v_add_f32_e32 v30, v30, v31
	v_and_b32_e32 v132, 0xffff0000, v29
	v_cvt_pk_bf16_f32 v28, v47, v28
	v_mul_f32_e32 v47, v30, v166
	v_mov_b32_e32 v30, v134
	v_mov_b32_e32 v31, v132
	v_pk_mul_f32 v[30:31], v[104:105], v[30:31]
	s_movk_i32 s6, 0x3000
	v_fma_f32 v29, v13, v135, v30
	v_and_b32_e32 v49, 0xffff0000, v49
	v_add_f32_e32 v29, v29, v31
	v_add_co_u32_e32 v30, vcc, s6, v102
	v_and_b32_e32 v133, 0xffff0000, v33
	v_mul_f32_e32 v29, v29, v49
	v_addc_co_u32_e32 v31, vcc, 0, v103, vcc
	v_cvt_pk_bf16_f32 v29, v44, v29
	global_store_dwordx4 v[30:31], v[26:29], off offset:768 sc1
	v_and_b32_e32 v45, 0xffff0000, v45
	s_mov_b32 s6, 0xc000
	v_pk_mul_f32 v[26:27], v[8:9], v[132:133]
	v_cvt_pk_bf16_f32 v28, v58, v32
	s_waitcnt vmcnt(10)
	v_lshlrev_b32_e32 v101, 16, v82
	v_fma_f32 v26, v5, v135, v26
	v_add_f32_e32 v26, v26, v27
	v_mul_f32_e32 v29, v26, v45
	v_cvt_pk_bf16_f32 v26, v64, v46
	v_cvt_pk_bf16_f32 v27, v42, v43
	v_cvt_pk_bf16_f32 v29, v47, v29
	global_store_dwordx4 v[30:31], v[26:29], off offset:2944 sc1
	v_lshlrev_b32_e32 v135, 16, v84
	v_and_b32_e32 v139, 0xffff0000, v84
	v_add_co_u32_e32 v26, vcc, s6, v128
	s_mov_b32 s6, 0xd000
	s_nop 0
	v_addc_co_u32_e32 v27, vcc, 0, v129, vcc
	v_add_co_u32_e32 v28, vcc, s6, v128
	s_mov_b32 s6, 0xe000
	s_nop 0
	v_addc_co_u32_e32 v29, vcc, 0, v129, vcc
	v_add_co_u32_e32 v30, vcc, s6, v128
	s_mov_b32 s6, 0xf000
	s_nop 0
	v_addc_co_u32_e32 v31, vcc, 0, v129, vcc
	v_add_co_u32_e32 v32, vcc, s6, v128
	v_and_b32_e32 v128, 0xffff0000, v82
	s_waitcnt vmcnt(10)
	v_lshlrev_b32_e32 v82, 16, v74
	v_and_b32_e32 v84, 0xffff0000, v74
	s_waitcnt vmcnt(7)
	v_lshlrev_b32_e32 v74, 16, v70
	v_lshlrev_b32_e32 v170, 16, v76
	v_and_b32_e32 v171, 0xffff0000, v76
	v_lshlrev_b32_e32 v172, 16, v77
	v_and_b32_e32 v173, 0xffff0000, v77
	v_mov_b32_e32 v76, v152
	v_mov_b32_e32 v77, v74
	v_pk_mul_f32 v[76:77], v[118:119], v[76:77]
	v_lshlrev_b32_e32 v168, 16, v75
	v_fma_f32 v76, v22, v153, v76
	v_and_b32_e32 v169, 0xffff0000, v75
	v_lshlrev_b32_e32 v75, 16, v66
	v_add_f32_e32 v76, v76, v77
	v_lshlrev_b32_e32 v166, 16, v85
	v_and_b32_e32 v167, 0xffff0000, v85
	v_mul_f32_e32 v85, v76, v101
	v_pk_mul_f32 v[76:77], v[120:121], v[74:75]
	v_addc_co_u32_e32 v33, vcc, 0, v129, vcc
	v_fma_f32 v76, v14, v153, v76
	v_add_f32_e32 v76, v76, v77
	v_mul_f32_e32 v101, v76, v82
	v_and_b32_e32 v76, 0xffff0000, v70
	v_lshlrev_b32_e32 v129, 16, v83
	v_and_b32_e32 v134, 0xffff0000, v83
	v_mov_b32_e32 v82, v156
	v_mov_b32_e32 v83, v76
	v_pk_mul_f32 v[82:83], v[116:117], v[82:83]
	v_and_b32_e32 v77, 0xffff0000, v66
	v_fma_f32 v66, v23, v157, v82
	v_add_f32_e32 v66, v66, v83
	v_pk_mul_f32 v[82:83], v[18:19], v[76:77]
	v_mul_f32_e32 v66, v66, v128
	v_fma_f32 v70, v15, v157, v82
	v_add_f32_e32 v70, v70, v83
	v_lshlrev_b32_e32 v82, 16, v71
	v_cvt_pk_bf16_f32 v66, v85, v66
	v_mul_f32_e32 v156, v70, v84
	v_mov_b32_e32 v84, v158
	v_mov_b32_e32 v85, v82
	v_pk_mul_f32 v[84:85], v[114:115], v[84:85]
	v_lshlrev_b32_e32 v83, 16, v67
	v_fma_f32 v70, v24, v159, v84
	v_add_f32_e32 v70, v70, v85
	v_pk_mul_f32 v[84:85], v[122:123], v[82:83]
	v_mul_f32_e32 v128, v70, v129
	v_fma_f32 v70, v16, v159, v84
	v_add_f32_e32 v70, v70, v85
	v_and_b32_e32 v84, 0xffff0000, v71
	v_mul_f32_e32 v157, v70, v168
	v_mov_b32_e32 v70, v160
	v_mov_b32_e32 v71, v84
	v_pk_mul_f32 v[70:71], v[112:113], v[70:71]
	v_and_b32_e32 v85, 0xffff0000, v67
	v_fma_f32 v67, v25, v161, v70
	v_add_f32_e32 v67, v67, v71
	v_pk_mul_f32 v[70:71], v[20:21], v[84:85]
	v_mul_f32_e32 v67, v67, v134
	v_fma_f32 v70, v17, v161, v70
	v_add_f32_e32 v70, v70, v71
	v_mul_f32_e32 v158, v70, v169
	v_lshlrev_b32_e32 v70, 16, v72
	v_cvt_pk_bf16_f32 v67, v128, v67
	v_mov_b32_e32 v128, v162
	v_mov_b32_e32 v129, v70
	v_pk_mul_f32 v[128:129], v[110:111], v[128:129]
	v_lshlrev_b32_e32 v71, 16, v68
	v_fma_f32 v128, v10, v163, v128
	v_add_f32_e32 v128, v128, v129
	v_mul_f32_e32 v152, v128, v135
	v_pk_mul_f32 v[128:129], v[124:125], v[70:71]
	v_mov_b32_e32 v134, v164
	v_fma_f32 v128, v2, v163, v128
	v_add_f32_e32 v128, v128, v129
	v_mul_f32_e32 v159, v128, v170
	v_and_b32_e32 v128, 0xffff0000, v72
	v_mov_b32_e32 v135, v128
	global_load_dwordx4 v[86:89], v[28:29], off offset:-4096
	global_load_dwordx4 v[78:81], v[28:29], off
; __device__ __forceinline__ u32x4 pack8(const float (&o)[8]) { u32x4 r; r.x = pk2(o[0], o[1]); r.y = pk2(o[2], o[3]); r.z = pk2(o[4], o[5]); r.w = pk2(o[6], o[7]); return r; }
; __device__ __forceinline__ void phase_convA(const Params& p, const bf16_t* bcv  , bf16_t* tout, const float* cw  ) {
;     ...
;         for (int bt = 0; bt < 4; ++bt) {
;             u32x4 bn[4], cn[4];
;             if (bt < 3) {
; #pragma unroll
;                 for (int q = 0; q < 4; ++q) { const bf16_t* rp = bcv + (r0 + (bt + 1) * 4 + q) * 2048 + c8 * 8; bn[q] = *(const u32x4*)rp; cn[q] = *(const u32x4*)(rp + 1024); }
;             }
; #pragma unroll
;             for (int q = 0; q < 4; ++q) {
;                 float bb[8], cv[8], o[8];
;                 unpack8(bq[q], bb); unpack8(cq[q], cv);
; #pragma unroll
;                 for (int i = 0; i < 8; ++i) { o[i] = bb[i] * (w0[i] * cvm2[i] + w1[i] * cvm1[i] + w2[i] * cv[i]); cvm2[i] = cvm1[i]; cvm1[i] = cv[i]; }
;                 *(u32x4*)(tout + (r0 + bt * 4 + q) * LDH + c8 * 8) = pack8(o);
;             }
;             if (bt < 3) {
; #pragma unroll
;                 for (int q = 0; q < 4; ++q) { bq[q] = bn[q]; cq[q] = cn[q]; }
	global_load_dwordx4 v[58:61], v[28:29], off offset:2048
	global_load_dwordx4 v[46:49], v[32:33], off offset:-4096
	global_load_dwordx4 v[62:65], v[26:27], off offset:2048
	s_nop 0
	global_load_dwordx4 v[26:29], v[30:31], off offset:2048
	global_load_dwordx4 v[42:45], v[32:33], off
	s_nop 0
	global_load_dwordx4 v[30:33], v[32:33], off offset:2048
	v_pk_mul_f32 v[134:135], v[108:109], v[134:135]
	v_and_b32_e32 v129, 0xffff0000, v68
	v_fma_f32 v68, v11, v165, v134
	v_add_f32_e32 v68, v68, v135
	v_pk_mul_f32 v[134:135], v[6:7], v[128:129]
	v_mul_f32_e32 v68, v68, v139
	v_fma_f32 v72, v3, v165, v134
	v_lshlrev_b32_e32 v134, 16, v73
	v_cvt_pk_bf16_f32 v68, v152, v68
	v_mov_b32_e32 v152, v130
	v_mov_b32_e32 v153, v134
	v_add_f32_e32 v72, v72, v135
	v_pk_mul_f32 v[152:153], v[106:107], v[152:153]
	v_mul_f32_e32 v139, v72, v171
	v_lshlrev_b32_e32 v135, 16, v69
	v_fma_f32 v72, v12, v131, v152
	v_add_f32_e32 v72, v72, v153
	v_pk_mul_f32 v[152:153], v[126:127], v[134:135]
	v_mul_f32_e32 v160, v72, v166
	v_fma_f32 v72, v4, v131, v152
	v_add_f32_e32 v72, v72, v153
	v_and_b32_e32 v130, 0xffff0000, v73
	v_mul_f32_e32 v152, v72, v172
	v_mov_b32_e32 v72, v132
	v_mov_b32_e32 v73, v130
	v_pk_mul_f32 v[72:73], v[104:105], v[72:73]
	v_and_b32_e32 v131, 0xffff0000, v69
	v_fma_f32 v69, v13, v133, v72
	v_add_f32_e32 v69, v69, v73
	v_add_co_u32_e32 v72, vcc, s9, v102
	v_mul_f32_e32 v69, v69, v167
	s_nop 0
	v_addc_co_u32_e32 v73, vcc, 0, v103, vcc
	v_cvt_pk_bf16_f32 v69, v160, v69
	global_store_dwordx4 v[72:73], v[66:69], off offset:1024 sc1
	s_waitcnt vmcnt(14)
	v_and_b32_e32 v153, 0xffff0000, v52
	v_and_b32_e32 v132, 0xffff0000, v57
	v_pk_mul_f32 v[66:67], v[8:9], v[130:131]
	v_cvt_pk_bf16_f32 v68, v159, v139
	v_and_b32_e32 v139, 0xffff0000, v51
	v_fma_f32 v66, v5, v133, v66
	v_add_f32_e32 v66, v66, v67
	v_mul_f32_e32 v69, v66, v173
	v_cvt_pk_bf16_f32 v66, v101, v156
	v_cvt_pk_bf16_f32 v67, v157, v158
	v_cvt_pk_bf16_f32 v69, v152, v69
	global_store_dwordx4 v[72:73], v[66:69], off offset:3200 sc1
	v_lshlrev_b32_e32 v72, 16, v56
	v_and_b32_e32 v73, 0xffff0000, v56
	v_lshlrev_b32_e32 v66, 16, v54
	v_and_b32_e32 v67, 0xffff0000, v54
	v_lshlrev_b32_e32 v54, 16, v50
	v_and_b32_e32 v56, 0xffff0000, v50
	v_lshlrev_b32_e32 v50, 16, v34
	v_lshlrev_b32_e32 v152, 16, v52
	v_lshlrev_b32_e32 v156, 16, v53
	v_and_b32_e32 v157, 0xffff0000, v53
	v_mov_b32_e32 v52, v74
	v_mov_b32_e32 v53, v50
	v_pk_mul_f32 v[52:53], v[118:119], v[52:53]
	v_lshlrev_b32_e32 v133, 16, v51
	v_fma_f32 v52, v22, v75, v52
	s_waitcnt vmcnt(14)
	v_lshlrev_b32_e32 v51, 16, v38
	v_add_f32_e32 v52, v52, v53
	v_lshlrev_b32_e32 v101, 16, v57
	v_mul_f32_e32 v57, v52, v66
	v_pk_mul_f32 v[52:53], v[120:121], v[50:51]
	v_lshlrev_b32_e32 v68, 16, v55
	v_fma_f32 v52, v14, v75, v52
	v_add_f32_e32 v52, v52, v53
	v_mul_f32_e32 v74, v52, v54
	v_and_b32_e32 v52, 0xffff0000, v34
	v_and_b32_e32 v69, 0xffff0000, v55
	v_mov_b32_e32 v54, v76
	v_mov_b32_e32 v55, v52
	v_pk_mul_f32 v[54:55], v[116:117], v[54:55]
	v_and_b32_e32 v53, 0xffff0000, v38
	v_fma_f32 v34, v23, v77, v54
	v_add_f32_e32 v34, v34, v55
	v_pk_mul_f32 v[54:55], v[18:19], v[52:53]
	v_mul_f32_e32 v34, v34, v67
	v_fma_f32 v38, v15, v77, v54
	v_add_f32_e32 v38, v38, v55
	v_lshlrev_b32_e32 v54, 16, v35
	v_cvt_pk_bf16_f32 v34, v57, v34
	v_mul_f32_e32 v75, v38, v56
	v_mov_b32_e32 v56, v82
	v_mov_b32_e32 v57, v54
	v_pk_mul_f32 v[56:57], v[114:115], v[56:57]
	v_lshlrev_b32_e32 v55, 16, v39
	v_fma_f32 v38, v24, v83, v56
	v_add_f32_e32 v38, v38, v57
	v_pk_mul_f32 v[56:57], v[122:123], v[54:55]
	v_mul_f32_e32 v66, v38, v68
	v_fma_f32 v38, v16, v83, v56
	v_add_f32_e32 v38, v38, v57
	v_mul_f32_e32 v76, v38, v133
	v_and_b32_e32 v38, 0xffff0000, v35
	v_mov_b32_e32 v56, v84
	v_mov_b32_e32 v57, v38
	v_pk_mul_f32 v[56:57], v[112:113], v[56:57]
	v_and_b32_e32 v39, 0xffff0000, v39
	v_fma_f32 v35, v25, v85, v56
	v_add_f32_e32 v35, v35, v57
	v_pk_mul_f32 v[56:57], v[20:21], v[38:39]
	v_mul_f32_e32 v35, v35, v69
	v_fma_f32 v56, v17, v85, v56
	v_add_f32_e32 v56, v56, v57
	v_mul_f32_e32 v77, v56, v139
	v_lshlrev_b32_e32 v56, 16, v36
	v_cvt_pk_bf16_f32 v35, v66, v35
	v_mov_b32_e32 v66, v70
	v_mov_b32_e32 v67, v56
	v_pk_mul_f32 v[66:67], v[110:111], v[66:67]
	v_lshlrev_b32_e32 v57, 16, v40
	v_fma_f32 v66, v10, v71, v66
	v_add_f32_e32 v66, v66, v67
	v_mul_f32_e32 v70, v66, v72
	v_pk_mul_f32 v[66:67], v[124:125], v[56:57]
	v_mov_b32_e32 v68, v128
	v_fma_f32 v66, v2, v71, v66
	v_add_f32_e32 v66, v66, v67
	v_mul_f32_e32 v72, v66, v152
	v_and_b32_e32 v66, 0xffff0000, v36
	v_mov_b32_e32 v69, v66
	v_pk_mul_f32 v[68:69], v[108:109], v[68:69]
	v_and_b32_e32 v67, 0xffff0000, v40
	v_fma_f32 v36, v11, v129, v68
	v_add_f32_e32 v36, v36, v69
	v_pk_mul_f32 v[68:69], v[6:7], v[66:67]
	v_mul_f32_e32 v36, v36, v73
	v_fma_f32 v40, v3, v129, v68
	v_lshlrev_b32_e32 v68, 16, v37
	v_cvt_pk_bf16_f32 v36, v70, v36
	v_mov_b32_e32 v70, v134
	v_mov_b32_e32 v71, v68
	v_add_f32_e32 v40, v40, v69
	v_pk_mul_f32 v[70:71], v[106:107], v[70:71]
	v_mul_f32_e32 v73, v40, v153
	v_lshlrev_b32_e32 v69, 16, v41
	v_fma_f32 v40, v12, v135, v70
	v_add_f32_e32 v40, v40, v71
	v_pk_mul_f32 v[70:71], v[126:127], v[68:69]
	v_mul_f32_e32 v82, v40, v101
	v_fma_f32 v40, v4, v135, v70
	v_add_f32_e32 v40, v40, v71
	v_mul_f32_e32 v83, v40, v156
	v_and_b32_e32 v40, 0xffff0000, v37
	v_mov_b32_e32 v70, v130
	v_mov_b32_e32 v71, v40
	v_pk_mul_f32 v[70:71], v[104:105], v[70:71]
	v_and_b32_e32 v41, 0xffff0000, v41
	v_fma_f32 v37, v13, v131, v70
	v_add_f32_e32 v37, v37, v71
	v_add_co_u32_e32 v70, vcc, s8, v102
	v_mul_f32_e32 v37, v37, v132
	s_nop 0
	v_addc_co_u32_e32 v71, vcc, 0, v103, vcc
	v_cvt_pk_bf16_f32 v37, v82, v37
	global_store_dwordx4 v[70:71], v[34:37], off offset:1280 sc1
	s_waitcnt vmcnt(9)
; __device__ __forceinline__ u32x4 pack8(const float (&o)[8]) { u32x4 r; r.x = pk2(o[0], o[1]); r.y = pk2(o[2], o[3]); r.z = pk2(o[4], o[5]); r.w = pk2(o[6], o[7]); return r; }
; __device__ __forceinline__ void phase_convA(const Params& p, const bf16_t* bcv  , bf16_t* tout, const float* cw  ) {
;     ...
;             for (int q = 0; q < 4; ++q) {
;                 float bb[8], cv[8], o[8];
;                 unpack8(bq[q], bb); unpack8(cq[q], cv);
; #pragma unroll
;                 for (int i = 0; i < 8; ++i) { o[i] = bb[i] * (w0[i] * cvm2[i] + w1[i] * cvm1[i] + w2[i] * cv[i]); cvm2[i] = cvm1[i]; cvm1[i] = cv[i]; }
;                 *(u32x4*)(tout + (r0 + bt * 4 + q) * LDH + c8 * 8) = pack8(o);
;             }
	v_lshlrev_b32_e32 v82, 16, v78
	v_and_b32_e32 v78, 0xffff0000, v78
	v_pk_mul_f32 v[34:35], v[8:9], v[40:41]
	v_cvt_pk_bf16_f32 v36, v72, v73
	v_lshlrev_b32_e32 v72, 16, v87
	v_fma_f32 v34, v5, v131, v34
	v_add_f32_e32 v34, v34, v35
	v_mul_f32_e32 v37, v34, v157
	v_cvt_pk_bf16_f32 v34, v74, v75
	v_cvt_pk_bf16_f32 v35, v76, v77
	v_cvt_pk_bf16_f32 v37, v83, v37
	global_store_dwordx4 v[70:71], v[34:37], off offset:3456 sc1
	s_waitcnt vmcnt(7)
	v_lshlrev_b32_e32 v70, 16, v62
	v_lshlrev_b32_e32 v71, 16, v58
	v_mov_b32_e32 v34, v50
	v_mov_b32_e32 v35, v70
	v_pk_mul_f32 v[34:35], v[118:119], v[34:35]
	v_lshlrev_b32_e32 v36, 16, v86
	v_fma_f32 v34, v22, v51, v34
	v_add_f32_e32 v34, v34, v35
	v_mul_f32_e32 v36, v34, v36
	v_pk_mul_f32 v[34:35], v[120:121], v[70:71]
	v_and_b32_e32 v50, 0xffff0000, v62
	v_fma_f32 v34, v14, v51, v34
	v_add_f32_e32 v34, v34, v35
	v_mul_f32_e32 v82, v34, v82
	v_mov_b32_e32 v34, v52
	v_mov_b32_e32 v35, v50
	v_pk_mul_f32 v[34:35], v[116:117], v[34:35]
	v_and_b32_e32 v37, 0xffff0000, v86
	v_fma_f32 v34, v23, v53, v34
	v_add_f32_e32 v34, v34, v35
	v_and_b32_e32 v51, 0xffff0000, v58
	v_mul_f32_e32 v34, v34, v37
	v_cvt_pk_bf16_f32 v34, v36, v34
	v_pk_mul_f32 v[36:37], v[18:19], v[50:51]
	v_lshlrev_b32_e32 v52, 16, v63
	v_fma_f32 v35, v15, v53, v36
	v_add_f32_e32 v35, v35, v37
	v_mov_b32_e32 v36, v54
	v_mov_b32_e32 v37, v52
	v_pk_mul_f32 v[36:37], v[114:115], v[36:37]
	v_mul_f32_e32 v78, v35, v78
	v_lshlrev_b32_e32 v53, 16, v59
	v_fma_f32 v35, v24, v55, v36
	v_add_f32_e32 v35, v35, v37
	v_pk_mul_f32 v[36:37], v[122:123], v[52:53]
	v_lshlrev_b32_e32 v83, 16, v79
	v_fma_f32 v36, v16, v55, v36
	v_add_f32_e32 v36, v36, v37
	v_and_b32_e32 v54, 0xffff0000, v63
	v_mul_f32_e32 v35, v35, v72
	v_mul_f32_e32 v72, v36, v83
	v_mov_b32_e32 v36, v38
	v_mov_b32_e32 v37, v54
	v_pk_mul_f32 v[36:37], v[112:113], v[36:37]
	v_and_b32_e32 v73, 0xffff0000, v87
	v_fma_f32 v36, v25, v39, v36
	v_add_f32_e32 v36, v36, v37
	v_and_b32_e32 v55, 0xffff0000, v59
	v_mul_f32_e32 v36, v36, v73
	v_cvt_pk_bf16_f32 v35, v35, v36
	v_pk_mul_f32 v[36:37], v[20:21], v[54:55]
	v_and_b32_e32 v79, 0xffff0000, v79
	v_fma_f32 v36, v17, v39, v36
	v_add_f32_e32 v36, v36, v37
	v_lshlrev_b32_e32 v38, 16, v64
	v_mul_f32_e32 v73, v36, v79
	v_mov_b32_e32 v36, v56
	v_mov_b32_e32 v37, v38
	v_pk_mul_f32 v[36:37], v[110:111], v[36:37]
	v_lshlrev_b32_e32 v74, 16, v88
	v_fma_f32 v36, v10, v57, v36
	v_lshlrev_b32_e32 v39, 16, v60
	v_add_f32_e32 v36, v36, v37
	v_mul_f32_e32 v58, v36, v74
	v_pk_mul_f32 v[36:37], v[124:125], v[38:39]
	v_lshlrev_b32_e32 v84, 16, v80
	v_fma_f32 v36, v2, v57, v36
	v_add_f32_e32 v36, v36, v37
	v_and_b32_e32 v56, 0xffff0000, v64
	v_mul_f32_e32 v74, v36, v84
	v_mov_b32_e32 v36, v66
	v_mov_b32_e32 v37, v56
	v_pk_mul_f32 v[36:37], v[108:109], v[36:37]
	v_and_b32_e32 v75, 0xffff0000, v88
	v_fma_f32 v36, v11, v67, v36
	v_add_f32_e32 v36, v36, v37
	v_and_b32_e32 v57, 0xffff0000, v60
	v_mul_f32_e32 v36, v36, v75
	v_cvt_pk_bf16_f32 v36, v58, v36
	v_pk_mul_f32 v[58:59], v[6:7], v[56:57]
	v_mov_b32_e32 v62, v68
	v_fma_f32 v37, v3, v67, v58
	v_lshlrev_b32_e32 v58, 16, v65
	v_mov_b32_e32 v63, v58
	v_and_b32_e32 v80, 0xffff0000, v80
	v_add_f32_e32 v37, v37, v59
	v_pk_mul_f32 v[62:63], v[106:107], v[62:63]
	v_mul_f32_e32 v64, v37, v80
	v_lshlrev_b32_e32 v59, 16, v61
	v_fma_f32 v37, v12, v69, v62
	v_add_f32_e32 v37, v37, v63
	v_pk_mul_f32 v[62:63], v[126:127], v[58:59]
	v_lshlrev_b32_e32 v85, 16, v81
	v_fma_f32 v60, v4, v69, v62
	v_add_f32_e32 v60, v60, v63
	v_mul_f32_e32 v66, v60, v85
	v_and_b32_e32 v60, 0xffff0000, v65
	v_mov_b32_e32 v62, v40
	v_mov_b32_e32 v63, v60
	v_pk_mul_f32 v[62:63], v[104:105], v[62:63]
	v_lshlrev_b32_e32 v76, 16, v89
	v_fma_f32 v40, v13, v41, v62
	v_add_co_u32_e32 v62, vcc, s10, v102
	v_and_b32_e32 v77, 0xffff0000, v89
	v_mul_f32_e32 v37, v37, v76
	v_and_b32_e32 v61, 0xffff0000, v61
	v_add_f32_e32 v40, v40, v63
	v_addc_co_u32_e32 v63, vcc, 0, v103, vcc
	v_mul_f32_e32 v40, v40, v77
	v_cvt_pk_bf16_f32 v37, v37, v40
	global_store_dwordx4 v[62:63], v[34:37], off offset:1536 sc1
	v_and_b32_e32 v81, 0xffff0000, v81
	v_lshlrev_b32_e32 v40, 16, v46
	v_pk_mul_f32 v[34:35], v[8:9], v[60:61]
	v_cvt_pk_bf16_f32 v36, v74, v64
	s_waitcnt vmcnt(6)
; __device__ __forceinline__ u32x4 pack8(const float (&o)[8]) { u32x4 r; r.x = pk2(o[0], o[1]); r.y = pk2(o[2], o[3]); r.z = pk2(o[4], o[5]); r.w = pk2(o[6], o[7]); return r; }
; __device__ __forceinline__ void phase_convA(const Params& p, const bf16_t* bcv  , bf16_t* tout, const float* cw  ) {
;     ...
;             for (int q = 0; q < 4; ++q) {
;                 float bb[8], cv[8], o[8];
;                 unpack8(bq[q], bb); unpack8(cq[q], cv);
; #pragma unroll
;                 for (int i = 0; i < 8; ++i) { o[i] = bb[i] * (w0[i] * cvm2[i] + w1[i] * cvm1[i] + w2[i] * cv[i]); cvm2[i] = cvm1[i]; cvm1[i] = cv[i]; }
;                 *(u32x4*)(tout + (r0 + bt * 4 + q) * LDH + c8 * 8) = pack8(o);
;             }
;             if (bt < 3) {
; #pragma unroll
;                 for (int q = 0; q < 4; ++q) { bq[q] = bn[q]; cq[q] = cn[q]; }
;             }
;         }
;     }
	v_lshlrev_b32_e32 v64, 16, v42
	v_fma_f32 v34, v5, v41, v34
	v_add_f32_e32 v34, v34, v35
	v_mul_f32_e32 v37, v34, v81
	v_cvt_pk_bf16_f32 v34, v82, v78
	v_cvt_pk_bf16_f32 v35, v72, v73
	v_cvt_pk_bf16_f32 v37, v66, v37
	global_store_dwordx4 v[62:63], v[34:37], off offset:3712 sc1
	v_and_b32_e32 v41, 0xffff0000, v46
	v_and_b32_e32 v42, 0xffff0000, v42
	v_lshlrev_b32_e32 v34, 16, v26
	s_waitcnt vmcnt(6)
	v_lshlrev_b32_e32 v35, 16, v30
	v_mov_b32_e32 v36, v70
	v_mov_b32_e32 v37, v34
	v_pk_mul_f32 v[36:37], v[118:119], v[36:37]
	v_pk_mul_f32 v[34:35], v[120:121], v[34:35]
	v_fma_f32 v22, v22, v71, v36
	v_fma_f32 v14, v14, v71, v34
	v_and_b32_e32 v34, 0xffff0000, v26
	v_add_f32_e32 v22, v22, v37
	v_mov_b32_e32 v36, v50
	v_mov_b32_e32 v37, v34
	v_add_f32_e32 v14, v14, v35
	v_pk_mul_f32 v[36:37], v[116:117], v[36:37]
	v_mul_f32_e32 v22, v22, v40
	v_mul_f32_e32 v40, v14, v64
	v_and_b32_e32 v35, 0xffff0000, v30
	v_fma_f32 v14, v23, v51, v36
	v_add_f32_e32 v14, v14, v37
	v_pk_mul_f32 v[18:19], v[18:19], v[34:35]
	v_mul_f32_e32 v14, v14, v41
	v_fma_f32 v15, v15, v51, v18
	v_lshlrev_b32_e32 v18, 16, v27
	v_cvt_pk_bf16_f32 v14, v22, v14
	v_add_f32_e32 v15, v15, v19
	v_lshlrev_b32_e32 v19, 16, v31
	v_mov_b32_e32 v22, v52
	v_mov_b32_e32 v23, v18
	v_pk_mul_f32 v[22:23], v[114:115], v[22:23]
	v_pk_mul_f32 v[18:19], v[122:123], v[18:19]
	v_mul_f32_e32 v26, v15, v42
	v_fma_f32 v15, v24, v53, v22
	v_fma_f32 v16, v16, v53, v18
	v_and_b32_e32 v18, 0xffff0000, v27
	v_add_f32_e32 v15, v15, v23
	v_mov_b32_e32 v22, v54
	v_mov_b32_e32 v23, v18
	v_lshlrev_b32_e32 v65, 16, v43
	v_add_f32_e32 v16, v16, v19
	v_pk_mul_f32 v[22:23], v[112:113], v[22:23]
	v_mul_f32_e32 v24, v16, v65
	v_fma_f32 v16, v25, v55, v22
	v_lshlrev_b32_e32 v46, 16, v47
	v_and_b32_e32 v47, 0xffff0000, v47
	v_and_b32_e32 v19, 0xffff0000, v31
	v_add_f32_e32 v16, v16, v23
	v_mul_f32_e32 v15, v15, v46
	v_mul_f32_e32 v16, v16, v47
	v_pk_mul_f32 v[18:19], v[20:21], v[18:19]
	v_cvt_pk_bf16_f32 v15, v15, v16
	v_and_b32_e32 v43, 0xffff0000, v43
	v_fma_f32 v16, v17, v55, v18
	v_add_f32_e32 v16, v16, v19
	v_mul_f32_e32 v20, v16, v43
	v_lshlrev_b32_e32 v16, 16, v28
	v_lshlrev_b32_e32 v17, 16, v32
	v_mov_b32_e32 v18, v38
	v_mov_b32_e32 v19, v16
	v_pk_mul_f32 v[18:19], v[110:111], v[18:19]
	v_pk_mul_f32 v[16:17], v[124:125], v[16:17]
	v_fma_f32 v10, v10, v39, v18
	v_fma_f32 v2, v2, v39, v16
	v_and_b32_e32 v18, 0xffff0000, v28
	v_add_f32_e32 v2, v2, v17
	v_mov_b32_e32 v16, v56
	v_mov_b32_e32 v17, v18
	v_lshlrev_b32_e32 v66, 16, v44
	v_pk_mul_f32 v[16:17], v[108:109], v[16:17]
	v_mul_f32_e32 v21, v2, v66
	v_fma_f32 v2, v11, v57, v16
	v_lshlrev_b32_e32 v62, 16, v48
	v_and_b32_e32 v48, 0xffff0000, v48
	v_add_f32_e32 v10, v10, v19
	v_and_b32_e32 v19, 0xffff0000, v32
	v_add_f32_e32 v2, v2, v17
	v_mul_f32_e32 v2, v2, v48
	v_pk_mul_f32 v[6:7], v[6:7], v[18:19]
	v_mul_f32_e32 v10, v10, v62
	v_cvt_pk_bf16_f32 v16, v10, v2
	v_fma_f32 v2, v3, v57, v6
	v_and_b32_e32 v44, 0xffff0000, v44
	v_add_f32_e32 v2, v2, v7
	v_mul_f32_e32 v10, v2, v44
	v_lshlrev_b32_e32 v2, 16, v29
	v_lshlrev_b32_e32 v3, 16, v33
	v_mov_b32_e32 v6, v58
	v_mov_b32_e32 v7, v2
	v_pk_mul_f32 v[2:3], v[126:127], v[2:3]
	v_pk_mul_f32 v[6:7], v[106:107], v[6:7]
	v_fma_f32 v2, v4, v59, v2
	v_lshlrev_b32_e32 v67, 16, v45
	v_fma_f32 v6, v12, v59, v6
	v_add_f32_e32 v2, v2, v3
	v_lshlrev_b32_e32 v63, 16, v49
	v_add_f32_e32 v6, v6, v7
	v_mul_f32_e32 v12, v2, v67
	v_and_b32_e32 v2, 0xffff0000, v29
	v_mul_f32_e32 v11, v6, v63
	v_mov_b32_e32 v6, v60
	v_mov_b32_e32 v7, v2
	v_and_b32_e32 v3, 0xffff0000, v33
	v_pk_mul_f32 v[6:7], v[104:105], v[6:7]
	v_pk_mul_f32 v[2:3], v[8:9], v[2:3]
	v_fma_f32 v4, v13, v61, v6
	v_add_co_u32_e32 v6, vcc, s11, v102
	v_readlane_b32 s6, v255, 4
	v_add_f32_e32 v4, v4, v7
	v_addc_co_u32_e32 v7, vcc, 0, v103, vcc
	v_fma_f32 v2, v5, v61, v2
	v_add_u32_e32 v1, s6, v1
	s_mov_b32 s6, 0x3ffff
	v_and_b32_e32 v49, 0xffff0000, v49
	v_and_b32_e32 v45, 0xffff0000, v45
	v_add_f32_e32 v2, v2, v3
	v_cmp_lt_i32_e32 vcc, s6, v1
	v_mul_f32_e32 v4, v4, v49
	v_mul_f32_e32 v5, v2, v45
	s_or_b64 s[4:5], vcc, s[4:5]
	v_cvt_pk_bf16_f32 v17, v11, v4
	global_store_dwordx4 v[6:7], v[14:17], off offset:1792 sc1
	v_cvt_pk_bf16_f32 v2, v40, v26
	v_cvt_pk_bf16_f32 v3, v24, v20
	v_cvt_pk_bf16_f32 v4, v21, v10
	v_cvt_pk_bf16_f32 v5, v12, v5
	global_store_dwordx4 v[6:7], v[2:5], off offset:3968 sc1
	s_andn2_b64 exec, exec, s[4:5]
	s_cbranch_execz .LBB0_750

; __device__ __forceinline__ float bflo(unsigned u) { return __uint_as_float(u << 16); }
; __device__ __forceinline__ float bfhi(unsigned u) { return __uint_as_float(u & 0xffff0000u); }
; __device__ __forceinline__ void phase_rowwise(const Params& p, const float* xs32, const bf16_t* xs16, float* xd32, bf16_t* xd16, const bf16_t* y, const float* gpost, int modres,
;                                               bf16_t* hout, const float* gpre, int modh) {
;     ...
;         if (y) {
;             u32x2 yp[RB][4];
; #pragma unroll
;             for (int r = 0; r < RB; ++r)
; #pragma unroll
;                 for (int j = 0; j < 4; ++j) yp[r][j] = *(const u32x2*)(y + (row0 + r) * LDH + lane * 4 + 256 * j);
;             float ss[RB];
; #pragma unroll
;             for (int r = 0; r < RB; ++r) { ss[r] = 0.f;
; #pragma unroll
;                 for (int j = 0; j < 4; ++j) { const float a = bflo(yp[r][j].x), b = bfhi(yp[r][j].x), c = bflo(yp[r][j].y), d = bfhi(yp[r][j].y); ss[r] += (a * a + b * b) + (c * c + d * d); } }
.LBB0_916:
	v_readlane_b32 s0, v254, 56
	v_readlane_b32 s1, v254, 57
	s_andn2_b64 vcc, exec, s[0:1]
	s_cbranch_vccnz .LBB0_912
	v_lshl_add_u64 v[82:83], v[76:77], 0, v[70:71]
	global_load_dwordx2 v[84:85], v[82:83], off
	global_load_dwordx2 v[86:87], v[82:83], off offset:512
	global_load_dwordx2 v[90:91], v[82:83], off offset:1024
	global_load_dwordx2 v[100:101], v[82:83], off offset:1536
	global_load_dwordx2 v[102:103], v[82:83], off offset:2176
	global_load_dwordx2 v[104:105], v[82:83], off offset:2688
	global_load_dwordx2 v[124:125], v[82:83], off offset:3200
	global_load_dwordx2 v[126:127], v[82:83], off offset:3712
	v_add_co_u32_e32 v80, vcc, 0x1000, v82
	v_ashrrev_i32_e32 v79, 9, v1
	s_nop 0
	v_addc_co_u32_e32 v81, vcc, 0, v83, vcc
	global_load_dwordx2 v[116:117], v[80:81], off offset:256
	global_load_dwordx2 v[114:115], v[80:81], off offset:768
	global_load_dwordx2 v[110:111], v[80:81], off offset:1280
	global_load_dwordx2 v[132:133], v[80:81], off offset:1792
	global_load_dwordx2 v[122:123], v[80:81], off offset:2432
	global_load_dwordx2 v[120:121], v[80:81], off offset:2944
	global_load_dwordx2 v[112:113], v[80:81], off offset:3456
	global_load_dwordx2 v[118:119], v[80:81], off offset:3968
	v_mul_hi_i32_i24_e32 v99, 0x18000, v79
	v_mul_i32_i24_e32 v98, 0x18000, v79
	v_lshl_add_u64 v[98:99], s[10:11], 0, v[98:99]
	s_movk_i32 s0, 0x3000
	s_mov_b32 s12, 0x3a800000
	s_waitcnt vmcnt(15)
	v_and_b32_e32 v131, 0xffff0000, v84
	s_waitcnt vmcnt(14)
	v_and_b32_e32 v97, 0xffff0000, v87
	v_and_b32_e32 v96, 0xffff0000, v86
	v_and_b32_e32 v129, 0xffff0000, v85
	v_lshlrev_b32_e32 v95, 16, v87
	v_lshlrev_b32_e32 v94, 16, v86
	v_pk_mul_f32 v[86:87], v[96:97], v[96:97]
	v_lshlrev_b32_e32 v130, 16, v84
	v_lshlrev_b32_e32 v128, 16, v85
	v_mul_f32_e32 v84, v129, v129
	v_pk_fma_f32 v[106:107], v[94:95], v[94:95], v[86:87]
	s_waitcnt vmcnt(12)
	v_lshlrev_b32_e32 v87, 16, v100
	v_mul_f32_e32 v86, v131, v131
	v_pk_fma_f32 v[84:85], v[128:129], v[128:129], v[84:85] op_sel_hi:[1,1,0]
	v_and_b32_e32 v184, 0xffff0000, v100
	v_lshlrev_b32_e32 v181, 16, v101
	v_and_b32_e32 v180, 0xffff0000, v101
	v_pk_fma_f32 v[100:101], v[130:131], v[130:131], v[86:87] op_sel_hi:[1,1,0]
	v_mov_b32_e32 v108, v84
	v_mov_b32_e32 v86, v100
	v_mov_b32_e32 v109, v87
	v_pk_add_f32 v[84:85], v[100:101], v[84:85]
	v_pk_mul_f32 v[100:101], v[86:87], v[108:109]
	v_and_b32_e32 v93, 0xffff0000, v90
	v_mul_f32_e32 v79, v184, v184
	v_mov_b32_e32 v85, v101
	v_pk_add_f32 v[100:101], v[106:107], v[106:107] op_sel:[0,1] op_sel_hi:[1,0]
	v_lshlrev_b32_e32 v92, 16, v90
	v_lshlrev_b32_e32 v90, 16, v91
	v_and_b32_e32 v91, 0xffff0000, v91
	v_mov_b32_e32 v101, v79
	v_mul_f32_e32 v86, v93, v93
	v_pk_add_f32 v[84:85], v[84:85], v[100:101]
	v_pk_fma_f32 v[100:101], v[92:93], v[92:93], v[86:87] op_sel_hi:[1,1,0]
	v_mul_f32_e32 v86, v91, v91
	v_mul_f32_e32 v134, v181, v181
	v_mul_f32_e32 v135, v180, v180
	v_pk_fma_f32 v[106:107], v[90:91], v[90:91], v[86:87] op_sel_hi:[1,1,0]
	v_mov_b32_e32 v101, v134
	v_mov_b32_e32 v107, v135
	v_pk_add_f32 v[100:101], v[100:101], v[106:107]
	s_waitcnt vmcnt(10)
	v_and_b32_e32 v109, 0xffff0000, v105
	v_and_b32_e32 v108, 0xffff0000, v104
	v_pk_add_f32 v[84:85], v[84:85], v[100:101]
	v_and_b32_e32 v165, 0xffff0000, v102
	v_and_b32_e32 v163, 0xffff0000, v103
	v_lshlrev_b32_e32 v107, 16, v105
	v_lshlrev_b32_e32 v106, 16, v104
	v_pk_mul_f32 v[100:101], v[108:109], v[108:109]
	v_lshlrev_b32_e32 v164, 16, v102
	v_lshlrev_b32_e32 v162, 16, v103
	v_mul_f32_e32 v86, v163, v163
	v_pk_fma_f32 v[154:155], v[106:107], v[106:107], v[100:101]
	s_waitcnt vmcnt(8)
	v_lshlrev_b32_e32 v101, 16, v126
	v_mul_f32_e32 v100, v165, v165
	v_pk_fma_f32 v[134:135], v[162:163], v[162:163], v[86:87] op_sel_hi:[1,1,0]
	v_lshlrev_b32_e32 v104, 16, v124
	v_and_b32_e32 v105, 0xffff0000, v124
	v_lshlrev_b32_e32 v102, 16, v125
	v_and_b32_e32 v103, 0xffff0000, v125
	v_pk_fma_f32 v[124:125], v[164:165], v[164:165], v[100:101] op_sel_hi:[1,1,0]
	v_and_b32_e32 v186, 0xffff0000, v126
	v_lshlrev_b32_e32 v185, 16, v127
	v_and_b32_e32 v86, 0xffff0000, v127
	v_mov_b32_e32 v100, v124
	v_mov_b32_e32 v126, v134
	v_mov_b32_e32 v127, v101
	v_pk_add_f32 v[124:125], v[124:125], v[134:135]
	v_pk_mul_f32 v[126:127], v[100:101], v[126:127]
	v_mul_f32_e32 v79, v186, v186
	v_mov_b32_e32 v125, v127
	v_pk_add_f32 v[126:127], v[154:155], v[154:155] op_sel:[0,1] op_sel_hi:[1,0]
	v_mul_f32_e32 v100, v105, v105
	v_mov_b32_e32 v127, v79
	v_pk_add_f32 v[124:125], v[124:125], v[126:127]
	v_pk_fma_f32 v[126:127], v[104:105], v[104:105], v[100:101] op_sel_hi:[1,1,0]
	v_mul_f32_e32 v100, v103, v103
	v_mul_f32_e32 v139, v185, v185
	v_mul_f32_e32 v144, v86, v86
	v_pk_fma_f32 v[134:135], v[102:103], v[102:103], v[100:101] op_sel_hi:[1,1,0]
	v_mov_b32_e32 v127, v139
	v_mov_b32_e32 v135, v144
	v_pk_add_f32 v[126:127], v[126:127], v[134:135]
	s_waitcnt vmcnt(7)
	v_and_b32_e32 v155, 0xffff0000, v117
	v_pk_add_f32 v[176:177], v[124:125], v[126:127]
	v_and_b32_e32 v157, 0xffff0000, v116
	v_lshlrev_b32_e32 v154, 16, v117
	v_mul_f32_e32 v100, v155, v155
	s_waitcnt vmcnt(6)
	v_and_b32_e32 v127, 0xffff0000, v115
	v_and_b32_e32 v126, 0xffff0000, v114
	v_lshlrev_b32_e32 v156, 16, v116
	v_pk_fma_f32 v[134:135], v[154:155], v[154:155], v[100:101] op_sel_hi:[1,1,0]
	v_lshlrev_b32_e32 v125, 16, v115
	v_lshlrev_b32_e32 v124, 16, v114
	v_pk_mul_f32 v[114:115], v[126:127], v[126:127]
	v_mul_f32_e32 v100, v157, v157
	v_pk_fma_f32 v[158:159], v[124:125], v[124:125], v[114:115]
	s_waitcnt vmcnt(5)
	v_lshlrev_b32_e32 v114, 16, v111
	v_and_b32_e32 v115, 0xffff0000, v111
	s_waitcnt vmcnt(4)
; __device__ __forceinline__ float bflo(unsigned u) { return __uint_as_float(u << 16); }
; __device__ __forceinline__ float bfhi(unsigned u) { return __uint_as_float(u & 0xffff0000u); }
; __device__ __forceinline__ void phase_rowwise(const Params& p, const float* xs32, const bf16_t* xs16, float* xd32, bf16_t* xd16, const bf16_t* y, const float* gpost, int modres,
;                                               bf16_t* hout, const float* gpre, int modh) {
;     ...
;             for (int r = 0; r < RB; ++r) { ss[r] = 0.f;
; #pragma unroll
;                 for (int j = 0; j < 4; ++j) { const float a = bflo(yp[r][j].x), b = bfhi(yp[r][j].x), c = bflo(yp[r][j].y), d = bfhi(yp[r][j].y); ss[r] += (a * a + b * b) + (c * c + d * d); } }
; #pragma unroll
;             for (int o = 1; o < 64; o <<= 1)
; #pragma unroll
;                 for (int r = 0; r < RB; ++r) ss[r] += __shfl_xor(ss[r], o);
; #pragma unroll
;             for (int j = 0; j < 4; ++j) { const f32x4 gt = *(const f32x4*)(modb + modres + lane * 4 + 256 * j), gp = *(const f32x4*)(gpost + lane * 4 + 256 * j);
;                 const f32x4 gg = gt * gp;
	v_lshlrev_b32_e32 v111, 16, v132
	v_and_b32_e32 v189, 0xffff0000, v132
	v_lshlrev_b32_e32 v188, 16, v133
	v_and_b32_e32 v187, 0xffff0000, v133
	v_pk_fma_f32 v[132:133], v[156:157], v[156:157], v[100:101] op_sel_hi:[1,1,0]
	v_lshlrev_b32_e32 v116, 16, v110
	v_and_b32_e32 v117, 0xffff0000, v110
	v_mov_b32_e32 v110, v132
	v_mov_b32_e32 v160, v134
	v_mov_b32_e32 v161, v111
	v_pk_add_f32 v[132:133], v[132:133], v[134:135]
	v_pk_mul_f32 v[134:135], v[110:111], v[160:161]
	v_mul_f32_e32 v79, v189, v189
	v_mov_b32_e32 v133, v135
	v_pk_add_f32 v[134:135], v[158:159], v[158:159] op_sel:[0,1] op_sel_hi:[1,0]
	v_mul_f32_e32 v100, v117, v117
	v_mov_b32_e32 v135, v79
	v_pk_add_f32 v[132:133], v[132:133], v[134:135]
	v_pk_fma_f32 v[134:135], v[116:117], v[116:117], v[100:101] op_sel_hi:[1,1,0]
	v_mul_f32_e32 v100, v115, v115
	v_mul_f32_e32 v139, v188, v188
	v_mul_f32_e32 v144, v187, v187
	v_pk_fma_f32 v[158:159], v[114:115], v[114:115], v[100:101] op_sel_hi:[1,1,0]
	v_mov_b32_e32 v135, v139
	v_mov_b32_e32 v159, v144
	v_pk_add_f32 v[134:135], v[134:135], v[158:159]
	s_waitcnt vmcnt(3)
	v_and_b32_e32 v159, 0xffff0000, v123
	v_pk_add_f32 v[168:169], v[132:133], v[134:135]
	v_and_b32_e32 v161, 0xffff0000, v122
	v_lshlrev_b32_e32 v158, 16, v123
	v_mul_f32_e32 v100, v159, v159
	s_waitcnt vmcnt(2)
	v_and_b32_e32 v135, 0xffff0000, v121
	v_and_b32_e32 v134, 0xffff0000, v120
	v_lshlrev_b32_e32 v160, 16, v122
	v_pk_fma_f32 v[166:167], v[158:159], v[158:159], v[100:101] op_sel_hi:[1,1,0]
	v_lshlrev_b32_e32 v133, 16, v121
	v_lshlrev_b32_e32 v132, 16, v120
	v_pk_mul_f32 v[120:121], v[134:135], v[134:135]
	v_mul_f32_e32 v100, v161, v161
	v_pk_fma_f32 v[170:171], v[132:133], v[132:133], v[120:121]
	s_waitcnt vmcnt(1)
	v_lshlrev_b32_e32 v120, 16, v113
	v_and_b32_e32 v121, 0xffff0000, v113
	s_waitcnt vmcnt(0)
	v_lshlrev_b32_e32 v113, 16, v118
	v_and_b32_e32 v192, 0xffff0000, v118
	v_lshlrev_b32_e32 v191, 16, v119
	v_and_b32_e32 v190, 0xffff0000, v119
	v_pk_fma_f32 v[118:119], v[160:161], v[160:161], v[100:101] op_sel_hi:[1,1,0]
	v_lshlrev_b32_e32 v122, 16, v112
	v_and_b32_e32 v123, 0xffff0000, v112
	v_mov_b32_e32 v112, v118
	v_mov_b32_e32 v172, v166
	v_mov_b32_e32 v173, v113
	v_pk_add_f32 v[118:119], v[118:119], v[166:167]
	v_pk_mul_f32 v[166:167], v[112:113], v[172:173]
	v_mul_f32_e32 v79, v192, v192
	v_mov_b32_e32 v119, v167
	v_pk_add_f32 v[166:167], v[170:171], v[170:171] op_sel:[0,1] op_sel_hi:[1,0]
	v_mul_f32_e32 v100, v123, v123
	v_mov_b32_e32 v167, v79
	v_pk_add_f32 v[118:119], v[118:119], v[166:167]
	v_pk_fma_f32 v[166:167], v[122:123], v[122:123], v[100:101] op_sel_hi:[1,1,0]
	v_mul_f32_e32 v100, v121, v121
	v_and_b32_e32 v79, 64, v137
	v_pk_fma_f32 v[170:171], v[120:121], v[120:121], v[100:101] op_sel_hi:[1,1,0]
	v_add_u32_e32 v79, 64, v79
	v_xor_b32_e32 v100, 1, v137
	v_cmp_lt_i32_e32 vcc, v100, v79
	v_mul_f32_e32 v139, v190, v190
	v_mov_b32_e32 v171, v139
	v_cndmask_b32_e32 v100, v137, v100, vcc
	v_lshlrev_b32_e32 v179, 2, v100
	v_xor_b32_e32 v100, 2, v137
	v_cmp_lt_i32_e32 vcc, v100, v79
	v_mul_f32_e32 v110, v191, v191
	v_mov_b32_e32 v167, v110
	v_cndmask_b32_e32 v100, v137, v100, vcc
	v_lshlrev_b32_e32 v178, 2, v100
	v_xor_b32_e32 v100, 4, v137
	v_cmp_lt_i32_e32 vcc, v100, v79
	v_pk_add_f32 v[166:167], v[166:167], v[170:171]
	s_nop 0
	v_cndmask_b32_e32 v100, v137, v100, vcc
	v_lshlrev_b32_e32 v139, 2, v100
	v_xor_b32_e32 v100, 8, v137
	v_cmp_lt_i32_e32 vcc, v100, v79
	v_pk_add_f32 v[170:171], v[118:119], v[166:167]
	s_nop 0
	v_cndmask_b32_e32 v100, v137, v100, vcc
	v_lshlrev_b32_e32 v112, 2, v100
	v_xor_b32_e32 v100, 16, v137
	v_cmp_lt_i32_e32 vcc, v100, v79
	s_nop 1
	v_cndmask_b32_e32 v100, v137, v100, vcc
	v_lshlrev_b32_e32 v110, 2, v100
	v_xor_b32_e32 v100, 32, v137
	v_cmp_lt_i32_e32 vcc, v100, v79
	s_nop 1
	v_cndmask_b32_e32 v79, v137, v100, vcc
	v_lshlrev_b32_e32 v100, 2, v79
	v_mov_b32_e32 v79, v0
	v_lshl_add_u64 v[98:99], v[98:99], 0, v[78:79]
	v_add_co_u32_e32 v118, vcc, s0, v98
	s_mov_b32 s0, 0x358637bd
	s_nop 0
	v_addc_co_u32_e32 v119, vcc, 0, v99, vcc
	global_load_dwordx4 v[194:197], v[118:119], off offset:-4096
	global_load_dwordx4 v[198:201], v[66:67], off
	v_lshl_add_u64 v[166:167], v[98:99], 0, s[88:89]
	s_waitcnt vmcnt(0)
	v_pk_mul_f32 v[174:175], v[194:195], v[198:199]
	v_mov_b32_e32 v194, v176
	v_mov_b32_e32 v195, v84
	v_mov_b32_e32 v84, v177
	v_pk_add_f32 v[84:85], v[194:195], v[84:85]
	ds_bpermute_b32 v177, v179, v85
	ds_bpermute_b32 v176, v179, v84
	v_pk_mul_f32 v[172:173], v[196:197], v[200:201]
	s_waitcnt lgkmcnt(0)
	v_pk_add_f32 v[84:85], v[84:85], v[176:177]
	ds_bpermute_b32 v177, v178, v85
	ds_bpermute_b32 v176, v178, v84
	s_waitcnt lgkmcnt(0)
	v_pk_add_f32 v[84:85], v[84:85], v[176:177]
	ds_bpermute_b32 v177, v139, v85
	ds_bpermute_b32 v176, v139, v84
	s_waitcnt lgkmcnt(0)
	v_pk_add_f32 v[84:85], v[84:85], v[176:177]
	ds_bpermute_b32 v177, v112, v85
	ds_bpermute_b32 v176, v112, v84
	s_waitcnt lgkmcnt(0)
	v_pk_add_f32 v[84:85], v[84:85], v[176:177]
	ds_bpermute_b32 v177, v110, v85
	ds_bpermute_b32 v176, v110, v84
	s_waitcnt lgkmcnt(0)
	v_pk_add_f32 v[84:85], v[84:85], v[176:177]
	ds_bpermute_b32 v177, v100, v85
	ds_bpermute_b32 v176, v100, v84
	s_waitcnt lgkmcnt(0)
; __device__ __forceinline__ unsigned pk2(float lo, float hi) { unsigned r; asm("v_cvt_pk_bf16_f32 %0, %1, %2" : "=v"(r) : "v"(lo), "v"(hi)); return r; }
; __device__ __forceinline__ float bflo(unsigned u) { return __uint_as_float(u << 16); }
; __device__ __forceinline__ float bfhi(unsigned u) { return __uint_as_float(u & 0xffff0000u); }
; __device__ __forceinline__ void phase_rowwise(const Params& p, const float* xs32, const bf16_t* xs16, float* xd32, bf16_t* xd16, const bf16_t* y, const float* gpost, int modres,
;                                               bf16_t* hout, const float* gpre, int modh) {
;     ...
;             for (int j = 0; j < 4; ++j) { const f32x4 gt = *(const f32x4*)(modb + modres + lane * 4 + 256 * j), gp = *(const f32x4*)(gpost + lane * 4 + 256 * j);
;                 const f32x4 gg = gt * gp;
; #pragma unroll
;                 for (int r = 0; r < RB; ++r) { const float rstd = rsqrtf(ss[r] * (1.f / D) + EPS);
;                     xv[r][j][0] += gg[0] * (bflo(yp[r][j].x) * rstd); xv[r][j][1] += gg[1] * (bfhi(yp[r][j].x) * rstd);
;                     xv[r][j][2] += gg[2] * (bflo(yp[r][j].y) * rstd); xv[r][j][3] += gg[3] * (bfhi(yp[r][j].y) * rstd);
;                     if (xd32) *(f32x4*)(xd32 + (row0 + r) * D + lane * 4 + 256 * j) = xv[r][j];
;                     if (xd16) { u32x2 o; o.x = pk2(xv[r][j][0], xv[r][j][1]); o.y = pk2(xv[r][j][2], xv[r][j][3]);
;                         *(u32x2*)(xd16 + (row0 + r) * D + lane * 4 + 256 * j) = o;
;                         xv[r][j][0] = bflo(o.x); xv[r][j][1] = bfhi(o.x); xv[r][j][2] = bflo(o.y); xv[r][j][3] = bfhi(o.y); } } }
	v_pk_add_f32 v[176:177], v[84:85], v[176:177]
	v_mov_b64_e32 v[84:85], s[0:1]
	v_pk_fma_f32 v[176:177], v[176:177], s[12:13], v[84:85] op_sel_hi:[1,0,0]
	s_nop 0
	v_mul_f32_e32 v79, 0x4b800000, v177
	v_cmp_gt_f32_e64 s[0:1], s76, v177
	v_cmp_gt_f32_e32 vcc, s76, v176
	s_nop 0
	v_cndmask_b32_e64 v79, v177, v79, s[0:1]
	v_rsq_f32_e32 v79, v79
	s_nop 0
	v_mul_f32_e32 v144, 0x45800000, v79
	v_cndmask_b32_e64 v79, v79, v144, s[0:1]
	v_mul_f32_e32 v128, v79, v128
	v_fma_f32 v60, v172, v128, v60
	v_mul_f32_e32 v128, v79, v129
	s_mov_b32 s0, 0x241c000
	v_mul_f32_e32 v130, v79, v130
	v_fmac_f32_e32 v61, v173, v128
	v_add_co_u32_e64 v128, s[0:1], s0, v88
	v_fma_f32 v58, v174, v130, v58
	v_mul_f32_e32 v130, v79, v131
	v_addc_co_u32_e64 v129, s[0:1], 0, v89, s[0:1]
	v_fma_f32 v59, v175, v130, v59
	s_mov_b32 s0, 0x241d000
	v_cvt_pk_bf16_f32 v58, v58, v59
	v_cvt_pk_bf16_f32 v59, v60, v61
	v_add_co_u32_e64 v60, s[0:1], s0, v88
	v_mul_f32_e32 v88, 0x4b800000, v176
	v_cndmask_b32_e32 v88, v176, v88, vcc
	v_rsq_f32_e32 v88, v88
	v_addc_co_u32_e64 v61, s[0:1], 0, v89, s[0:1]
	global_store_dwordx2 v[60:61], v[58:59], off offset:-4096 sc1
	v_mul_f32_e32 v89, 0x45800000, v88
	v_cndmask_b32_e32 v130, v88, v89, vcc
	v_mul_f32_e32 v88, v130, v164
	v_fma_f32 v62, v174, v88, v62
	v_mul_f32_e32 v88, v130, v165
	v_fma_f32 v63, v175, v88, v63
	v_mul_f32_e32 v88, v130, v162
	v_fma_f32 v64, v172, v88, v64
	v_mul_f32_e32 v88, v130, v163
	v_fmac_f32_e32 v65, v173, v88
	v_cvt_pk_bf16_f32 v62, v62, v63
	v_cvt_pk_bf16_f32 v63, v64, v65
	v_mov_b32_e32 v64, v170
	v_mov_b32_e32 v65, v168
	v_mov_b32_e32 v168, v171
	v_pk_add_f32 v[64:65], v[64:65], v[168:169]
	ds_bpermute_b32 v89, v179, v65
	ds_bpermute_b32 v88, v179, v64
	global_store_dwordx2 v[128:129], v[62:63], off offset:2048 sc1
	s_waitcnt lgkmcnt(0)
	v_pk_add_f32 v[64:65], v[64:65], v[88:89]
	ds_bpermute_b32 v89, v178, v65
	ds_bpermute_b32 v88, v178, v64
	s_waitcnt lgkmcnt(0)
	v_pk_add_f32 v[64:65], v[64:65], v[88:89]
	ds_bpermute_b32 v89, v139, v65
	ds_bpermute_b32 v88, v139, v64
	s_waitcnt lgkmcnt(0)
	v_pk_add_f32 v[64:65], v[64:65], v[88:89]
	ds_bpermute_b32 v89, v112, v65
	ds_bpermute_b32 v88, v112, v64
	s_waitcnt lgkmcnt(0)
	v_pk_add_f32 v[64:65], v[64:65], v[88:89]
	ds_bpermute_b32 v89, v110, v65
	ds_bpermute_b32 v88, v110, v64
	s_waitcnt lgkmcnt(0)
	v_pk_add_f32 v[64:65], v[64:65], v[88:89]
	ds_bpermute_b32 v89, v100, v65
	ds_bpermute_b32 v88, v100, v64
	s_waitcnt lgkmcnt(0)
	v_pk_add_f32 v[64:65], v[64:65], v[88:89]
	s_nop 0
	v_pk_fma_f32 v[64:65], v[64:65], s[12:13], v[84:85] op_sel_hi:[1,0,0]
	s_nop 0
	v_mul_f32_e32 v88, 0x4b800000, v65
	v_cmp_gt_f32_e64 s[0:1], s76, v65
	v_cmp_gt_f32_e32 vcc, s76, v64
	s_nop 0
	v_cndmask_b32_e64 v65, v65, v88, s[0:1]
	v_rsq_f32_e32 v65, v65
	s_nop 0
	v_mul_f32_e32 v88, 0x45800000, v65
	v_cndmask_b32_e64 v88, v65, v88, s[0:1]
	v_mul_f32_e32 v65, v88, v156
	v_fma_f32 v54, v174, v65, v54
	v_mul_f32_e32 v65, v88, v157
	v_fma_f32 v55, v175, v65, v55
	v_mul_f32_e32 v65, v88, v154
	v_fma_f32 v65, v172, v65, v56
	v_mul_f32_e32 v56, v88, v155
	v_fmac_f32_e32 v57, v173, v56
	v_cvt_pk_bf16_f32 v56, v54, v55
	v_mul_f32_e32 v54, 0x4b800000, v64
	v_cndmask_b32_e32 v54, v64, v54, vcc
	v_rsq_f32_e32 v54, v54
	v_cvt_pk_bf16_f32 v57, v65, v57
	global_store_dwordx2 v[60:61], v[56:57], off sc1
	v_mul_f32_e32 v64, v79, v94
	v_mul_f32_e32 v55, 0x45800000, v54
	v_cndmask_b32_e32 v89, v54, v55, vcc
	v_mul_f32_e32 v54, v89, v160
	v_fma_f32 v50, v174, v54, v50
	v_mul_f32_e32 v54, v89, v161
	v_fma_f32 v51, v175, v54, v51
	v_mul_f32_e32 v54, v89, v158
	v_fma_f32 v52, v172, v54, v52
	v_mul_f32_e32 v54, v89, v159
	v_fmac_f32_e32 v53, v173, v54
	v_cvt_pk_bf16_f32 v54, v50, v51
	v_cvt_pk_bf16_f32 v55, v52, v53
	global_store_dwordx2 v[60:61], v[54:55], off offset:2048 sc1
	global_load_dwordx4 v[50:53], v[166:167], off offset:1024
	global_load_dwordx4 v[154:157], v[66:67], off offset:1024
	s_mov_b64 s[0:1], 0x3000
	s_waitcnt vmcnt(0)
	v_pk_mul_f32 v[50:51], v[50:51], v[154:155]
	s_nop 0
	v_fma_f32 v42, v64, v50, v42
	v_mul_f32_e32 v64, v79, v96
	v_pk_mul_f32 v[52:53], v[52:53], v[156:157]
	v_fma_f32 v43, v64, v51, v43
	v_mul_f32_e32 v64, v79, v95
	v_fma_f32 v44, v64, v52, v44
	v_mul_f32_e32 v64, v79, v97
	v_fmac_f32_e32 v45, v64, v53
	v_cvt_pk_bf16_f32 v64, v42, v43
	v_mul_f32_e32 v42, v130, v106
	v_fma_f32 v42, v42, v50, v46
	v_mul_f32_e32 v43, v130, v108
	v_fma_f32 v43, v43, v51, v47
	v_cvt_pk_bf16_f32 v46, v42, v43
	v_mul_f32_e32 v42, v88, v124
	v_fma_f32 v34, v42, v50, v34
	v_mul_f32_e32 v42, v88, v126
	v_fma_f32 v35, v42, v51, v35
	v_mul_f32_e32 v42, v88, v125
	v_fma_f32 v42, v42, v52, v36
	v_mul_f32_e32 v36, v88, v127
	v_fmac_f32_e32 v37, v36, v53
	v_cvt_pk_bf16_f32 v36, v34, v35
	v_mul_f32_e32 v34, v89, v132
	v_mul_f32_e32 v35, v89, v134
	v_cvt_pk_bf16_f32 v65, v44, v45
	v_mul_f32_e32 v44, v130, v107
	v_mul_f32_e32 v45, v130, v109
	v_fma_f32 v34, v34, v50, v38
	v_fma_f32 v35, v35, v51, v39
	v_mul_f32_e32 v38, v89, v133
	v_mul_f32_e32 v39, v89, v135
	global_store_dwordx2 v[128:129], v[64:65], off offset:512 sc1
	v_fma_f32 v44, v44, v52, v48
	v_fmac_f32_e32 v49, v45, v53
	v_cvt_pk_bf16_f32 v47, v44, v49
	global_store_dwordx2 v[128:129], v[46:47], off offset:2560 sc1
	v_cvt_pk_bf16_f32 v37, v42, v37
	global_store_dwordx2 v[60:61], v[36:37], off offset:512 sc1
	v_fma_f32 v38, v38, v52, v40
	v_fmac_f32_e32 v41, v39, v53
	v_cvt_pk_bf16_f32 v34, v34, v35
	v_cvt_pk_bf16_f32 v35, v38, v41
	global_store_dwordx2 v[60:61], v[34:35], off offset:2560 sc1
	global_load_dwordx4 v[38:41], v[166:167], off offset:2048
	global_load_dwordx4 v[42:45], v[66:67], off offset:2048
	v_and_b32_e32 v53, 0xffff0000, v56
	v_and_b32_e32 v51, 0xffff0000, v57
	v_lshlrev_b32_e32 v52, 16, v56
	v_lshlrev_b32_e32 v50, 16, v57
	v_lshlrev_b32_e32 v56, 16, v54
	v_and_b32_e32 v57, 0xffff0000, v54
	v_lshlrev_b32_e32 v54, 16, v55
	v_and_b32_e32 v55, 0xffff0000, v55
	s_waitcnt vmcnt(0)
; __device__ __forceinline__ unsigned pk2(float lo, float hi) { unsigned r; asm("v_cvt_pk_bf16_f32 %0, %1, %2" : "=v"(r) : "v"(lo), "v"(hi)); return r; }
; __device__ __forceinline__ float bflo(unsigned u) { return __uint_as_float(u << 16); }
; __device__ __forceinline__ float bfhi(unsigned u) { return __uint_as_float(u & 0xffff0000u); }
; __device__ __forceinline__ void phase_rowwise(const Params& p, const float* xs32, const bf16_t* xs16, float* xd32, bf16_t* xd16, const bf16_t* y, const float* gpost, int modres,
;                                               bf16_t* hout, const float* gpre, int modh) {
;     ...
;             for (int j = 0; j < 4; ++j) { const f32x4 gt = *(const f32x4*)(modb + modres + lane * 4 + 256 * j), gp = *(const f32x4*)(gpost + lane * 4 + 256 * j);
;                 const f32x4 gg = gt * gp;
; #pragma unroll
;                 for (int r = 0; r < RB; ++r) { const float rstd = rsqrtf(ss[r] * (1.f / D) + EPS);
;                     xv[r][j][0] += gg[0] * (bflo(yp[r][j].x) * rstd); xv[r][j][1] += gg[1] * (bfhi(yp[r][j].x) * rstd);
;                     xv[r][j][2] += gg[2] * (bflo(yp[r][j].y) * rstd); xv[r][j][3] += gg[3] * (bfhi(yp[r][j].y) * rstd);
;                     if (xd32) *(f32x4*)(xd32 + (row0 + r) * D + lane * 4 + 256 * j) = xv[r][j];
;                     if (xd16) { u32x2 o; o.x = pk2(xv[r][j][0], xv[r][j][1]); o.y = pk2(xv[r][j][2], xv[r][j][3]);
;                         *(u32x2*)(xd16 + (row0 + r) * D + lane * 4 + 256 * j) = o;
;                         xv[r][j][0] = bflo(o.x); xv[r][j][1] = bfhi(o.x); xv[r][j][2] = bflo(o.y); xv[r][j][3] = bfhi(o.y); } } }
;         }
;         if (hout) {
;             float ss[RB];
; #pragma unroll
;             for (int r = 0; r < RB; ++r) { ss[r] = 0.f;
; #pragma unroll
;                 for (int j = 0; j < 4; ++j) ss[r] += (xv[r][j][0] * xv[r][j][0] + xv[r][j][1] * xv[r][j][1]) + (xv[r][j][2] * xv[r][j][2] + xv[r][j][3] * xv[r][j][3]); }
	v_pk_mul_f32 v[38:39], v[38:39], v[42:43]
	v_mul_f32_e32 v42, v79, v92
	v_fma_f32 v26, v42, v38, v26
	v_mul_f32_e32 v42, v79, v93
	v_pk_mul_f32 v[40:41], v[40:41], v[44:45]
	v_fma_f32 v27, v42, v39, v27
	v_mul_f32_e32 v42, v79, v90
	v_fma_f32 v28, v42, v40, v28
	v_mul_f32_e32 v42, v79, v91
	v_fmac_f32_e32 v29, v42, v41
	v_cvt_pk_bf16_f32 v26, v26, v27
	v_cvt_pk_bf16_f32 v27, v28, v29
	v_mul_f32_e32 v28, v130, v104
	v_fma_f32 v28, v28, v38, v30
	v_mul_f32_e32 v29, v130, v105
	v_mul_f32_e32 v30, v130, v102
	v_fma_f32 v29, v29, v39, v31
	v_fma_f32 v30, v30, v40, v32
	v_mul_f32_e32 v31, v130, v103
	v_fmac_f32_e32 v33, v31, v41
	v_cvt_pk_bf16_f32 v28, v28, v29
	v_cvt_pk_bf16_f32 v29, v30, v33
	v_mul_f32_e32 v30, v88, v116
	v_fma_f32 v14, v30, v38, v14
	v_mul_f32_e32 v30, v88, v117
	v_fma_f32 v15, v30, v39, v15
	v_mul_f32_e32 v30, v88, v114
	v_fma_f32 v16, v30, v40, v16
	v_mul_f32_e32 v30, v88, v115
	v_fmac_f32_e32 v17, v30, v41
	v_cvt_pk_bf16_f32 v48, v14, v15
	v_cvt_pk_bf16_f32 v49, v16, v17
	v_mul_f32_e32 v14, v89, v122
	v_mul_f32_e32 v15, v89, v123
	v_mul_f32_e32 v16, v89, v120
	v_mul_f32_e32 v17, v89, v121
	global_store_dwordx2 v[128:129], v[26:27], off offset:1024 sc1
	global_store_dwordx2 v[128:129], v[28:29], off offset:3072 sc1
	global_store_dwordx2 v[60:61], v[48:49], off offset:1024 sc1
	v_fma_f32 v14, v14, v38, v18
	v_fma_f32 v15, v15, v39, v19
	v_fma_f32 v16, v16, v40, v20
	v_fmac_f32_e32 v21, v17, v41
	v_cvt_pk_bf16_f32 v38, v14, v15
	v_cvt_pk_bf16_f32 v39, v16, v21
	global_store_dwordx2 v[60:61], v[38:39], off offset:3072 sc1
	global_load_dwordx4 v[14:17], v[166:167], off offset:3072
	global_load_dwordx4 v[18:21], v[66:67], off offset:3072
	v_and_b32_e32 v31, 0xffff0000, v47
	v_and_b32_e32 v30, 0xffff0000, v46
	v_lshlrev_b32_e32 v33, 16, v47
	v_lshlrev_b32_e32 v32, 16, v46
	v_and_b32_e32 v43, 0xffff0000, v37
	v_and_b32_e32 v42, 0xffff0000, v36
	v_lshlrev_b32_e32 v45, 16, v37
	v_lshlrev_b32_e32 v44, 16, v36
	v_and_b32_e32 v47, 0xffff0000, v35
	s_waitcnt vmcnt(0)
	v_pk_mul_f32 v[14:15], v[14:15], v[18:19]
	v_mul_f32_e32 v18, v79, v87
	v_fma_f32 v6, v18, v14, v6
	v_mul_f32_e32 v18, v79, v184
	v_pk_mul_f32 v[16:17], v[16:17], v[20:21]
	v_fma_f32 v7, v18, v15, v7
	v_mul_f32_e32 v18, v79, v181
	v_fma_f32 v18, v18, v16, v8
	v_mul_f32_e32 v8, v79, v180
	v_fmac_f32_e32 v9, v8, v17
	v_cvt_pk_bf16_f32 v8, v6, v7
	v_mul_f32_e32 v6, v130, v101
	v_cvt_pk_bf16_f32 v9, v18, v9
	global_store_dwordx2 v[128:129], v[8:9], off offset:1536 sc1
	v_lshlrev_b32_e32 v7, 16, v8
	v_and_b32_e32 v103, 0xffff0000, v8
	v_fma_f32 v6, v6, v14, v10
	v_mul_f32_e32 v8, v130, v186
	v_mul_f32_e32 v10, v130, v86
	v_fma_f32 v8, v8, v15, v11
	v_fmac_f32_e32 v13, v10, v17
	v_cvt_pk_bf16_f32 v10, v6, v8
	v_mul_f32_e32 v6, v88, v111
	v_fma_f32 v2, v6, v14, v2
	v_mul_f32_e32 v6, v88, v189
	v_fma_f32 v3, v6, v15, v3
	v_mul_f32_e32 v6, v88, v188
	v_lshlrev_b32_e32 v102, 16, v9
	v_and_b32_e32 v79, 0xffff0000, v9
	v_mul_f32_e32 v9, v130, v185
	v_fma_f32 v4, v6, v16, v4
	v_mul_f32_e32 v6, v88, v187
	v_fma_f32 v9, v9, v16, v12
	v_cvt_pk_bf16_f32 v11, v9, v13
	v_fmac_f32_e32 v5, v6, v17
	v_cvt_pk_bf16_f32 v2, v2, v3
	v_cvt_pk_bf16_f32 v3, v4, v5
	global_store_dwordx2 v[128:129], v[10:11], off offset:3584 sc1
	v_lshlrev_b32_e32 v104, 16, v11
	v_and_b32_e32 v101, 0xffff0000, v11
	global_store_dwordx2 v[60:61], v[2:3], off offset:1536 sc1
	v_lshlrev_b32_e32 v11, 16, v2
	v_and_b32_e32 v108, 0xffff0000, v2
	v_lshlrev_b32_e32 v107, 16, v3
	v_and_b32_e32 v106, 0xffff0000, v3
	v_mul_f32_e32 v2, v89, v113
	v_mul_f32_e32 v3, v89, v192
	v_fma_f32 v2, v2, v14, v22
	v_fma_f32 v3, v3, v15, v23
	v_mul_f32_e32 v4, v89, v191
	v_mul_f32_e32 v5, v89, v190
	v_fma_f32 v4, v4, v16, v24
	v_fmac_f32_e32 v25, v5, v17
	v_cvt_pk_bf16_f32 v2, v2, v3
	v_cvt_pk_bf16_f32 v3, v4, v25
	global_store_dwordx2 v[60:61], v[2:3], off offset:3584 sc1
	v_lshlrev_b32_e32 v60, 16, v58
	v_and_b32_e32 v61, 0xffff0000, v58
	v_lshlrev_b32_e32 v58, 16, v59
	v_and_b32_e32 v59, 0xffff0000, v59
	v_lshlrev_b32_e32 v13, 16, v2
	v_and_b32_e32 v113, 0xffff0000, v2
	v_mul_f32_e32 v2, v59, v59
	v_and_b32_e32 v23, 0xffff0000, v65
	v_and_b32_e32 v22, 0xffff0000, v64
	v_mul_f32_e32 v6, v61, v61
	v_lshlrev_b32_e32 v111, 16, v3
	v_and_b32_e32 v109, 0xffff0000, v3
	v_pk_fma_f32 v[2:3], v[58:59], v[58:59], v[2:3] op_sel_hi:[1,1,0]
	v_lshlrev_b32_e32 v24, 16, v64
	v_lshlrev_b32_e32 v25, 16, v65
	v_pk_mul_f32 v[4:5], v[22:23], v[22:23]
	v_pk_fma_f32 v[18:19], v[60:61], v[60:61], v[6:7] op_sel_hi:[1,1,0]
	v_pk_fma_f32 v[4:5], v[24:25], v[24:25], v[4:5]
	v_mov_b32_e32 v6, v18
	v_mov_b32_e32 v20, v2
	v_mov_b32_e32 v21, v7
	v_mul_f32_e32 v8, v103, v103
	v_pk_add_f32 v[2:3], v[18:19], v[2:3]
	v_pk_mul_f32 v[18:19], v[6:7], v[20:21]
	v_pk_add_f32 v[4:5], v[4:5], v[4:5] op_sel:[0,1] op_sel_hi:[1,0]
	v_and_b32_e32 v17, 0xffff0000, v26
	v_and_b32_e32 v15, 0xffff0000, v27
	v_mov_b32_e32 v3, v19
	v_mov_b32_e32 v5, v8
	v_lshlrev_b32_e32 v16, 16, v26
	v_lshlrev_b32_e32 v14, 16, v27
	v_pk_add_f32 v[2:3], v[2:3], v[4:5]
	v_mul_f32_e32 v4, v17, v17
	v_mul_f32_e32 v6, v15, v15
	v_lshlrev_b32_e32 v9, 16, v10
	v_and_b32_e32 v105, 0xffff0000, v10
	v_mul_f32_e32 v10, v102, v102
	v_mul_f32_e32 v12, v79, v79
	v_pk_fma_f32 v[4:5], v[16:17], v[16:17], v[4:5] op_sel_hi:[1,1,0]
	v_pk_fma_f32 v[18:19], v[14:15], v[14:15], v[6:7] op_sel_hi:[1,1,0]
	v_mov_b32_e32 v5, v10
	v_mov_b32_e32 v19, v12
	v_pk_add_f32 v[4:5], v[4:5], v[18:19]
	v_and_b32_e32 v87, 0xffff0000, v62
	v_and_b32_e32 v65, 0xffff0000, v63
	v_pk_add_f32 v[94:95], v[2:3], v[4:5]
	v_lshlrev_b32_e32 v86, 16, v62
	v_lshlrev_b32_e32 v64, 16, v63
	v_mul_f32_e32 v2, v65, v65
	v_mul_f32_e32 v6, v87, v87
; __device__ __forceinline__ void phase_rowwise(const Params& p, const float* xs32, const bf16_t* xs16, float* xd32, bf16_t* xd16, const bf16_t* y, const float* gpost, int modres,
;                                               bf16_t* hout, const float* gpre, int modh) {
;     ...
;             float ss[RB];
; #pragma unroll
;             for (int r = 0; r < RB; ++r) { ss[r] = 0.f;
; #pragma unroll
;                 for (int j = 0; j < 4; ++j) ss[r] += (xv[r][j][0] * xv[r][j][0] + xv[r][j][1] * xv[r][j][1]) + (xv[r][j][2] * xv[r][j][2] + xv[r][j][3] * xv[r][j][3]); }
; #pragma unroll
;             for (int o = 1; o < 64; o <<= 1)
; #pragma unroll
;                 for (int r = 0; r < RB; ++r) ss[r] += __shfl_xor(ss[r], o);
; #pragma unroll
;             for (int j = 0; j < 4; ++j) { const f32x4 sh = *(const f32x4*)(modb + modh + lane * 4 + 256 * j), scl = *(const f32x4*)(modb + modh + 1024 + lane * 4 + 256 * j), gp = *(const f32x4*)(gpre + lane * 4 + 256 * j);
;                 const f32x4 gs = gp * (scl + 1.f);
	v_pk_fma_f32 v[2:3], v[64:65], v[64:65], v[2:3] op_sel_hi:[1,1,0]
	v_pk_mul_f32 v[4:5], v[30:31], v[30:31]
	v_pk_fma_f32 v[26:27], v[86:87], v[86:87], v[6:7] op_sel_hi:[1,1,0]
	v_pk_fma_f32 v[4:5], v[32:33], v[32:33], v[4:5]
	v_lshlrev_b32_e32 v20, 16, v28
	v_and_b32_e32 v21, 0xffff0000, v28
	v_lshlrev_b32_e32 v18, 16, v29
	v_and_b32_e32 v19, 0xffff0000, v29
	v_mov_b32_e32 v8, v26
	v_mov_b32_e32 v28, v2
	v_mov_b32_e32 v29, v9
	v_mul_f32_e32 v10, v105, v105
	v_pk_add_f32 v[2:3], v[26:27], v[2:3]
	v_pk_mul_f32 v[26:27], v[8:9], v[28:29]
	v_pk_add_f32 v[4:5], v[4:5], v[4:5] op_sel:[0,1] op_sel_hi:[1,0]
	v_mov_b32_e32 v3, v27
	v_mov_b32_e32 v5, v10
	v_pk_add_f32 v[2:3], v[2:3], v[4:5]
	v_mul_f32_e32 v4, v21, v21
	v_mul_f32_e32 v6, v19, v19
	v_mul_f32_e32 v12, v104, v104
	v_mul_f32_e32 v40, v101, v101
	v_pk_fma_f32 v[4:5], v[20:21], v[20:21], v[4:5] op_sel_hi:[1,1,0]
	v_pk_fma_f32 v[26:27], v[18:19], v[18:19], v[6:7] op_sel_hi:[1,1,0]
	v_mov_b32_e32 v5, v12
	v_mov_b32_e32 v27, v40
	v_pk_add_f32 v[4:5], v[4:5], v[26:27]
	v_mul_f32_e32 v6, v53, v53
	v_pk_add_f32 v[96:97], v[2:3], v[4:5]
	v_mul_f32_e32 v2, v51, v51
	v_pk_fma_f32 v[2:3], v[50:51], v[50:51], v[2:3] op_sel_hi:[1,1,0]
	v_pk_mul_f32 v[4:5], v[42:43], v[42:43]
	v_pk_fma_f32 v[36:37], v[52:53], v[52:53], v[6:7] op_sel_hi:[1,1,0]
	v_pk_fma_f32 v[4:5], v[44:45], v[44:45], v[4:5]
	v_mov_b32_e32 v10, v36
	v_mov_b32_e32 v40, v2
	v_mov_b32_e32 v41, v11
	v_mul_f32_e32 v8, v108, v108
	v_pk_add_f32 v[2:3], v[36:37], v[2:3]
	v_pk_mul_f32 v[36:37], v[10:11], v[40:41]
	v_pk_add_f32 v[4:5], v[4:5], v[4:5] op_sel:[0,1] op_sel_hi:[1,0]
	v_and_b32_e32 v29, 0xffff0000, v48
	v_and_b32_e32 v27, 0xffff0000, v49
	v_mov_b32_e32 v3, v37
	v_mov_b32_e32 v5, v8
	v_lshlrev_b32_e32 v28, 16, v48
	v_lshlrev_b32_e32 v26, 16, v49
	v_pk_add_f32 v[2:3], v[2:3], v[4:5]
	v_mul_f32_e32 v4, v29, v29
	v_mul_f32_e32 v6, v27, v27
	v_mul_f32_e32 v12, v107, v107
	v_mul_f32_e32 v46, v106, v106
	v_pk_fma_f32 v[4:5], v[28:29], v[28:29], v[4:5] op_sel_hi:[1,1,0]
	v_pk_fma_f32 v[36:37], v[26:27], v[26:27], v[6:7] op_sel_hi:[1,1,0]
	v_mov_b32_e32 v5, v12
	v_mov_b32_e32 v37, v46
	v_pk_add_f32 v[4:5], v[4:5], v[36:37]
	v_and_b32_e32 v46, 0xffff0000, v34
	v_pk_add_f32 v[62:63], v[2:3], v[4:5]
	v_mul_f32_e32 v2, v55, v55
	v_mul_f32_e32 v6, v57, v57
	v_pk_fma_f32 v[2:3], v[54:55], v[54:55], v[2:3] op_sel_hi:[1,1,0]
	v_lshlrev_b32_e32 v49, 16, v35
	v_lshlrev_b32_e32 v48, 16, v34
	v_pk_mul_f32 v[4:5], v[46:47], v[46:47]
	v_lshlrev_b32_e32 v36, 16, v38
	v_and_b32_e32 v37, 0xffff0000, v38
	v_lshlrev_b32_e32 v34, 16, v39
	v_and_b32_e32 v35, 0xffff0000, v39
	v_pk_fma_f32 v[38:39], v[56:57], v[56:57], v[6:7] op_sel_hi:[1,1,0]
	v_pk_fma_f32 v[4:5], v[48:49], v[48:49], v[4:5]
	v_mov_b32_e32 v12, v38
	v_mov_b32_e32 v40, v2
	v_mov_b32_e32 v41, v13
	v_mul_f32_e32 v8, v113, v113
	v_pk_add_f32 v[2:3], v[38:39], v[2:3]
	v_pk_mul_f32 v[38:39], v[12:13], v[40:41]
	v_pk_add_f32 v[4:5], v[4:5], v[4:5] op_sel:[0,1] op_sel_hi:[1,0]
	v_mov_b32_e32 v3, v39
	v_mov_b32_e32 v5, v8
	v_pk_add_f32 v[2:3], v[2:3], v[4:5]
	v_mul_f32_e32 v4, v37, v37
	v_mul_f32_e32 v6, v35, v35
	v_mul_f32_e32 v10, v111, v111
	v_mul_f32_e32 v88, v109, v109
	v_pk_fma_f32 v[4:5], v[36:37], v[36:37], v[4:5] op_sel_hi:[1,1,0]
	v_pk_fma_f32 v[38:39], v[34:35], v[34:35], v[6:7] op_sel_hi:[1,1,0]
	v_mov_b32_e32 v5, v10
	v_mov_b32_e32 v39, v88
	v_lshl_add_u64 v[40:41], v[98:99], 0, s[0:1]
	s_mov_b64 s[0:1], 0x4000
	v_pk_add_f32 v[4:5], v[4:5], v[38:39]
	v_lshl_add_u64 v[38:39], v[98:99], 0, s[0:1]
	s_movk_i32 s0, 0x4000
	v_add_co_u32_e32 v90, vcc, s0, v98
	v_pk_add_f32 v[88:89], v[2:3], v[4:5]
	s_nop 0
	v_addc_co_u32_e32 v91, vcc, 0, v99, vcc
	global_load_dwordx4 v[2:5], v[118:119], off
	s_nop 0
	global_load_dwordx4 v[90:93], v[90:91], off
	s_nop 0
	global_load_dwordx4 v[114:117], v[68:69], off
	s_waitcnt vmcnt(1)
	v_pk_add_f32 v[92:93], v[92:93], 1.0 op_sel_hi:[1,0]
	v_pk_add_f32 v[98:99], v[90:91], 1.0 op_sel_hi:[1,0]
	s_waitcnt vmcnt(0)
	v_pk_mul_f32 v[90:91], v[116:117], v[92:93]
	v_pk_mul_f32 v[92:93], v[114:115], v[98:99]
	v_mov_b32_e32 v98, v96
	v_mov_b32_e32 v99, v94
	v_mov_b32_e32 v94, v97
	v_pk_add_f32 v[94:95], v[98:99], v[94:95]
	ds_bpermute_b32 v97, v179, v95
	ds_bpermute_b32 v96, v179, v94
	s_waitcnt lgkmcnt(0)
	v_pk_add_f32 v[94:95], v[94:95], v[96:97]
	ds_bpermute_b32 v97, v178, v95
	ds_bpermute_b32 v96, v178, v94
	s_waitcnt lgkmcnt(0)
	v_pk_add_f32 v[94:95], v[94:95], v[96:97]
	ds_bpermute_b32 v97, v139, v95
	ds_bpermute_b32 v96, v139, v94
	s_waitcnt lgkmcnt(0)
	v_pk_add_f32 v[94:95], v[94:95], v[96:97]
	ds_bpermute_b32 v97, v112, v95
	ds_bpermute_b32 v96, v112, v94
	s_waitcnt lgkmcnt(0)
	v_pk_add_f32 v[94:95], v[94:95], v[96:97]
	ds_bpermute_b32 v97, v110, v95
	ds_bpermute_b32 v96, v110, v94
	s_waitcnt lgkmcnt(0)
	v_pk_add_f32 v[94:95], v[94:95], v[96:97]
	ds_bpermute_b32 v97, v100, v95
	ds_bpermute_b32 v96, v100, v94
	s_waitcnt lgkmcnt(0)
; __device__ __forceinline__ unsigned pk2(float lo, float hi) { unsigned r; asm("v_cvt_pk_bf16_f32 %0, %1, %2" : "=v"(r) : "v"(lo), "v"(hi)); return r; }
; __device__ __forceinline__ void phase_rowwise(const Params& p, const float* xs32, const bf16_t* xs16, float* xd32, bf16_t* xd16, const bf16_t* y, const float* gpost, int modres,
;                                               bf16_t* hout, const float* gpre, int modh) {
;     ...
;             for (int o = 1; o < 64; o <<= 1)
; #pragma unroll
;                 for (int r = 0; r < RB; ++r) ss[r] += __shfl_xor(ss[r], o);
; #pragma unroll
;             for (int j = 0; j < 4; ++j) { const f32x4 sh = *(const f32x4*)(modb + modh + lane * 4 + 256 * j), scl = *(const f32x4*)(modb + modh + 1024 + lane * 4 + 256 * j), gp = *(const f32x4*)(gpre + lane * 4 + 256 * j);
;                 const f32x4 gs = gp * (scl + 1.f);
; #pragma unroll
;                 for (int r = 0; r < RB; ++r) { const float rstd = rsqrtf(ss[r] * (1.f / D) + EPS);
;                     u32x2 o; o.x = pk2(xv[r][j][0] * rstd * gs[0] + sh[0], xv[r][j][1] * rstd * gs[1] + sh[1]); o.y = pk2(xv[r][j][2] * rstd * gs[2] + sh[2], xv[r][j][3] * rstd * gs[3] + sh[3]);
;                     *(u32x2*)(hout + (row0 + r) * LDH + lane * 4 + 256 * j) = o; } }
	v_pk_add_f32 v[94:95], v[94:95], v[96:97]
	s_nop 0
	v_pk_fma_f32 v[94:95], v[94:95], s[12:13], v[84:85] op_sel_hi:[1,0,0]
	s_nop 0
	v_mul_f32_e32 v6, 0x4b800000, v95
	v_cmp_gt_f32_e64 s[0:1], s76, v95
	v_cmp_gt_f32_e32 vcc, s76, v94
	s_nop 0
	v_cndmask_b32_e64 v6, v95, v6, s[0:1]
	v_rsq_f32_e32 v6, v6
	s_nop 0
	v_mul_f32_e32 v8, 0x45800000, v6
	v_cndmask_b32_e64 v6, v6, v8, s[0:1]
	v_mul_f32_e32 v8, v6, v60
	v_fma_f32 v8, v92, v8, v2
	v_mul_f32_e32 v10, v6, v61
	v_fma_f32 v10, v93, v10, v3
	v_cvt_pk_bf16_f32 v60, v8, v10
	v_mul_f32_e32 v8, v6, v58
	v_fma_f32 v8, v90, v8, v4
	v_mul_f32_e32 v10, v6, v59
	v_fma_f32 v10, v91, v10, v5
	v_cvt_pk_bf16_f32 v61, v8, v10
	v_mul_f32_e32 v8, 0x4b800000, v94
	v_cndmask_b32_e32 v8, v94, v8, vcc
	v_rsq_f32_e32 v8, v8
	global_store_dwordx2 v[82:83], v[60:61], off sc1
	v_mul_f32_e32 v24, v6, v24
	v_mul_f32_e32 v22, v6, v22
	v_mul_f32_e32 v10, 0x45800000, v8
	v_cndmask_b32_e32 v8, v8, v10, vcc
	v_mul_f32_e32 v10, v8, v86
	v_mul_f32_e32 v12, v8, v87
	v_fma_f32 v10, v92, v10, v2
	v_fma_f32 v12, v93, v12, v3
	v_cvt_pk_bf16_f32 v58, v10, v12
	v_mul_f32_e32 v10, v8, v64
	v_mul_f32_e32 v12, v8, v65
	v_fma_f32 v10, v90, v10, v4
	v_fma_f32 v12, v91, v12, v5
	v_cvt_pk_bf16_f32 v59, v10, v12
	global_store_dwordx2 v[82:83], v[58:59], off offset:2176 sc1
	v_mov_b32_e32 v58, v88
	v_mov_b32_e32 v59, v62
	v_mov_b32_e32 v62, v89
	v_pk_add_f32 v[58:59], v[58:59], v[62:63]
	ds_bpermute_b32 v61, v179, v59
	ds_bpermute_b32 v60, v179, v58
	v_mul_f32_e32 v23, v6, v23
	v_mul_f32_e32 v16, v6, v16
	v_mul_f32_e32 v17, v6, v17
	v_mul_f32_e32 v14, v6, v14
	s_waitcnt lgkmcnt(0)
	v_pk_add_f32 v[58:59], v[58:59], v[60:61]
	ds_bpermute_b32 v61, v178, v59
	ds_bpermute_b32 v60, v178, v58
	v_mul_f32_e32 v15, v6, v15
	v_mul_f32_e32 v7, v6, v7
	s_waitcnt lgkmcnt(0)
	v_pk_add_f32 v[58:59], v[58:59], v[60:61]
	ds_bpermute_b32 v61, v139, v59
	ds_bpermute_b32 v60, v139, v58
	s_waitcnt lgkmcnt(0)
	v_pk_add_f32 v[58:59], v[58:59], v[60:61]
	ds_bpermute_b32 v61, v112, v59
	ds_bpermute_b32 v60, v112, v58
	s_waitcnt lgkmcnt(0)
	v_pk_add_f32 v[58:59], v[58:59], v[60:61]
	ds_bpermute_b32 v61, v110, v59
	ds_bpermute_b32 v60, v110, v58
	s_waitcnt lgkmcnt(0)
	v_pk_add_f32 v[58:59], v[58:59], v[60:61]
	ds_bpermute_b32 v61, v100, v59
	ds_bpermute_b32 v60, v100, v58
	s_waitcnt lgkmcnt(0)
	v_pk_add_f32 v[58:59], v[58:59], v[60:61]
	s_nop 0
	v_pk_fma_f32 v[58:59], v[58:59], s[12:13], v[84:85] op_sel_hi:[1,0,0]
	s_nop 0
	v_mul_f32_e32 v10, 0x4b800000, v59
	v_cmp_gt_f32_e64 s[0:1], s76, v59
	v_cmp_gt_f32_e32 vcc, s76, v58
	s_nop 0
	v_cndmask_b32_e64 v10, v59, v10, s[0:1]
	v_rsq_f32_e32 v10, v10
	s_nop 0
	v_mul_f32_e32 v12, 0x45800000, v10
	v_cndmask_b32_e64 v10, v10, v12, s[0:1]
	v_mul_f32_e32 v12, v10, v52
	v_mul_f32_e32 v52, v10, v53
	v_fma_f32 v12, v92, v12, v2
	v_fma_f32 v52, v93, v52, v3
	v_cvt_pk_bf16_f32 v52, v12, v52
	v_mul_f32_e32 v12, v10, v50
	v_fma_f32 v12, v90, v12, v4
	v_mul_f32_e32 v50, v10, v51
	v_fma_f32 v50, v91, v50, v5
	v_cvt_pk_bf16_f32 v53, v12, v50
	v_mul_f32_e32 v12, 0x4b800000, v58
	v_cndmask_b32_e32 v12, v58, v12, vcc
	v_rsq_f32_e32 v12, v12
	global_store_dwordx2 v[80:81], v[52:53], off offset:256 sc1
	v_mul_f32_e32 v50, 0x45800000, v12
	v_cndmask_b32_e32 v12, v12, v50, vcc
	v_mul_f32_e32 v50, v12, v56
	v_fma_f32 v2, v92, v50, v2
	v_mul_f32_e32 v50, v12, v57
	v_fma_f32 v3, v93, v50, v3
	v_cvt_pk_bf16_f32 v2, v2, v3
	v_mul_f32_e32 v3, v12, v54
	v_fma_f32 v3, v90, v3, v4
	v_mul_f32_e32 v4, v12, v55
	v_fmac_f32_e32 v5, v91, v4
	v_cvt_pk_bf16_f32 v3, v3, v5
	global_store_dwordx2 v[80:81], v[2:3], off offset:2432 sc1
	global_load_dwordx4 v[2:5], v[40:41], off offset:1024
	s_nop 0
	global_load_dwordx4 v[50:53], v[38:39], off offset:1024
	global_load_dwordx4 v[54:57], v[68:69], off offset:1024
	s_waitcnt vmcnt(1)
	v_pk_add_f32 v[50:51], v[50:51], 1.0 op_sel_hi:[1,0]
	v_pk_add_f32 v[52:53], v[52:53], 1.0 op_sel_hi:[1,0]
	s_waitcnt vmcnt(0)
; __device__ __forceinline__ unsigned pk2(float lo, float hi) { unsigned r; asm("v_cvt_pk_bf16_f32 %0, %1, %2" : "=v"(r) : "v"(lo), "v"(hi)); return r; }
; __device__ __forceinline__ void phase_rowwise(const Params& p, const float* xs32, const bf16_t* xs16, float* xd32, bf16_t* xd16, const bf16_t* y, const float* gpost, int modres,
;                                               bf16_t* hout, const float* gpre, int modh) {
;     ...
;             for (int j = 0; j < 4; ++j) { const f32x4 sh = *(const f32x4*)(modb + modh + lane * 4 + 256 * j), scl = *(const f32x4*)(modb + modh + 1024 + lane * 4 + 256 * j), gp = *(const f32x4*)(gpre + lane * 4 + 256 * j);
;                 const f32x4 gs = gp * (scl + 1.f);
; #pragma unroll
;                 for (int r = 0; r < RB; ++r) { const float rstd = rsqrtf(ss[r] * (1.f / D) + EPS);
;                     u32x2 o; o.x = pk2(xv[r][j][0] * rstd * gs[0] + sh[0], xv[r][j][1] * rstd * gs[1] + sh[1]); o.y = pk2(xv[r][j][2] * rstd * gs[2] + sh[2], xv[r][j][3] * rstd * gs[3] + sh[3]);
;                     *(u32x2*)(hout + (row0 + r) * LDH + lane * 4 + 256 * j) = o; } }
	v_pk_mul_f32 v[50:51], v[54:55], v[50:51]
	v_pk_mul_f32 v[52:53], v[56:57], v[52:53]
	v_fma_f32 v24, v24, v50, v2
	v_fma_f32 v22, v22, v51, v3
	v_cvt_pk_bf16_f32 v22, v24, v22
	v_mul_f32_e32 v24, v6, v25
	v_fma_f32 v23, v23, v53, v5
	v_fma_f32 v24, v24, v52, v4
	v_cvt_pk_bf16_f32 v23, v24, v23
	global_store_dwordx2 v[82:83], v[22:23], off offset:512 sc1
	v_mul_f32_e32 v22, v8, v32
	v_mul_f32_e32 v23, v8, v30
	v_fma_f32 v22, v22, v50, v2
	v_fma_f32 v23, v23, v51, v3
	v_cvt_pk_bf16_f32 v22, v22, v23
	v_mul_f32_e32 v23, v8, v33
	v_fma_f32 v23, v23, v52, v4
	v_mul_f32_e32 v24, v8, v31
	v_fma_f32 v24, v24, v53, v5
	v_cvt_pk_bf16_f32 v23, v23, v24
	global_store_dwordx2 v[82:83], v[22:23], off offset:2688 sc1
	v_mul_f32_e32 v22, v10, v44
	v_mul_f32_e32 v23, v10, v42
	v_fma_f32 v22, v22, v50, v2
	v_fma_f32 v23, v23, v51, v3
	v_cvt_pk_bf16_f32 v22, v22, v23
	v_mul_f32_e32 v23, v10, v45
	v_fma_f32 v23, v23, v52, v4
	v_mul_f32_e32 v24, v10, v43
	v_fma_f32 v24, v24, v53, v5
	v_cvt_pk_bf16_f32 v23, v23, v24
	global_store_dwordx2 v[80:81], v[22:23], off offset:768 sc1
	v_mul_f32_e32 v22, v12, v48
	v_fma_f32 v2, v22, v50, v2
	v_mul_f32_e32 v22, v12, v46
	v_fma_f32 v3, v22, v51, v3
	v_cvt_pk_bf16_f32 v2, v2, v3
	v_mul_f32_e32 v3, v12, v49
	v_fma_f32 v3, v3, v52, v4
	v_mul_f32_e32 v4, v12, v47
	v_fmac_f32_e32 v5, v4, v53
	v_cvt_pk_bf16_f32 v3, v3, v5
	global_store_dwordx2 v[80:81], v[2:3], off offset:2944 sc1
	global_load_dwordx4 v[2:5], v[40:41], off offset:2048
	s_nop 0
	global_load_dwordx4 v[22:25], v[38:39], off offset:2048
	global_load_dwordx4 v[30:33], v[68:69], off offset:2048
	s_waitcnt vmcnt(1)
	v_pk_add_f32 v[24:25], v[24:25], 1.0 op_sel_hi:[1,0]
	v_pk_add_f32 v[22:23], v[22:23], 1.0 op_sel_hi:[1,0]
	s_waitcnt vmcnt(0)
	v_pk_mul_f32 v[24:25], v[32:33], v[24:25]
	v_pk_mul_f32 v[22:23], v[30:31], v[22:23]
	v_fma_f32 v14, v14, v24, v4
	v_fma_f32 v16, v16, v22, v2
	v_fma_f32 v17, v17, v23, v3
	v_fma_f32 v15, v15, v25, v5
	v_cvt_pk_bf16_f32 v16, v16, v17
	v_cvt_pk_bf16_f32 v17, v14, v15
	v_mul_f32_e32 v14, v8, v20
	v_mul_f32_e32 v15, v8, v21
	v_fma_f32 v14, v14, v22, v2
	v_fma_f32 v15, v15, v23, v3
	v_cvt_pk_bf16_f32 v14, v14, v15
	v_mul_f32_e32 v15, v8, v18
	global_store_dwordx2 v[82:83], v[16:17], off offset:1024 sc1
	v_fma_f32 v15, v15, v24, v4
	v_mul_f32_e32 v16, v8, v19
	v_fma_f32 v16, v16, v25, v5
	v_cvt_pk_bf16_f32 v15, v15, v16
	global_store_dwordx2 v[82:83], v[14:15], off offset:3200 sc1
	v_mul_f32_e32 v14, v10, v28
	v_mul_f32_e32 v15, v10, v29
	v_fma_f32 v14, v14, v22, v2
	v_fma_f32 v15, v15, v23, v3
	v_cvt_pk_bf16_f32 v14, v14, v15
	v_mul_f32_e32 v15, v10, v26
	v_fma_f32 v15, v15, v24, v4
	v_mul_f32_e32 v16, v10, v27
	v_fma_f32 v16, v16, v25, v5
	v_cvt_pk_bf16_f32 v15, v15, v16
	global_store_dwordx2 v[80:81], v[14:15], off offset:1280 sc1
	v_mul_f32_e32 v14, v12, v36
	v_fma_f32 v2, v14, v22, v2
	v_mul_f32_e32 v14, v12, v37
	v_fma_f32 v3, v14, v23, v3
	v_cvt_pk_bf16_f32 v2, v2, v3
	v_mul_f32_e32 v3, v12, v34
	v_fma_f32 v3, v3, v24, v4
	v_mul_f32_e32 v4, v12, v35
	v_fmac_f32_e32 v5, v4, v25
	v_cvt_pk_bf16_f32 v3, v3, v5
	global_store_dwordx2 v[80:81], v[2:3], off offset:3456 sc1
	global_load_dwordx4 v[2:5], v[40:41], off offset:3072
	s_nop 0
	global_load_dwordx4 v[14:17], v[38:39], off offset:3072
	global_load_dwordx4 v[18:21], v[68:69], off offset:3072
	s_waitcnt vmcnt(1)
	v_pk_add_f32 v[14:15], v[14:15], 1.0 op_sel_hi:[1,0]
	s_waitcnt vmcnt(0)
	v_pk_mul_f32 v[14:15], v[18:19], v[14:15]
	v_mul_f32_e32 v18, v6, v103
	v_pk_add_f32 v[16:17], v[16:17], 1.0 op_sel_hi:[1,0]
	v_fma_f32 v7, v7, v14, v2
	v_fma_f32 v18, v18, v15, v3
	v_pk_mul_f32 v[16:17], v[20:21], v[16:17]
	v_cvt_pk_bf16_f32 v18, v7, v18
	v_mul_f32_e32 v7, v6, v102
	v_mul_f32_e32 v6, v6, v79
	v_fma_f32 v7, v7, v16, v4
	v_fma_f32 v6, v6, v17, v5
	v_cvt_pk_bf16_f32 v19, v7, v6
	v_mul_f32_e32 v6, v8, v9
	v_mul_f32_e32 v7, v8, v105
	v_fma_f32 v6, v6, v14, v2
	v_fma_f32 v7, v7, v15, v3
	v_cvt_pk_bf16_f32 v6, v6, v7
	v_mul_f32_e32 v7, v8, v104
	v_fma_f32 v7, v7, v16, v4
	v_mul_f32_e32 v8, v8, v101
	v_fma_f32 v8, v8, v17, v5
	v_cvt_pk_bf16_f32 v7, v7, v8
	global_store_dwordx2 v[82:83], v[6:7], off offset:3712 sc1
	v_mul_f32_e32 v6, v10, v11
	v_mul_f32_e32 v7, v10, v108
	v_fma_f32 v6, v6, v14, v2
	v_fma_f32 v7, v7, v15, v3
	v_cvt_pk_bf16_f32 v6, v6, v7
	v_mul_f32_e32 v7, v10, v107
	v_fma_f32 v7, v7, v16, v4
	v_mul_f32_e32 v8, v10, v106
	v_fma_f32 v8, v8, v17, v5
	v_cvt_pk_bf16_f32 v7, v7, v8
	global_store_dwordx2 v[80:81], v[6:7], off offset:1792 sc1
	v_mul_f32_e32 v6, v12, v13
	v_fma_f32 v2, v6, v14, v2
	v_mul_f32_e32 v6, v12, v113
	v_fma_f32 v3, v6, v15, v3
	v_cvt_pk_bf16_f32 v2, v2, v3
	v_mul_f32_e32 v3, v12, v111
	v_fma_f32 v3, v3, v16, v4
	v_mul_f32_e32 v4, v12, v109
	global_store_dwordx2 v[82:83], v[18:19], off offset:1536 sc1
	v_fmac_f32_e32 v5, v4, v17
	v_cvt_pk_bf16_f32 v3, v3, v5
	global_store_dwordx2 v[80:81], v[2:3], off offset:3968 sc1
	s_branch .LBB0_912

; __device__ __forceinline__ unsigned pk2(float lo, float hi) { unsigned r; asm("v_cvt_pk_bf16_f32 %0, %1, %2" : "=v"(r) : "v"(lo), "v"(hi)); return r; }
; __device__ __forceinline__ void cvt_store(const CvtJob& jb, int tid, const float* scr) {
;     const int nkt = jb.K / 64, nb = jb.tile / nkt, kb = jb.tile % nkt, n0 = nb * 64, k0 = kb * 64;
;     const int nl = tid >> 3, kc = tid & 7; const float* sp = scr + (kc * 8) * 65 + nl;
;     u32x4 o; o.x = pk2(sp[0], sp[65]); o.y = pk2(sp[2 * 65], sp[3 * 65]); o.z = pk2(sp[4 * 65], sp[5 * 65]); o.w = pk2(sp[6 * 65], sp[7 * 65]);
;     *(u32x4*)(jb.Wt + (size_t)(n0 + nl) * jb.ldw + k0 + kc * 8) = o;
; }
; __device__ __forceinline__ void convert_layer_weights(const Params& p, uchar* sm, int i, bool mixer, bool ffn) {
;     ...
;     for (; it < n_all; it += gridDim.x) {
;         const CvtJob jb = job(it);
;         cvt_to_lds(tid, cur, scr);
;         if (it + (int)gridDim.x < n_all) cvt_load(job(it + gridDim.x), tid, nxt);
;         __syncthreads();
;         cvt_store(jb, tid, scr);
;         __syncthreads();
.LBB0_942:
	s_abs_i32 s22, s40
	v_cvt_f32_u32_e32 v10, s22
	s_sub_i32 s23, 0, s22
	s_abs_i32 s1, s38
	s_xor_b32 s0, s38, s40
	v_rcp_iflag_f32_e32 v10, v10
	s_ashr_i32 s0, s0, 31
	s_waitcnt lgkmcnt(0)
	s_barrier
	v_mul_f32_e32 v10, 0x4f7ffffe, v10
	v_cvt_u32_f32_e32 v10, v10
	ds_read2_b32 v[12:13], v24 offset0:130 offset1:195
	v_add_u32_e32 v17, 0x400, v24
	v_readfirstlane_b32 s24, v10
	s_mul_i32 s23, s23, s24
	s_mul_hi_u32 s23, s24, s23
	s_add_i32 s24, s24, s23
	s_mul_hi_u32 s23, s1, s24
	s_mul_i32 s24, s23, s22
	s_sub_i32 s1, s1, s24
	s_add_i32 s24, s23, 1
	s_sub_i32 s25, s1, s22
	s_cmp_ge_u32 s1, s22
	s_cselect_b32 s23, s24, s23
	s_cselect_b32 s1, s25, s1
	s_add_i32 s24, s23, 1
	s_cmp_ge_u32 s1, s22
	s_cselect_b32 s1, s24, s23
	s_xor_b32 s1, s1, s0
	s_sub_i32 s1, s1, s0
	ds_read2_b32 v[10:11], v24 offset1:65
	s_waitcnt lgkmcnt(0)
	v_cvt_pk_bf16_f32 v10, v10, v11
	v_cvt_pk_bf16_f32 v11, v12, v13
	ds_read2_b32 v[12:13], v17 offset0:4 offset1:69
	ds_read2_b32 v[18:19], v17 offset0:134 offset1:199
	v_lshl_add_u32 v17, s1, 6, v23
	s_mul_i32 s0, s1, s40
	s_waitcnt lgkmcnt(1)
	v_cvt_pk_bf16_f32 v12, v12, v13
	s_waitcnt lgkmcnt(0)
	v_cvt_pk_bf16_f32 v13, v18, v19
	v_ashrrev_i32_e32 v18, 31, v17
	s_sub_i32 s0, s38, s0
	v_mul_lo_u32 v20, s18, v18
	v_mul_lo_u32 v21, s19, v17
	v_mad_u64_u32 v[18:19], s[18:19], s18, v17, 0
	s_lshl_b32 s0, s0, 6
	v_add3_u32 v19, v19, v20, v21
	v_lshl_add_u64 v[18:19], v[18:19], 1, s[16:17]
	s_ashr_i32 s1, s0, 31
	v_lshl_add_u64 v[18:19], s[0:1], 1, v[18:19]
	v_mov_b32_e32 v17, v0
	v_lshl_add_u64 v[18:19], v[18:19], 0, v[16:17]
	global_store_dwordx4 v[18:19], v[10:13], off sc1
	s_andn2_b64 vcc, exec, s[20:21]
	s_mov_b32 s28, s39
	s_barrier
	s_cbranch_vccz .LBB0_971

; __device__ __forceinline__ float bflo(unsigned u) { return __uint_as_float(u << 16); }
; __device__ __forceinline__ float bfhi(unsigned u) { return __uint_as_float(u & 0xffff0000u); }
; __device__ __forceinline__ void phase_rowwise(const Params& p, const float* xs32, const bf16_t* xs16, float* xd32, bf16_t* xd16, const bf16_t* y, const float* gpost, int modres,
;                                               bf16_t* hout, const float* gpre, int modh) {
;     ...
;         if (y) {
;             u32x2 yp[RB][4];
; #pragma unroll
;             for (int r = 0; r < RB; ++r)
; #pragma unroll
;                 for (int j = 0; j < 4; ++j) yp[r][j] = *(const u32x2*)(y + (row0 + r) * LDH + lane * 4 + 256 * j);
;             float ss[RB];
; #pragma unroll
;             for (int r = 0; r < RB; ++r) { ss[r] = 0.f;
; #pragma unroll
;                 for (int j = 0; j < 4; ++j) { const float a = bflo(yp[r][j].x), b = bfhi(yp[r][j].x), c = bflo(yp[r][j].y), d = bfhi(yp[r][j].y); ss[r] += (a * a + b * b) + (c * c + d * d); } }
.LBB0_1215:
	v_lshl_add_u64 v[12:13], v[6:7], 0, v[4:5]
	v_add_co_u32_e32 v14, vcc, 0x1241c000, v12
	v_readlane_b32 s0, v254, 56
	s_nop 0
	v_addc_co_u32_e32 v15, vcc, 0, v13, vcc
	global_load_dwordx2 v[16:17], v[14:15], off
	global_load_dwordx2 v[18:19], v[14:15], off offset:512
	global_load_dwordx2 v[20:21], v[14:15], off offset:1024
	global_load_dwordx2 v[22:23], v[14:15], off offset:1536
	global_load_dwordx2 v[32:33], v[14:15], off offset:2176
	global_load_dwordx2 v[34:35], v[14:15], off offset:2688
	global_load_dwordx2 v[36:37], v[14:15], off offset:3200
	global_load_dwordx2 v[38:39], v[14:15], off offset:3712
	v_add_co_u32_e32 v12, vcc, 0x1241d000, v12
	v_readlane_b32 s1, v254, 57
	s_nop 0
	v_addc_co_u32_e32 v13, vcc, 0, v13, vcc
	global_load_dwordx2 v[40:41], v[12:13], off offset:256
	global_load_dwordx2 v[42:43], v[12:13], off offset:768
	global_load_dwordx2 v[60:61], v[12:13], off offset:1280
	global_load_dwordx2 v[62:63], v[12:13], off offset:1792
	global_load_dwordx2 v[80:81], v[12:13], off offset:2432
	global_load_dwordx2 v[88:89], v[12:13], off offset:2944
	global_load_dwordx2 v[90:91], v[12:13], off offset:3456
	global_load_dwordx2 v[92:93], v[12:13], off offset:3968
	s_andn2_b64 vcc, exec, s[0:1]
	s_waitcnt vmcnt(15)
	v_lshlrev_b32_e32 v68, 16, v16
	v_and_b32_e32 v73, 0xffff0000, v16
	v_lshlrev_b32_e32 v70, 16, v17
	v_and_b32_e32 v75, 0xffff0000, v17
	s_waitcnt vmcnt(11)
	v_and_b32_e32 v69, 0xffff0000, v32
	v_and_b32_e32 v71, 0xffff0000, v33
	v_mov_b32_e32 v72, v69
	v_mov_b32_e32 v74, v71
	v_lshlrev_b32_e32 v30, 16, v20
	v_and_b32_e32 v25, 0xffff0000, v20
	v_lshlrev_b32_e32 v14, 16, v22
	v_and_b32_e32 v17, 0xffff0000, v22
	v_lshlrev_b32_e32 v76, 16, v32
	v_lshlrev_b32_e32 v78, 16, v33
	s_waitcnt vmcnt(10)
	v_lshlrev_b32_e32 v58, 16, v34
	v_and_b32_e32 v45, 0xffff0000, v34
	v_and_b32_e32 v49, 0xffff0000, v35
	s_waitcnt vmcnt(9)
	v_lshlrev_b32_e32 v34, 16, v36
	v_and_b32_e32 v27, 0xffff0000, v36
	v_lshlrev_b32_e32 v32, 16, v37
	v_and_b32_e32 v31, 0xffff0000, v37
	s_waitcnt vmcnt(8)
	v_lshlrev_b32_e32 v22, 16, v38
	v_and_b32_e32 v13, 0xffff0000, v38
	v_lshlrev_b32_e32 v20, 16, v39
	v_and_b32_e32 v15, 0xffff0000, v39
	v_mov_b32_e32 v77, v68
	v_mov_b32_e32 v79, v70
	v_pk_mul_f32 v[36:37], v[72:73], v[72:73]
	v_pk_mul_f32 v[38:39], v[74:75], v[74:75]
	v_lshlrev_b32_e32 v48, 16, v18
	v_and_b32_e32 v47, 0xffff0000, v18
	v_lshlrev_b32_e32 v44, 16, v19
	v_and_b32_e32 v51, 0xffff0000, v19
	v_mov_b32_e32 v46, v45
	v_mov_b32_e32 v50, v49
	v_pk_fma_f32 v[36:37], v[76:77], v[76:77], v[36:37]
	v_pk_fma_f32 v[38:39], v[78:79], v[78:79], v[38:39]
	s_waitcnt vmcnt(3)
	v_and_b32_e32 v77, 0xffff0000, v80
	v_and_b32_e32 v79, 0xffff0000, v81
	v_lshlrev_b32_e32 v26, 16, v21
	v_and_b32_e32 v29, 0xffff0000, v21
	v_lshlrev_b32_e32 v56, 16, v35
	v_mov_b32_e32 v59, v48
	v_mov_b32_e32 v57, v44
	v_mov_b32_e32 v28, v31
	v_pk_mul_f32 v[64:65], v[46:47], v[46:47]
	v_pk_mul_f32 v[66:67], v[50:51], v[50:51]
	v_lshlrev_b32_e32 v98, 16, v40
	v_and_b32_e32 v105, 0xffff0000, v40
	v_lshlrev_b32_e32 v94, 16, v41
	v_and_b32_e32 v115, 0xffff0000, v41
	v_mov_b32_e32 v104, v77
	v_mov_b32_e32 v114, v79
	v_mov_b32_e32 v24, v27
	v_mov_b32_e32 v33, v26
	v_pk_mul_f32 v[84:85], v[28:29], v[28:29]
	v_pk_fma_f32 v[64:65], v[58:59], v[58:59], v[64:65]
	v_pk_fma_f32 v[66:67], v[56:57], v[56:57], v[66:67]
	v_pk_add_f32 v[110:111], v[36:37], v[38:39]
	v_lshlrev_b32_e32 v102, 16, v80
	v_lshlrev_b32_e32 v100, 16, v81
	v_mov_b32_e32 v103, v98
	v_pk_mul_f32 v[36:37], v[104:105], v[104:105]
	v_mov_b32_e32 v101, v94
	v_pk_mul_f32 v[40:41], v[114:115], v[114:115]
	s_waitcnt vmcnt(2)
	v_and_b32_e32 v57, 0xffff0000, v88
	v_and_b32_e32 v59, 0xffff0000, v89
	v_mov_b32_e32 v35, v30
	v_pk_mul_f32 v[82:83], v[24:25], v[24:25]
	v_pk_fma_f32 v[108:109], v[32:33], v[32:33], v[84:85]
	v_lshlrev_b32_e32 v74, 16, v42
	v_and_b32_e32 v85, 0xffff0000, v42
	v_lshlrev_b32_e32 v72, 16, v43
	v_and_b32_e32 v87, 0xffff0000, v43
	v_pk_fma_f32 v[36:37], v[102:103], v[102:103], v[36:37]
	v_pk_fma_f32 v[40:41], v[100:101], v[100:101], v[40:41]
	v_mov_b32_e32 v84, v57
	v_mov_b32_e32 v86, v59
	v_pk_fma_f32 v[106:107], v[34:35], v[34:35], v[82:83]
	v_pk_add_f32 v[118:119], v[36:37], v[40:41]
	v_lshlrev_b32_e32 v82, 16, v88
	v_lshlrev_b32_e32 v80, 16, v89
	v_mov_b32_e32 v83, v74
	v_pk_mul_f32 v[36:37], v[84:85], v[84:85]
	v_mov_b32_e32 v81, v72
	v_pk_mul_f32 v[40:41], v[86:87], v[86:87]
	s_waitcnt vmcnt(1)
	v_and_b32_e32 v33, 0xffff0000, v90
	v_pk_add_f32 v[112:113], v[64:65], v[66:67]
	v_lshlrev_b32_e32 v50, 16, v60
	v_and_b32_e32 v65, 0xffff0000, v60
	v_pk_fma_f32 v[36:37], v[82:83], v[82:83], v[36:37]
	v_pk_fma_f32 v[40:41], v[80:81], v[80:81], v[40:41]
	v_and_b32_e32 v35, 0xffff0000, v91
	v_mov_b32_e32 v64, v33
	v_lshlrev_b32_e32 v46, 16, v61
	v_and_b32_e32 v67, 0xffff0000, v61
	v_lshlrev_b32_e32 v28, 16, v62
	v_and_b32_e32 v39, 0xffff0000, v62
	v_lshlrev_b32_e32 v24, 16, v63
	v_and_b32_e32 v43, 0xffff0000, v63
	v_pk_add_f32 v[88:89], v[36:37], v[40:41]
	v_lshlrev_b32_e32 v62, 16, v90
	v_mov_b32_e32 v63, v50
	v_pk_mul_f32 v[36:37], v[64:65], v[64:65]
	v_mov_b32_e32 v66, v35
	v_lshlrev_b32_e32 v60, 16, v91
	v_pk_fma_f32 v[90:91], v[62:63], v[62:63], v[36:37]
	v_mov_b32_e32 v61, v46
	v_pk_mul_f32 v[36:37], v[66:67], v[66:67]
	s_waitcnt vmcnt(0)
; __device__ __forceinline__ float bflo(unsigned u) { return __uint_as_float(u << 16); }
; __device__ __forceinline__ float bfhi(unsigned u) { return __uint_as_float(u & 0xffff0000u); }
; __device__ __forceinline__ void phase_rowwise(const Params& p, const float* xs32, const bf16_t* xs16, float* xd32, bf16_t* xd16, const bf16_t* y, const float* gpost, int modres,
;                                               bf16_t* hout, const float* gpre, int modh) {
;     ...
;         } else {
; #pragma unroll
;             for (int r = 0; r < RB; ++r)
; #pragma unroll
;                 for (int j = 0; j < 4; ++j) { const u32x2 t = *(const u32x2*)(xs16 + (row0 + r) * D + lane * 4 + 256 * j);
;                     xv[r][j][0] = bflo(t.x); xv[r][j][1] = bfhi(t.x); xv[r][j][2] = bflo(t.y); xv[r][j][3] = bfhi(t.y); }
;         }
;         if (y) {
;             u32x2 yp[RB][4];
; #pragma unroll
;             for (int r = 0; r < RB; ++r)
; #pragma unroll
;                 for (int j = 0; j < 4; ++j) yp[r][j] = *(const u32x2*)(y + (row0 + r) * LDH + lane * 4 + 256 * j);
;             float ss[RB];
; #pragma unroll
;             for (int r = 0; r < RB; ++r) { ss[r] = 0.f;
; #pragma unroll
;                 for (int j = 0; j < 4; ++j) { const float a = bflo(yp[r][j].x), b = bfhi(yp[r][j].x), c = bflo(yp[r][j].y), d = bfhi(yp[r][j].y); ss[r] += (a * a + b * b) + (c * c + d * d); } }
; #pragma unroll
;             for (int o = 1; o < 64; o <<= 1)
; #pragma unroll
;                 for (int r = 0; r < RB; ++r) ss[r] += __shfl_xor(ss[r], o);
; #pragma unroll
;             for (int j = 0; j < 4; ++j) { const f32x4 gt = *(const f32x4*)(modb + modres + lane * 4 + 256 * j), gp = *(const f32x4*)(gpost + lane * 4 + 256 * j);
;                 const f32x4 gg = gt * gp;
; #pragma unroll
;                 for (int r = 0; r < RB; ++r) { const float rstd = rsqrtf(ss[r] * (1.f / D) + EPS);
	v_and_b32_e32 v53, 0xffff0000, v92
	v_and_b32_e32 v55, 0xffff0000, v93
	v_lshlrev_b32_e32 v12, 16, v23
	v_and_b32_e32 v19, 0xffff0000, v23
	v_mov_b32_e32 v16, v13
	v_mov_b32_e32 v18, v15
	v_pk_fma_f32 v[120:121], v[60:61], v[60:61], v[36:37]
	v_mov_b32_e32 v38, v53
	v_mov_b32_e32 v42, v55
	v_mov_b32_e32 v23, v14
	v_pk_mul_f32 v[96:97], v[16:17], v[16:17]
	v_mov_b32_e32 v21, v12
	v_pk_mul_f32 v[116:117], v[18:19], v[18:19]
	v_lshlrev_b32_e32 v40, 16, v92
	v_lshlrev_b32_e32 v36, 16, v93
	v_mov_b32_e32 v41, v28
	v_pk_mul_f32 v[92:93], v[38:39], v[38:39]
	v_mov_b32_e32 v37, v24
	v_pk_mul_f32 v[122:123], v[42:43], v[42:43]
	v_pk_add_f32 v[88:89], v[118:119], v[88:89]
	v_pk_add_f32 v[90:91], v[90:91], v[120:121]
	v_pk_add_f32 v[110:111], v[110:111], v[112:113]
	v_pk_add_f32 v[106:107], v[106:107], v[108:109]
	v_pk_fma_f32 v[96:97], v[22:23], v[22:23], v[96:97]
	v_pk_fma_f32 v[108:109], v[20:21], v[20:21], v[116:117]
	v_pk_add_f32 v[88:89], v[88:89], v[90:91]
	v_pk_fma_f32 v[90:91], v[40:41], v[40:41], v[92:93]
	v_pk_fma_f32 v[92:93], v[36:37], v[36:37], v[122:123]
	v_pk_add_f32 v[106:107], v[110:111], v[106:107]
	v_pk_add_f32 v[96:97], v[96:97], v[108:109]
	v_pk_add_f32 v[90:91], v[90:91], v[92:93]
	v_pk_add_f32 v[96:97], v[106:107], v[96:97]
	v_pk_add_f32 v[88:89], v[88:89], v[90:91]
	ds_bpermute_b32 v107, v54, v97
	ds_bpermute_b32 v106, v54, v96
	ds_bpermute_b32 v91, v54, v89
	ds_bpermute_b32 v90, v54, v88
	s_waitcnt lgkmcnt(2)
	v_pk_add_f32 v[92:93], v[96:97], v[106:107]
	ds_bpermute_b32 v97, v130, v93
	s_waitcnt lgkmcnt(1)
	v_pk_add_f32 v[88:89], v[88:89], v[90:91]
	ds_bpermute_b32 v96, v130, v92
	ds_bpermute_b32 v91, v130, v89
	ds_bpermute_b32 v90, v130, v88
	s_waitcnt lgkmcnt(2)
	v_pk_add_f32 v[92:93], v[92:93], v[96:97]
	ds_bpermute_b32 v97, v131, v93
	s_waitcnt lgkmcnt(1)
	v_pk_add_f32 v[88:89], v[88:89], v[90:91]
	ds_bpermute_b32 v96, v131, v92
	ds_bpermute_b32 v91, v131, v89
	ds_bpermute_b32 v90, v131, v88
	s_waitcnt lgkmcnt(2)
	v_pk_add_f32 v[92:93], v[92:93], v[96:97]
	ds_bpermute_b32 v97, v132, v93
	s_waitcnt lgkmcnt(1)
	v_pk_add_f32 v[88:89], v[88:89], v[90:91]
	ds_bpermute_b32 v96, v132, v92
	ds_bpermute_b32 v91, v132, v89
	ds_bpermute_b32 v90, v132, v88
	s_waitcnt lgkmcnt(2)
	v_pk_add_f32 v[92:93], v[92:93], v[96:97]
	ds_bpermute_b32 v97, v133, v93
	s_waitcnt lgkmcnt(1)
	v_pk_add_f32 v[88:89], v[88:89], v[90:91]
	ds_bpermute_b32 v96, v133, v92
	ds_bpermute_b32 v91, v133, v89
	ds_bpermute_b32 v90, v133, v88
	s_waitcnt lgkmcnt(2)
	v_pk_add_f32 v[126:127], v[92:93], v[96:97]
	ds_bpermute_b32 v129, v134, v127
	s_waitcnt lgkmcnt(1)
	v_pk_add_f32 v[122:123], v[88:89], v[90:91]
	ds_bpermute_b32 v128, v134, v126
	ds_bpermute_b32 v125, v134, v123
	ds_bpermute_b32 v124, v134, v122
	s_cbranch_vccnz .LBB0_1214
	v_ashrrev_i32_e32 v16, 9, v52
	v_readlane_b32 s16, v254, 0
	v_mul_hi_i32_i24_e32 v89, 0x18000, v16
	v_mul_i32_i24_e32 v88, 0x18000, v16
	v_readlane_b32 s22, v254, 6
	v_readlane_b32 s23, v254, 7
	v_mov_b32_e32 v95, v115
	s_waitcnt lgkmcnt(2)
	v_pk_add_f32 v[114:115], v[126:127], v[128:129]
	v_lshl_add_u64 v[88:89], s[22:23], 0, v[88:89]
	v_lshl_add_u64 v[144:145], v[88:89], 0, v[0:1]
	v_lshl_add_u64 v[88:89], v[10:11], 0, v[4:5]
	v_add_co_u32_e32 v146, vcc, s11, v88
	v_mov_b64_e32 v[126:127], s[8:9]
	s_nop 0
	v_addc_co_u32_e32 v147, vcc, 0, v89, vcc
	global_load_dwordx2 v[148:149], v[146:147], off
	global_load_dwordx4 v[136:139], v[2:3], off
	global_load_dwordx2 v[150:151], v[146:147], off offset:2048
	v_add_co_u32_e32 v92, vcc, s9, v144
	v_mov_b32_e32 v99, v105
	s_nop 0
	v_addc_co_u32_e32 v93, vcc, 0, v145, vcc
	v_add_co_u32_e32 v96, vcc, s10, v88
	v_pk_fma_f32 v[114:115], v[114:115], s[6:7], v[126:127] op_sel_hi:[1,0,0]
	s_nop 0
	v_addc_co_u32_e32 v97, vcc, 0, v89, vcc
	global_load_dwordx2 v[152:153], v[96:97], off
	global_load_dwordx4 v[140:143], v[92:93], off
	global_load_dwordx2 v[88:89], v[96:97], off offset:3584
	global_load_dwordx2 v[106:107], v[96:97], off offset:3072
	global_load_dwordx2 v[116:117], v[96:97], off offset:2560
	global_load_dwordx2 v[154:155], v[96:97], off offset:2048
	global_load_dwordx2 v[90:91], v[96:97], off offset:1536
	global_load_dwordx2 v[108:109], v[96:97], off offset:1024
	global_load_dwordx2 v[118:119], v[96:97], off offset:512
	global_load_dwordx2 v[92:93], v[146:147], off offset:3584
	global_load_dwordx2 v[110:111], v[146:147], off offset:3072
	global_load_dwordx2 v[120:121], v[146:147], off offset:2560
	s_nop 0
	global_load_dwordx2 v[96:97], v[146:147], off offset:1536
	global_load_dwordx2 v[112:113], v[146:147], off offset:1024
	s_nop 0
	global_load_dwordx2 v[146:147], v[146:147], off offset:512
	v_add_co_u32_e32 v104, vcc, s7, v8
	v_mul_f32_e32 v16, 0x4b800000, v115
	s_nop 0
	v_addc_co_u32_e32 v105, vcc, 0, v9, vcc
	v_cmp_gt_f32_e32 vcc, s12, v115
	v_mul_f32_e32 v18, 0x4b800000, v114
	v_cmp_gt_f32_e64 s[0:1], s12, v114
	v_cndmask_b32_e32 v16, v115, v16, vcc
	v_rsq_f32_e32 v16, v16
	v_cndmask_b32_e64 v18, v114, v18, s[0:1]
	v_rsq_f32_e32 v18, v18
	s_waitcnt lgkmcnt(0)
; __device__ __forceinline__ float bflo(unsigned u) { return __uint_as_float(u << 16); }
; __device__ __forceinline__ float bfhi(unsigned u) { return __uint_as_float(u & 0xffff0000u); }
; __device__ __forceinline__ void phase_rowwise(const Params& p, const float* xs32, const bf16_t* xs16, float* xd32, bf16_t* xd16, const bf16_t* y, const float* gpost, int modres,
;                                               bf16_t* hout, const float* gpre, int modh) {
;     ...
;             for (int j = 0; j < 4; ++j) { const f32x4 gt = *(const f32x4*)(modb + modres + lane * 4 + 256 * j), gp = *(const f32x4*)(gpost + lane * 4 + 256 * j);
;                 const f32x4 gg = gt * gp;
; #pragma unroll
;                 for (int r = 0; r < RB; ++r) { const float rstd = rsqrtf(ss[r] * (1.f / D) + EPS);
;                     xv[r][j][0] += gg[0] * (bflo(yp[r][j].x) * rstd); xv[r][j][1] += gg[1] * (bfhi(yp[r][j].x) * rstd);
;                     xv[r][j][2] += gg[2] * (bflo(yp[r][j].y) * rstd); xv[r][j][3] += gg[3] * (bfhi(yp[r][j].y) * rstd);
;                     if (xd32) *(f32x4*)(xd32 + (row0 + r) * D + lane * 4 + 256 * j) = xv[r][j];
	v_pk_add_f32 v[122:123], v[122:123], v[124:125]
	v_mul_f32_e32 v23, 0x45800000, v16
	v_pk_fma_f32 v[122:123], v[122:123], s[6:7], v[126:127] op_sel_hi:[1,0,0]
	v_mul_f32_e32 v37, 0x45800000, v18
	v_mul_f32_e32 v21, 0x4b800000, v123
	v_cndmask_b32_e32 v42, v16, v23, vcc
	v_cmp_gt_f32_e32 vcc, s12, v123
	v_cndmask_b32_e64 v16, v18, v37, s[0:1]
	v_mov_b32_e32 v101, v79
	v_cndmask_b32_e32 v18, v123, v21, vcc
	v_rsq_f32_e32 v18, v18
	v_mov_b32_e32 v103, v77
	v_mov_b32_e32 v79, v71
	v_mov_b32_e32 v77, v69
	v_mul_f32_e32 v21, 0x45800000, v18
	v_cndmask_b32_e32 v18, v18, v21, vcc
	v_mul_f32_e32 v21, 0x4b800000, v122
	v_cmp_gt_f32_e32 vcc, s12, v122
	v_mov_b32_e32 v71, v75
	v_mov_b32_e32 v69, v73
	v_cndmask_b32_e32 v21, v122, v21, vcc
	v_rsq_f32_e32 v21, v21
	v_pk_mul_f32 v[68:69], v[42:43], v[68:69] op_sel_hi:[0,1]
	v_pk_mul_f32 v[70:71], v[42:43], v[70:71] op_sel_hi:[0,1]
	v_pk_mul_f32 v[76:77], v[16:17], v[76:77] op_sel_hi:[0,1]
	v_lshl_add_u64 v[114:115], v[144:145], 0, s[4:5]
	v_pk_mul_f32 v[78:79], v[16:17], v[78:79] op_sel_hi:[0,1]
	v_mul_f32_e32 v23, 0x45800000, v21
	v_cndmask_b32_e32 v38, v21, v23, vcc
	v_mov_b32_e32 v81, v59
	v_mov_b32_e32 v83, v57
	v_mov_b32_e32 v57, v49
	v_mov_b32_e32 v59, v45
	v_mov_b32_e32 v45, v51
	v_mov_b32_e32 v49, v47
	v_mov_b32_e32 v73, v87
	v_mov_b32_e32 v75, v85
	v_pk_mul_f32 v[48:49], v[42:43], v[48:49] op_sel_hi:[0,1]
	v_pk_mul_f32 v[44:45], v[42:43], v[44:45] op_sel_hi:[0,1]
	v_pk_mul_f32 v[84:85], v[16:17], v[58:59] op_sel_hi:[0,1]
	v_pk_mul_f32 v[86:87], v[16:17], v[56:57] op_sel_hi:[0,1]
	v_pk_mul_f32 v[82:83], v[38:39], v[82:83] op_sel_hi:[0,1]
	v_pk_mul_f32 v[122:123], v[38:39], v[80:81] op_sel_hi:[0,1]
	v_mov_b32_e32 v61, v35
	v_mov_b32_e32 v63, v33
	v_mov_b32_e32 v33, v31
	v_mov_b32_e32 v35, v27
	v_mov_b32_e32 v27, v29
	v_mov_b32_e32 v31, v25
	v_mov_b32_e32 v47, v67
	v_mov_b32_e32 v51, v65
	v_pk_mul_f32 v[30:31], v[42:43], v[30:31] op_sel_hi:[0,1]
	v_pk_mul_f32 v[26:27], v[42:43], v[26:27] op_sel_hi:[0,1]
	v_pk_mul_f32 v[34:35], v[16:17], v[34:35] op_sel_hi:[0,1]
	v_pk_mul_f32 v[50:51], v[18:19], v[50:51] op_sel_hi:[0,1]
	s_waitcnt vmcnt(17)
	v_lshlrev_b32_e32 v124, 16, v148
	v_and_b32_e32 v125, 0xffff0000, v148
	v_lshlrev_b32_e32 v126, 16, v149
	v_and_b32_e32 v127, 0xffff0000, v149
	s_waitcnt vmcnt(15)
	v_lshlrev_b32_e32 v128, 16, v150
	v_and_b32_e32 v129, 0xffff0000, v150
	s_waitcnt vmcnt(13)
	v_pk_mul_f32 v[138:139], v[142:143], v[138:139]
	v_pk_mul_f32 v[136:137], v[140:141], v[136:137]
	v_lshlrev_b32_e32 v144, 16, v151
	v_and_b32_e32 v145, 0xffff0000, v151
	v_pk_fma_f32 v[68:69], v[136:137], v[68:69], v[124:125]
	v_pk_fma_f32 v[70:71], v[138:139], v[70:71], v[126:127]
	v_pk_fma_f32 v[76:77], v[136:137], v[76:77], v[128:129]
	v_lshlrev_b32_e32 v148, 16, v152
	v_pk_fma_f32 v[78:79], v[138:139], v[78:79], v[144:145]
	global_store_dwordx4 v[8:9], v[68:71], off sc1
	global_store_dwordx4 v[104:105], v[76:79], off offset:-4096 sc1
	v_and_b32_e32 v149, 0xffff0000, v152
	v_lshlrev_b32_e32 v70, 16, v153
	v_and_b32_e32 v71, 0xffff0000, v153
	v_pk_mul_f32 v[68:69], v[18:19], v[98:99] op_sel_hi:[0,1]
	v_pk_mul_f32 v[76:77], v[18:19], v[94:95] op_sel_hi:[0,1]
	v_pk_fma_f32 v[68:69], v[136:137], v[68:69], v[148:149]
	v_pk_fma_f32 v[70:71], v[138:139], v[76:77], v[70:71]
	global_store_dwordx4 v[104:105], v[68:71], off sc1
	s_waitcnt vmcnt(3)
	v_lshlrev_b32_e32 v56, 16, v146
	v_and_b32_e32 v57, 0xffff0000, v146
	v_lshlrev_b32_e32 v68, 16, v154
	v_and_b32_e32 v69, 0xffff0000, v154
	v_pk_mul_f32 v[70:71], v[38:39], v[102:103] op_sel_hi:[0,1]
	v_pk_fma_f32 v[76:77], v[136:137], v[70:71], v[68:69]
	v_lshlrev_b32_e32 v68, 16, v155
	v_and_b32_e32 v69, 0xffff0000, v155
	v_pk_mul_f32 v[70:71], v[38:39], v[100:101] op_sel_hi:[0,1]
	v_pk_fma_f32 v[78:79], v[138:139], v[70:71], v[68:69]
	v_add_co_u32_e32 v68, vcc, s14, v8
	v_lshlrev_b32_e32 v58, 16, v147
	s_nop 0
	v_addc_co_u32_e32 v69, vcc, 0, v9, vcc
	global_store_dwordx4 v[68:69], v[76:79], off sc1
	global_load_dwordx4 v[76:79], v[114:115], off offset:1024
	s_nop 0
	global_load_dwordx4 v[98:101], v[2:3], off offset:1024
	v_and_b32_e32 v59, 0xffff0000, v147
	v_add_co_u32_e32 v70, vcc, s13, v8
	v_pk_mul_f32 v[94:95], v[18:19], v[74:75] op_sel_hi:[0,1]
	v_pk_mul_f32 v[102:103], v[18:19], v[72:73] op_sel_hi:[0,1]
	v_lshlrev_b32_e32 v72, 16, v120
	v_and_b32_e32 v73, 0xffff0000, v120
	v_lshlrev_b32_e32 v74, 16, v121
	v_and_b32_e32 v75, 0xffff0000, v121
	v_lshlrev_b32_e32 v80, 16, v118
	v_and_b32_e32 v81, 0xffff0000, v118
	v_lshlrev_b32_e32 v118, 16, v119
	v_and_b32_e32 v119, 0xffff0000, v119
	v_lshlrev_b32_e32 v120, 16, v116
	v_and_b32_e32 v121, 0xffff0000, v116
	v_lshlrev_b32_e32 v116, 16, v117
	v_and_b32_e32 v117, 0xffff0000, v117
	v_addc_co_u32_e32 v71, vcc, 0, v9, vcc
	v_pk_mul_f32 v[64:65], v[18:19], v[46:47] op_sel_hi:[0,1]
	v_pk_mul_f32 v[62:63], v[38:39], v[62:63] op_sel_hi:[0,1]
	v_pk_mul_f32 v[60:61], v[38:39], v[60:61] op_sel_hi:[0,1]
	v_lshlrev_b32_e32 v46, 16, v110
	v_and_b32_e32 v47, 0xffff0000, v110
	v_lshlrev_b32_e32 v66, 16, v111
	v_and_b32_e32 v67, 0xffff0000, v111
	v_mov_b32_e32 v21, v15
	v_mov_b32_e32 v23, v13
	v_mov_b32_e32 v13, v19
	v_mov_b32_e32 v15, v17
	v_mov_b32_e32 v37, v55
	v_mov_b32_e32 v41, v53
	v_mov_b32_e32 v25, v43
	v_mov_b32_e32 v29, v39
	v_pk_mul_f32 v[14:15], v[42:43], v[14:15] op_sel_hi:[0,1]
	v_pk_mul_f32 v[22:23], v[16:17], v[22:23] op_sel_hi:[0,1]
	v_pk_mul_f32 v[20:21], v[16:17], v[20:21] op_sel_hi:[0,1]
	v_pk_mul_f32 v[28:29], v[18:19], v[28:29] op_sel_hi:[0,1]
	v_pk_mul_f32 v[24:25], v[18:19], v[24:25] op_sel_hi:[0,1]
	v_pk_mul_f32 v[36:37], v[38:39], v[36:37] op_sel_hi:[0,1]
	v_lshlrev_b32_e32 v18, 16, v92
	v_and_b32_e32 v19, 0xffff0000, v92
	v_readlane_b32 s17, v254, 1
	v_readlane_b32 s18, v254, 2
	v_readlane_b32 s19, v254, 3
	v_readlane_b32 s20, v254, 4
	v_readlane_b32 s21, v254, 5
	s_waitcnt vmcnt(0)
; __device__ __forceinline__ float bflo(unsigned u) { return __uint_as_float(u << 16); }
; __device__ __forceinline__ float bfhi(unsigned u) { return __uint_as_float(u & 0xffff0000u); }
; __device__ __forceinline__ void phase_rowwise(const Params& p, const float* xs32, const bf16_t* xs16, float* xd32, bf16_t* xd16, const bf16_t* y, const float* gpost, int modres,
;                                               bf16_t* hout, const float* gpre, int modh) {
;     ...
;             for (int j = 0; j < 4; ++j) { const f32x4 gt = *(const f32x4*)(modb + modres + lane * 4 + 256 * j), gp = *(const f32x4*)(gpost + lane * 4 + 256 * j);
;                 const f32x4 gg = gt * gp;
; #pragma unroll
;                 for (int r = 0; r < RB; ++r) { const float rstd = rsqrtf(ss[r] * (1.f / D) + EPS);
;                     xv[r][j][0] += gg[0] * (bflo(yp[r][j].x) * rstd); xv[r][j][1] += gg[1] * (bfhi(yp[r][j].x) * rstd);
;                     xv[r][j][2] += gg[2] * (bflo(yp[r][j].y) * rstd); xv[r][j][3] += gg[3] * (bfhi(yp[r][j].y) * rstd);
;                     if (xd32) *(f32x4*)(xd32 + (row0 + r) * D + lane * 4 + 256 * j) = xv[r][j];
	v_pk_mul_f32 v[100:101], v[78:79], v[100:101]
	v_pk_mul_f32 v[98:99], v[76:77], v[98:99]
	v_pk_fma_f32 v[58:59], v[44:45], v[100:101], v[58:59]
	v_pk_fma_f32 v[56:57], v[48:49], v[98:99], v[56:57]
	v_pk_fma_f32 v[72:73], v[84:85], v[98:99], v[72:73]
	v_pk_fma_f32 v[74:75], v[86:87], v[100:101], v[74:75]
	v_pk_fma_f32 v[76:77], v[94:95], v[98:99], v[80:81]
	v_pk_fma_f32 v[78:79], v[102:103], v[100:101], v[118:119]
	v_pk_fma_f32 v[80:81], v[82:83], v[98:99], v[120:121]
	v_pk_fma_f32 v[82:83], v[122:123], v[100:101], v[116:117]
	global_store_dwordx4 v[8:9], v[56:59], off offset:1024 sc1
	global_store_dwordx4 v[70:71], v[72:75], off offset:1024 sc1
	global_store_dwordx4 v[104:105], v[76:79], off offset:1024 sc1
	global_store_dwordx4 v[68:69], v[80:83], off offset:1024 sc1
	global_load_dwordx4 v[56:59], v[114:115], off offset:2048
	s_nop 0
	global_load_dwordx4 v[72:75], v[2:3], off offset:2048
	v_pk_mul_f32 v[48:49], v[16:17], v[32:33] op_sel_hi:[0,1]
	v_lshlrev_b32_e32 v32, 16, v112
	v_and_b32_e32 v33, 0xffff0000, v112
	v_lshlrev_b32_e32 v44, 16, v113
	v_and_b32_e32 v45, 0xffff0000, v113
	v_lshlrev_b32_e32 v76, 16, v108
	v_and_b32_e32 v77, 0xffff0000, v108
	v_lshlrev_b32_e32 v78, 16, v109
	v_and_b32_e32 v79, 0xffff0000, v109
	v_lshlrev_b32_e32 v80, 16, v106
	v_and_b32_e32 v81, 0xffff0000, v106
	v_lshlrev_b32_e32 v82, 16, v107
	v_and_b32_e32 v83, 0xffff0000, v107
	v_lshlrev_b32_e32 v16, 16, v97
	v_and_b32_e32 v17, 0xffff0000, v97
	s_waitcnt vmcnt(0)
	v_pk_mul_f32 v[58:59], v[58:59], v[74:75]
	v_pk_mul_f32 v[56:57], v[56:57], v[72:73]
	s_nop 0
	v_pk_fma_f32 v[30:31], v[30:31], v[56:57], v[32:33]
	v_pk_fma_f32 v[32:33], v[26:27], v[58:59], v[44:45]
	v_pk_fma_f32 v[44:45], v[34:35], v[56:57], v[46:47]
	v_pk_fma_f32 v[46:47], v[48:49], v[58:59], v[66:67]
	v_pk_fma_f32 v[48:49], v[50:51], v[56:57], v[76:77]
	v_pk_fma_f32 v[50:51], v[64:65], v[58:59], v[78:79]
	v_pk_fma_f32 v[56:57], v[62:63], v[56:57], v[80:81]
	v_pk_fma_f32 v[58:59], v[60:61], v[58:59], v[82:83]
	global_store_dwordx4 v[8:9], v[30:33], off offset:2048 sc1
	global_store_dwordx4 v[70:71], v[44:47], off offset:2048 sc1
	global_store_dwordx4 v[104:105], v[48:51], off offset:2048 sc1
	global_store_dwordx4 v[68:69], v[56:59], off offset:2048 sc1
	global_load_dwordx4 v[30:33], v[114:115], off offset:3072
	s_nop 0
	global_load_dwordx4 v[44:47], v[2:3], off offset:3072
	v_pk_mul_f32 v[26:27], v[42:43], v[12:13] op_sel_hi:[0,1]
	v_lshlrev_b32_e32 v12, 16, v96
	v_and_b32_e32 v13, 0xffff0000, v96
	v_pk_mul_f32 v[34:35], v[38:39], v[40:41] op_sel_hi:[0,1]
	v_lshlrev_b32_e32 v38, 16, v93
	v_and_b32_e32 v39, 0xffff0000, v93
	v_lshlrev_b32_e32 v40, 16, v90
	v_and_b32_e32 v41, 0xffff0000, v90
	v_lshlrev_b32_e32 v42, 16, v91
	v_and_b32_e32 v43, 0xffff0000, v91
	v_lshlrev_b32_e32 v48, 16, v88
	v_and_b32_e32 v49, 0xffff0000, v88
	v_lshlrev_b32_e32 v50, 16, v89
	v_and_b32_e32 v51, 0xffff0000, v89
	s_waitcnt vmcnt(0)
	v_pk_mul_f32 v[32:33], v[32:33], v[46:47]
	v_pk_mul_f32 v[30:31], v[30:31], v[44:45]
	s_nop 0
	v_pk_fma_f32 v[12:13], v[14:15], v[30:31], v[12:13]
	v_pk_fma_f32 v[14:15], v[26:27], v[32:33], v[16:17]
	v_pk_fma_f32 v[16:17], v[22:23], v[30:31], v[18:19]
	v_pk_fma_f32 v[18:19], v[20:21], v[32:33], v[38:39]
	v_pk_fma_f32 v[20:21], v[28:29], v[30:31], v[40:41]
	v_pk_fma_f32 v[22:23], v[24:25], v[32:33], v[42:43]
	v_pk_fma_f32 v[24:25], v[34:35], v[30:31], v[48:49]
	v_pk_fma_f32 v[26:27], v[36:37], v[32:33], v[50:51]
	global_store_dwordx4 v[8:9], v[12:15], off offset:3072 sc1
	global_store_dwordx4 v[70:71], v[16:19], off offset:3072 sc1
	global_store_dwordx4 v[104:105], v[20:23], off offset:3072 sc1
	global_store_dwordx4 v[68:69], v[24:27], off offset:3072 sc1
	s_branch .LBB0_1214
